# prepBC: SGU epilogue batched loads, SGU layer-norm params hoisted + token prefetch, W_s/q/kv weight-fragment loads issued ahead, rope loads batched, MLA token-loop norm weights hoisted; attention epil
# speedup vs baseline: 1.0933x; 1.0463x over previous
; DEVI u16 f2bf(float f) { return (u16)(cvtpk(f, 0.f) & 0xffffu); }
; DEVI float bf2f(u16 v) { return __uint_as_float(((unsigned)v) << 16); }
; DEVI int crow(int r, int hi) { return (r & 3) + 8 * (r >> 2) + 4 * hi; }
; DEVI void attn_unit(const u16* __restrict__ Qb, const u16* __restrict__ Kh, const u16* __restrict__ Vh, u16* __restrict__ Yrow0, int seq, char* lds) {
;     ...
;   if (hi == 0) li_l[r32] = l_reg; asm volatile("s_waitcnt lgkmcnt(0)" ::: "memory");
;   float rli[16];
; #pragma unroll
;   for (int r = 0; r < 16; ++r) rli[r] = __builtin_amdgcn_rcpf(li_l[crow(r, hi)]);
;   u16* Yw = Yrow0 + (size_t)(wid * 32) * 384;
; #pragma unroll
;   for (int r = 0; r < 16; ++r) {
;     int orow = crow(r, hi);
; #pragma unroll
;     for (int d0 = 0; d0 < 2; ++d0) {
;       u16* yp = Yw + (size_t)orow * 384 + d0 * 32 + r32;
;       float gsig = bf2f(*yp);
;       *yp = f2bf(o[d0][r] * rli[r] * gsig);
;     }
;   }
.LBB0_705:
	s_or_b64 exec, exec, s[6:7]
	s_waitcnt lgkmcnt(0)
	v_add_u32_e32 v43, v160, v128
	ds_read_b128 v[32:35], v43
	ds_read_b128 v[36:39], v43 offset:32
	s_add_i32 s1, s60, s1
	s_mul_hi_i32 s6, s1, 0x300
	s_mulk_i32 s1, 0x300
	v_readlane_b32 s4, v218, 3
	s_add_u32 s7, s4, s1
	v_readlane_b32 s1, v218, 5
	s_addc_u32 s6, s1, s6
	s_lshl_b32 s0, s0, 6
	s_waitcnt lgkmcnt(1)
	v_rcp_f32_e32 v48, v32
	v_rcp_f32_e32 v49, v33
	v_rcp_f32_e32 v50, v34
	v_rcp_f32_e32 v51, v35
	ds_read_b128 v[32:35], v43 offset:64
	ds_read_b128 v[44:47], v43 offset:96
	s_ashr_i32 s1, s0, 31
	s_lshl_b64 s[0:1], s[0:1], 1
	s_add_u32 s0, s7, s0
	s_addc_u32 s1, s6, s1
	s_waitcnt lgkmcnt(1)
	v_rcp_f32_e32 v41, v32
	v_rcp_f32_e32 v40, v33
	v_mov_b64_e32 v[32:33], s[0:1]
	v_mad_i64_i32 v[32:33], s[0:1], v159, s35, v[32:33]
	v_lshlrev_b32_e32 v128, 1, v158
	v_lshl_add_u64 v[32:33], v[32:33], 0, v[128:129]
	v_mul_u32_u24_e32 v128, 0xc00, v157
	v_lshl_add_u64 v[32:33], v[32:33], 0, v[128:129]
	v_rcp_f32_e32 v52, v36
	v_rcp_f32_e32 v53, v37
	v_rcp_f32_e32 v54, v38
	v_rcp_f32_e32 v42, v39
	v_rcp_f32_e32 v39, v34
	v_rcp_f32_e32 v38, v35
	s_waitcnt lgkmcnt(0)
	v_rcp_f32_e32 v37, v44
	v_rcp_f32_e32 v36, v45
	v_rcp_f32_e32 v35, v46
	v_rcp_f32_e32 v34, v47
	s_add_i32 s84, s84, 1
	s_cmp_eq_u32 s84, s61
	s_cselect_b64 s[0:1], -1, 0
	v_add_co_u32_e32 v96, vcc, 0x1800, v32
	s_nop 1
	v_addc_co_u32_e32 v97, vcc, 0, v33, vcc
	v_add_co_u32_e32 v98, vcc, 0x3000, v32
	s_nop 1
	v_addc_co_u32_e32 v99, vcc, 0, v33, vcc
	v_add_co_u32_e32 v100, vcc, 0x4800, v32
	s_nop 1
	v_addc_co_u32_e32 v101, vcc, 0, v33, vcc
	global_load_ushort v64, v[32:33], off
	global_load_ushort v65, v[32:33], off offset:64
	global_load_ushort v66, v[32:33], off offset:768
	global_load_ushort v67, v[32:33], off offset:832
	global_load_ushort v68, v[32:33], off offset:1536
	global_load_ushort v69, v[32:33], off offset:1600
	global_load_ushort v70, v[32:33], off offset:2304
	global_load_ushort v71, v[32:33], off offset:2368
	global_load_ushort v72, v[96:97], off
	global_load_ushort v73, v[96:97], off offset:64
	global_load_ushort v74, v[96:97], off offset:768
	global_load_ushort v75, v[96:97], off offset:832
	global_load_ushort v76, v[96:97], off offset:1536
	global_load_ushort v77, v[96:97], off offset:1600
	global_load_ushort v78, v[96:97], off offset:2304
	global_load_ushort v79, v[96:97], off offset:2368
	global_load_ushort v80, v[98:99], off
	global_load_ushort v81, v[98:99], off offset:64
	global_load_ushort v82, v[98:99], off offset:768
	global_load_ushort v83, v[98:99], off offset:832
	global_load_ushort v84, v[98:99], off offset:1536
	global_load_ushort v85, v[98:99], off offset:1600
	global_load_ushort v86, v[98:99], off offset:2304
	global_load_ushort v87, v[98:99], off offset:2368
	global_load_ushort v88, v[100:101], off
	global_load_ushort v89, v[100:101], off offset:64
	global_load_ushort v90, v[100:101], off offset:768
	global_load_ushort v91, v[100:101], off offset:832
	global_load_ushort v92, v[100:101], off offset:1536
	global_load_ushort v93, v[100:101], off offset:1600
	global_load_ushort v94, v[100:101], off offset:2304
	global_load_ushort v95, v[100:101], off offset:2368
	v_mul_f32_e32 v0, v0, v48
	v_mul_f32_e32 v16, v16, v48
	v_mul_f32_e32 v1, v1, v49
	v_mul_f32_e32 v17, v17, v49
	v_mul_f32_e32 v2, v2, v50
	v_mul_f32_e32 v18, v18, v50
	v_mul_f32_e32 v3, v3, v51
	v_mul_f32_e32 v19, v19, v51
	v_mul_f32_e32 v4, v4, v52
	v_mul_f32_e32 v20, v20, v52
	v_mul_f32_e32 v5, v5, v53
	v_mul_f32_e32 v21, v21, v53
	v_mul_f32_e32 v6, v6, v54
	v_mul_f32_e32 v22, v22, v54
	v_mul_f32_e32 v7, v7, v42
	v_mul_f32_e32 v23, v23, v42
	v_mul_f32_e32 v8, v8, v41
	v_mul_f32_e32 v24, v24, v41
	v_mul_f32_e32 v9, v9, v40
	v_mul_f32_e32 v25, v25, v40
	v_mul_f32_e32 v10, v10, v39
	v_mul_f32_e32 v26, v26, v39
	v_mul_f32_e32 v11, v11, v38
	v_mul_f32_e32 v27, v27, v38
	v_mul_f32_e32 v12, v12, v37
	v_mul_f32_e32 v28, v28, v37
	v_mul_f32_e32 v13, v13, v36
	v_mul_f32_e32 v29, v29, v36
	v_mul_f32_e32 v14, v14, v35
	v_mul_f32_e32 v30, v30, v35
	v_mul_f32_e32 v15, v15, v34
	v_mul_f32_e32 v31, v31, v34
	s_waitcnt vmcnt(0)
; DEVI u16 f2bf(float f) { return (u16)(cvtpk(f, 0.f) & 0xffffu); }
; DEVI float bf2f(u16 v) { return __uint_as_float(((unsigned)v) << 16); }
; DEVI int crow(int r, int hi) { return (r & 3) + 8 * (r >> 2) + 4 * hi; }
; DEVI void attn_unit(const u16* __restrict__ Qb, const u16* __restrict__ Kh, const u16* __restrict__ Vh, u16* __restrict__ Yrow0, int seq, char* lds) {
;     ...
;   for (int r = 0; r < 16; ++r) {
;     int orow = crow(r, hi);
; #pragma unroll
;     for (int d0 = 0; d0 < 2; ++d0) {
;       u16* yp = Yw + (size_t)orow * 384 + d0 * 32 + r32;
;       float gsig = bf2f(*yp);
;       *yp = f2bf(o[d0][r] * rli[r] * gsig);
;     }
;   }
	v_lshlrev_b32_e32 v64, 16, v64
	v_lshlrev_b32_e32 v65, 16, v65
	v_lshlrev_b32_e32 v66, 16, v66
	v_lshlrev_b32_e32 v67, 16, v67
	v_lshlrev_b32_e32 v68, 16, v68
	v_lshlrev_b32_e32 v69, 16, v69
	v_lshlrev_b32_e32 v70, 16, v70
	v_lshlrev_b32_e32 v71, 16, v71
	v_lshlrev_b32_e32 v72, 16, v72
	v_lshlrev_b32_e32 v73, 16, v73
	v_lshlrev_b32_e32 v74, 16, v74
	v_lshlrev_b32_e32 v75, 16, v75
	v_lshlrev_b32_e32 v76, 16, v76
	v_lshlrev_b32_e32 v77, 16, v77
	v_lshlrev_b32_e32 v78, 16, v78
	v_lshlrev_b32_e32 v79, 16, v79
	v_lshlrev_b32_e32 v80, 16, v80
	v_lshlrev_b32_e32 v81, 16, v81
	v_lshlrev_b32_e32 v82, 16, v82
	v_lshlrev_b32_e32 v83, 16, v83
	v_lshlrev_b32_e32 v84, 16, v84
	v_lshlrev_b32_e32 v85, 16, v85
	v_lshlrev_b32_e32 v86, 16, v86
	v_lshlrev_b32_e32 v87, 16, v87
	v_lshlrev_b32_e32 v88, 16, v88
	v_lshlrev_b32_e32 v89, 16, v89
	v_lshlrev_b32_e32 v90, 16, v90
	v_lshlrev_b32_e32 v91, 16, v91
	v_lshlrev_b32_e32 v92, 16, v92
	v_lshlrev_b32_e32 v93, 16, v93
	v_lshlrev_b32_e32 v94, 16, v94
	v_lshlrev_b32_e32 v95, 16, v95
	v_mul_f32_e32 v0, v0, v64
	v_mul_f32_e32 v16, v16, v65
	v_mul_f32_e32 v1, v1, v66
	v_mul_f32_e32 v17, v17, v67
	v_mul_f32_e32 v2, v2, v68
	v_mul_f32_e32 v18, v18, v69
	v_mul_f32_e32 v3, v3, v70
	v_mul_f32_e32 v19, v19, v71
	v_mul_f32_e32 v4, v4, v72
	v_mul_f32_e32 v20, v20, v73
	v_mul_f32_e32 v5, v5, v74
	v_mul_f32_e32 v21, v21, v75
	v_mul_f32_e32 v6, v6, v76
	v_mul_f32_e32 v22, v22, v77
	v_mul_f32_e32 v7, v7, v78
	v_mul_f32_e32 v23, v23, v79
	v_mul_f32_e32 v8, v8, v80
	v_mul_f32_e32 v24, v24, v81
	v_mul_f32_e32 v9, v9, v82
	v_mul_f32_e32 v25, v25, v83
	v_mul_f32_e32 v10, v10, v84
	v_mul_f32_e32 v26, v26, v85
	v_mul_f32_e32 v11, v11, v86
	v_mul_f32_e32 v27, v27, v87
	v_mul_f32_e32 v12, v12, v88
	v_mul_f32_e32 v28, v28, v89
	v_mul_f32_e32 v13, v13, v90
	v_mul_f32_e32 v29, v29, v91
	v_mul_f32_e32 v14, v14, v92
	v_mul_f32_e32 v30, v30, v93
	v_mul_f32_e32 v15, v15, v94
	v_mul_f32_e32 v31, v31, v95
	v_cvt_pk_bf16_f32 v0, v0, v129
	v_cvt_pk_bf16_f32 v16, v16, v129
	v_cvt_pk_bf16_f32 v1, v1, v129
	v_cvt_pk_bf16_f32 v17, v17, v129
	v_cvt_pk_bf16_f32 v2, v2, v129
	v_cvt_pk_bf16_f32 v18, v18, v129
	v_cvt_pk_bf16_f32 v3, v3, v129
	v_cvt_pk_bf16_f32 v19, v19, v129
	v_cvt_pk_bf16_f32 v4, v4, v129
	v_cvt_pk_bf16_f32 v20, v20, v129
	v_cvt_pk_bf16_f32 v5, v5, v129
	v_cvt_pk_bf16_f32 v21, v21, v129
	v_cvt_pk_bf16_f32 v6, v6, v129
	v_cvt_pk_bf16_f32 v22, v22, v129
	v_cvt_pk_bf16_f32 v7, v7, v129
	v_cvt_pk_bf16_f32 v23, v23, v129
	v_cvt_pk_bf16_f32 v8, v8, v129
	v_cvt_pk_bf16_f32 v24, v24, v129
	v_cvt_pk_bf16_f32 v9, v9, v129
	v_cvt_pk_bf16_f32 v25, v25, v129
	v_cvt_pk_bf16_f32 v10, v10, v129
	v_cvt_pk_bf16_f32 v26, v26, v129
	v_cvt_pk_bf16_f32 v11, v11, v129
	v_cvt_pk_bf16_f32 v27, v27, v129
	v_cvt_pk_bf16_f32 v12, v12, v129
	v_cvt_pk_bf16_f32 v28, v28, v129
	v_cvt_pk_bf16_f32 v13, v13, v129
	v_cvt_pk_bf16_f32 v29, v29, v129
	v_cvt_pk_bf16_f32 v14, v14, v129
	v_cvt_pk_bf16_f32 v30, v30, v129
	v_cvt_pk_bf16_f32 v15, v15, v129
	v_cvt_pk_bf16_f32 v31, v31, v129
	global_store_short v[32:33], v0, off
	global_store_short v[32:33], v16, off offset:64
	global_store_short v[32:33], v1, off offset:768
	global_store_short v[32:33], v17, off offset:832
	global_store_short v[32:33], v2, off offset:1536
	global_store_short v[32:33], v18, off offset:1600
	global_store_short v[32:33], v3, off offset:2304
	global_store_short v[32:33], v19, off offset:2368
	global_store_short v[96:97], v4, off
	global_store_short v[96:97], v20, off offset:64
	global_store_short v[96:97], v5, off offset:768
	global_store_short v[96:97], v21, off offset:832
	global_store_short v[96:97], v6, off offset:1536
	global_store_short v[96:97], v22, off offset:1600
	global_store_short v[96:97], v7, off offset:2304
	global_store_short v[96:97], v23, off offset:2368
	global_store_short v[98:99], v8, off
	global_store_short v[98:99], v24, off offset:64
	global_store_short v[98:99], v9, off offset:768
	global_store_short v[98:99], v25, off offset:832
	global_store_short v[98:99], v10, off offset:1536
	global_store_short v[98:99], v26, off offset:1600
	global_store_short v[98:99], v11, off offset:2304
	global_store_short v[98:99], v27, off offset:2368
	global_store_short v[100:101], v12, off
	global_store_short v[100:101], v28, off offset:64
	global_store_short v[100:101], v13, off offset:768
	global_store_short v[100:101], v29, off offset:832
	global_store_short v[100:101], v14, off offset:1536
	global_store_short v[100:101], v30, off offset:1600
	global_store_short v[100:101], v15, off offset:2304
	global_store_short v[100:101], v31, off offset:2368
	s_barrier

; #define SWRITE(b, i) do { *(bf16x8*)(V_lds + (b) * SHM_V + vst0) = sr_[i].vs;                                  \
;     *(bf16x8*)(K_lds + (b) * SHM_K + kst0) = sr_[i].ks0;                                                      \
;     if (w1) *(bf16x8*)(K_lds + (b) * SHM_K + kst1) = sr_[i].ks1; } while (0)
; #define SWAIT() asm volatile("s_waitcnt vmcnt(3)" ::: "memory")
; DEVI void attn_unit(const u16* __restrict__ Qb, const u16* __restrict__ Kh, const u16* __restrict__ Vh, u16* __restrict__ Yrow0, int seq, char* lds) {
;     ...
;     SWAIT(); SWRITE((j + 1) & 3, SE);
.LBB0_735:
	s_or_b64 exec, exec, s[6:7]
	s_and_b32 s6, s9, 3
	s_waitcnt vmcnt(3)
	v_lshl_add_u32 v112, s6, 13, v165
	s_mulk_i32 s6, 0x3400
	s_add_i32 s30, s6, 16
	ds_write_b128 v112, v[64:67]
	v_add_u32_e32 v112, s30, v163
	ds_write_b128 v112, v[68:71] offset:32768
	s_and_saveexec_b64 s[6:7], s[40:41]
	s_cbranch_execz .LBB0_737
	v_add_u32_e32 v112, s30, v164
	ds_write_b128 v112, v[72:75] offset:32768

; #define SBAR() __builtin_amdgcn_sched_barrier(0)
; #define SLOAD(i, k0) do { sr_[i].vs = *reinterpret_cast<const bf16x8*>(Vh + (size_t)(k0) * 64 + tid * 8);      \
;     sr_[i].ks0 = *reinterpret_cast<const bf16x8*>(Kh + (size_t)(k0) * 96 + tid * 8);                          \
;     sr_[i].ks1 = *reinterpret_cast<const bf16x8*>(Kh + (size_t)(k0) * 96 + idx1 * 8); } while (0)
; DEVI void finishSM(f32x16& p0, f32x16& p1, float alpha, float& l_reg, bf16x8& pa0, bf16x8& pa1, bf16x8& pa2, bf16x8& pa3) {
; #pragma unroll
;   for (int r = 0; r < 16; ++r) p1[r] = __builtin_amdgcn_exp2f(p1[r]);
;   float ps = 0;
; #pragma unroll
;   for (int r = 0; r < 16; ++r) ps += p0[r];
; #pragma unroll
;   for (int r = 0; r < 16; ++r) ps += p1[r];
;   { auto rr = __builtin_amdgcn_permlane32_swap(__float_as_uint(ps), __float_as_uint(ps), false, false);
;     ps = __uint_as_float(rr[0]) + __uint_as_float(rr[1]); }
;   l_reg = l_reg * alpha + ps;
;     ...
;   PK4(p0, 0, pa0); PK4(p0, 8, pa1); PK4(p1, 0, pa2); PK4(p1, 8, pa3);
;     ...
; }
; DEVI void qkt(f32x16& p0, f32x16& p1, const char* Ks, const bf16x8* qr, int r32, int hi, float minit) {
; #pragma unroll
;   for (int r = 0; r < 16; ++r) { p0[r] = minit; p1[r] = minit; }
; #pragma unroll
;   for (int d0 = 0; d0 < 6; ++d0) {
;     int cb = d0 * 32 + hi * 16;
;     bf16x8 b0 = *reinterpret_cast<const bf16x8*>(Ks + r32 * KROW + cb);
;     bf16x8 b1 = *reinterpret_cast<const bf16x8*>(Ks + (32 + r32) * KROW + cb);
;     p0 = __builtin_amdgcn_mfma_f32_32x32x16_bf16(b0, qr[d0], p0, 0, 0, 0);
;     p1 = __builtin_amdgcn_mfma_f32_32x32x16_bf16(b1, qr[d0], p1, 0, 0, 0);
;   }
; DEVI void attn_unit(const u16* __restrict__ Qb, const u16* __restrict__ Kh, const u16* __restrict__ Vh, u16* __restrict__ Yrow0, int seq, char* lds) {
;     ...
;       SBAR(); qkt(pA0, pA1, Kj1, qr, r32, hi, -m_reg);
;       finishSM(pB0, pB1, alB, l_reg, pa0, pa1, pa2, pa3); SBAR();
;       if (j + 3 < NT) SLOAD(SE, (j + 3) * 64); SBAR();
.LBB0_746:
	s_andn2_saveexec_b64 s[6:7], s[6:7]
	s_cbranch_execz .LBB0_751
	v_add3_u32 v112, s30, v166, v128
	ds_read_b128 v[222:225], v112 offset:32768
	ds_read_b128 v[226:229], v112 offset:39424
	ds_read_b128 v[230:233], v112 offset:32800
	ds_read_b128 v[234:237], v112 offset:39456
	ds_read_b128 v[238:241], v112 offset:32832
	ds_read_b128 v[242:245], v112 offset:39488
	ds_read_b128 v[246:249], v112 offset:32864
	ds_read_b128 v[250:253], v112 offset:39520
	v_xor_b32_e32 v32, 0x80000000, v167
	v_mov_b32_e32 v33, v32
	v_mov_b32_e32 v34, v32
	v_mov_b32_e32 v35, v32
	v_mov_b32_e32 v36, v32
	v_mov_b32_e32 v37, v32
	v_mov_b32_e32 v38, v32
	v_mov_b32_e32 v39, v32
	v_mov_b32_e32 v40, v32
	v_mov_b32_e32 v41, v32
	v_mov_b32_e32 v42, v32
	v_mov_b32_e32 v43, v32
	v_mov_b32_e32 v44, v32
	v_mov_b32_e32 v45, v32
	v_mov_b32_e32 v46, v32
	v_mov_b32_e32 v47, v32
	s_waitcnt lgkmcnt(7)
	s_nop 0
	v_mfma_f32_32x32x16_bf16 v[48:63], v[222:225], v[100:103], v[32:47]
	s_waitcnt lgkmcnt(6)
	v_mfma_f32_32x32x16_bf16 v[32:47], v[226:229], v[100:103], v[32:47]
	ds_read_b128 v[222:225], v112 offset:32896
	ds_read_b128 v[226:229], v112 offset:39552
	s_waitcnt lgkmcnt(7)
	v_mfma_f32_32x32x16_bf16 v[48:63], v[230:233], v[96:99], v[48:63]
	s_waitcnt lgkmcnt(6)
	v_mfma_f32_32x32x16_bf16 v[32:47], v[234:237], v[96:99], v[32:47]
	ds_read_b128 v[230:233], v112 offset:32928
	ds_read_b128 v[234:237], v112 offset:39584
	s_waitcnt lgkmcnt(7)
	v_mfma_f32_32x32x16_bf16 v[48:63], v[238:241], v[92:95], v[48:63]
	s_waitcnt lgkmcnt(6)
	v_mfma_f32_32x32x16_bf16 v[32:47], v[242:245], v[92:95], v[32:47]
	s_waitcnt lgkmcnt(5)
	v_mfma_f32_32x32x16_bf16 v[48:63], v[246:249], v[88:91], v[48:63]
	s_waitcnt lgkmcnt(4)
	v_mfma_f32_32x32x16_bf16 v[32:47], v[250:253], v[88:91], v[32:47]
	s_waitcnt lgkmcnt(3)
	v_mfma_f32_32x32x16_bf16 v[48:63], v[222:225], v[84:87], v[48:63]
	s_waitcnt lgkmcnt(2)
	v_mfma_f32_32x32x16_bf16 v[32:47], v[226:229], v[84:87], v[32:47]
	v_add_f32_e32 v112, v185, v190
	v_add_f32_e32 v112, v188, v112
	v_add_f32_e32 v112, v114, v112
	v_add_f32_e32 v112, v186, v112
	v_add_f32_e32 v112, v115, v112
	v_add_f32_e32 v112, v184, v112
	v_add_f32_e32 v112, v116, v112
	v_add_f32_e32 v112, v183, v112
	v_add_f32_e32 v112, v117, v112
	v_add_f32_e32 v112, v182, v112
	v_add_f32_e32 v112, v118, v112
	v_add_f32_e32 v112, v181, v112
	v_add_f32_e32 v112, v119, v112
	v_add_f32_e32 v112, v180, v112
	v_add_f32_e32 v112, v112, v120
	v_add_f32_e32 v112, v121, v112
	v_add_f32_e32 v112, v122, v112
	v_add_f32_e32 v112, v123, v112
	v_add_f32_e32 v112, v176, v112
	v_add_f32_e32 v112, v177, v112
	v_add_f32_e32 v112, v178, v112
	v_add_f32_e32 v112, v179, v112
	v_add_f32_e32 v112, v124, v112
	v_add_f32_e32 v112, v125, v112
	s_waitcnt lgkmcnt(1)
	v_mfma_f32_32x32x16_bf16 v[48:63], v[230:233], v[80:83], v[48:63]
	v_add_f32_e32 v112, v126, v112
	v_add_f32_e32 v112, v127, v112
	v_add_f32_e32 v112, v172, v112
	v_add_f32_e32 v112, v173, v112
	v_add_f32_e32 v112, v174, v112
	v_add_f32_e32 v190, v175, v112
	v_mov_b32_e32 v191, v190
	s_waitcnt lgkmcnt(0)
	v_mfma_f32_32x32x16_bf16 v[32:47], v[234:237], v[80:83], v[32:47]
	v_cvt_pk_bf16_f32 v112, v187, v189
	v_cvt_pk_bf16_f32 v113, v185, v188
	v_cvt_pk_bf16_f32 v114, v114, v186
	v_cvt_pk_bf16_f32 v115, v115, v184
	v_cvt_pk_bf16_f32 v116, v116, v183
	v_cvt_pk_bf16_f32 v117, v117, v182
	v_cvt_pk_bf16_f32 v118, v118, v181
	v_cvt_pk_bf16_f32 v119, v119, v180
	v_cvt_pk_bf16_f32 v120, v120, v121
	v_cvt_pk_bf16_f32 v121, v122, v123
	v_cvt_pk_bf16_f32 v122, v176, v177
	v_cvt_pk_bf16_f32 v123, v178, v179
	v_cvt_pk_bf16_f32 v124, v124, v125
	v_cvt_pk_bf16_f32 v125, v126, v127
	v_cvt_pk_bf16_f32 v126, v172, v173
	v_cvt_pk_bf16_f32 v127, v174, v175
	v_permlane32_swap_b32_e32 v190, v191
	v_permlane32_swap_b32_e32 v112, v114
	v_permlane32_swap_b32_e32 v113, v115
	v_permlane32_swap_b32_e32 v116, v118
	v_permlane32_swap_b32_e32 v117, v119
	v_permlane32_swap_b32_e32 v120, v122
	v_permlane32_swap_b32_e32 v121, v123
	v_permlane32_swap_b32_e32 v124, v126
	v_permlane32_swap_b32_e32 v125, v127
	s_add_i32 s29, s9, 2
	s_cmp_ge_u32 s29, s8
	s_cbranch_scc1 .LBB0_749
	v_lshl_add_u64 v[64:65], v[136:137], 0, s[80:81]
	v_add_co_u32_e32 v64, vcc, 0x1c2b8000, v64
	v_lshl_add_u64 v[68:69], v[132:133], 0, s[80:81]
	v_addc_co_u32_e32 v65, vcc, 0, v65, vcc
	v_add_co_u32_e32 v68, vcc, 0x156bc000, v68
	v_lshl_add_u64 v[72:73], v[134:135], 0, s[80:81]
	v_addc_co_u32_e32 v69, vcc, 0, v69, vcc
	v_add_co_u32_e32 v72, vcc, 0x156be000, v72
	global_load_dwordx4 v[64:67], v[64:65], off
	s_nop 0
	v_addc_co_u32_e32 v73, vcc, 0, v73, vcc
	global_load_dwordx4 v[68:71], v[68:69], off
	s_nop 0
	global_load_dwordx4 v[72:75], v[72:73], off

; #define SBAR() __builtin_amdgcn_sched_barrier(0)
; #define SLOAD(i, k0) do { sr_[i].vs = *reinterpret_cast<const bf16x8*>(Vh + (size_t)(k0) * 64 + tid * 8);      \
;     sr_[i].ks0 = *reinterpret_cast<const bf16x8*>(Kh + (size_t)(k0) * 96 + tid * 8);                          \
;     sr_[i].ks1 = *reinterpret_cast<const bf16x8*>(Kh + (size_t)(k0) * 96 + idx1 * 8); } while (0)
; #define SWRITE(b, i) do { *(bf16x8*)(V_lds + (b) * SHM_V + vst0) = sr_[i].vs;                                  \
;     *(bf16x8*)(K_lds + (b) * SHM_K + kst0) = sr_[i].ks0;                                                      \
;     if (w1) *(bf16x8*)(K_lds + (b) * SHM_K + kst1) = sr_[i].ks1; } while (0)
; #define SWAIT() asm volatile("s_waitcnt vmcnt(3)" ::: "memory")
; DEVI void attn_unit(const u16* __restrict__ Qb, const u16* __restrict__ Kh, const u16* __restrict__ Vh, u16* __restrict__ Yrow0, int seq, char* lds) {
;     ...
;       if (j + 3 < NT) SLOAD(SE, (j + 3) * 64); SBAR();
;     ...
;     SWAIT(); SWRITE((j + 2) & 3, SO);
.LBB0_751:
	s_or_b64 exec, exec, s[6:7]
	s_add_i32 s6, s9, 2
	s_cmp_ge_u32 s6, s8
	s_cbranch_scc0 .Lattn_sw2_ok
	s_waitcnt vmcnt(0)
.Lattn_sw2_ok:
	s_add_i32 s6, s9, 1
	s_and_b32 s6, s6, 3
	s_waitcnt vmcnt(3)
	v_lshl_add_u32 v114, s6, 13, v165
	s_mulk_i32 s6, 0x3400
	s_add_i32 s29, s6, 16
	ds_write_b128 v114, v[76:79]
	v_add_u32_e32 v76, s29, v163
	ds_write_b128 v76, v[104:107] offset:32768
	s_and_saveexec_b64 s[6:7], s[40:41]
	s_cbranch_execz .LBB0_753
	v_add_u32_e32 v76, s29, v164
	ds_write_b128 v76, v[108:111] offset:32768

; DEVI unsigned cvtpk(float lo, float hi) { unsigned r; asm volatile("v_cvt_pk_bf16_f32 %0, %1, %2" : "=v"(r) : "v"(lo), "v"(hi)); return r; }
; DEVI float siluf_(float x) { return x / (1.f + __expf(-x)); }
; DEVI void prepMLA_tile(const Params& p, int l, int g, int tile, char* lds) {
;     ...
; #pragma unroll
;   for (int i = 0; i < 6; ++i) {
;     int it = tid + i * 512; int tok = it / 48, ch = it % 48;
;     h16x8 z = *(const h16x8*)(Z + (size_t)tok * NBC + 352 + ch * 8);
;     u32x4 w; w.x = cvtpk(siluf_((float)z[0]), siluf_((float)z[1])); w.y = cvtpk(siluf_((float)z[2]), siluf_((float)z[3]));
;     w.z = cvtpk(siluf_((float)z[4]), siluf_((float)z[5])); w.w = cvtpk(siluf_((float)z[6]), siluf_((float)z[7]));
;     *(u32x4*)(Yb + (size_t)(t0 + tok) * 384 + ch * 8) = w;
;   }
.LBB0_779:
	s_cmpk_gt_i32 s12, 0x2ff
	s_cbranch_scc1 .LBB0_798
	s_lshl_b32 s0, s12, 6
	s_add_i32 s17, s0, s13
	s_mul_i32 s1, s12, 0x2f000
	s_mul_hi_i32 s38, s0, 0xbc0
	s_add_u32 s0, s14, s1
	s_waitcnt vmcnt(19)
	v_mov_b32_e32 v55, v131
	s_addc_u32 s1, s15, s38
	s_mov_b32 s38, 0x2aaaaaab
	v_mov_b64_e32 v[4:5], s[0:1]
	v_mul_hi_i32 v0, v55, s38
	v_lshrrev_b32_e32 v1, 31, v0
	v_ashrrev_i32_e32 v0, 3, v0
	v_add_u32_e32 v6, v0, v1
	v_mul_lo_u32 v0, v6, 48
	v_sub_u32_e32 v2, v55, v0
	v_lshlrev_b32_e32 v2, 3, v2
	v_ashrrev_i32_e32 v3, 31, v2
	v_mad_i64_i32 v[0:1], s[0:1], v6, s23, v[4:5]
	v_lshlrev_b64 v[8:9], 1, v[2:3]
	v_lshl_add_u64 v[0:1], v[0:1], 0, v[8:9]
	global_load_dwordx4 v[0:3], v[0:1], off offset:704
	v_and_b32_e32 v54, 63, v55
	v_ashrrev_i32_e32 v52, 6, v55
	v_lshlrev_b32_e32 v128, 2, v54
	s_waitcnt vmcnt(0)
	v_cvt_f32_f16_e32 v7, v0
	v_cvt_f32_f16_sdwa v0, v0 dst_sel:DWORD dst_unused:UNUSED_PAD src0_sel:WORD_1
	v_mul_f32_e32 v10, 0xbfb8aa3b, v7
	v_exp_f32_e32 v10, v10
	s_nop 0
	v_add_f32_e32 v10, 1.0, v10
	v_div_scale_f32 v11, s[0:1], v10, v10, v7
	v_rcp_f32_e32 v12, v11
	s_nop 0
	v_fma_f32 v13, -v11, v12, 1.0
	v_fmac_f32_e32 v12, v13, v12
	v_div_scale_f32 v13, vcc, v7, v10, v7
	v_mul_f32_e32 v14, v13, v12
	v_fma_f32 v15, -v11, v14, v13
	v_fmac_f32_e32 v14, v15, v12
	v_fma_f32 v11, -v11, v14, v13
	v_div_fmas_f32 v11, v11, v12, v14
	v_div_fixup_f32 v7, v11, v10, v7
	v_mul_f32_e32 v10, 0xbfb8aa3b, v0
	v_exp_f32_e32 v10, v10
	s_nop 0
	v_add_f32_e32 v10, 1.0, v10
	v_div_scale_f32 v11, s[0:1], v10, v10, v0
	v_rcp_f32_e32 v12, v11
	s_nop 0
	v_fma_f32 v13, -v11, v12, 1.0
	v_fmac_f32_e32 v12, v13, v12
	v_div_scale_f32 v13, vcc, v0, v10, v0
	v_mul_f32_e32 v14, v13, v12
	v_fma_f32 v15, -v11, v14, v13
	v_fmac_f32_e32 v14, v15, v12
	v_fma_f32 v11, -v11, v14, v13
	v_div_fmas_f32 v11, v11, v12, v14
	v_div_fixup_f32 v0, v11, v10, v0
	v_cvt_pk_bf16_f32 v0, v7, v0
	v_cvt_f32_f16_e32 v7, v1
	v_cvt_f32_f16_sdwa v1, v1 dst_sel:DWORD dst_unused:UNUSED_PAD src0_sel:WORD_1
	v_mul_f32_e32 v10, 0xbfb8aa3b, v7
	v_exp_f32_e32 v10, v10
	s_nop 0
	v_add_f32_e32 v10, 1.0, v10
	v_div_scale_f32 v11, s[0:1], v10, v10, v7
	v_rcp_f32_e32 v12, v11
	s_nop 0
	v_fma_f32 v13, -v11, v12, 1.0
	v_fmac_f32_e32 v12, v13, v12
	v_div_scale_f32 v13, vcc, v7, v10, v7
	v_mul_f32_e32 v14, v13, v12
	v_fma_f32 v15, -v11, v14, v13
	v_fmac_f32_e32 v14, v15, v12
	v_fma_f32 v11, -v11, v14, v13
	v_div_fmas_f32 v11, v11, v12, v14
	v_div_fixup_f32 v7, v11, v10, v7
	v_mul_f32_e32 v10, 0xbfb8aa3b, v1
	v_exp_f32_e32 v10, v10
	s_nop 0
	v_add_f32_e32 v10, 1.0, v10
	v_div_scale_f32 v11, s[0:1], v10, v10, v1
	v_rcp_f32_e32 v12, v11
	s_nop 0
	v_fma_f32 v13, -v11, v12, 1.0
	v_fmac_f32_e32 v12, v13, v12
	v_div_scale_f32 v13, vcc, v1, v10, v1
	v_mul_f32_e32 v14, v13, v12
	v_fma_f32 v15, -v11, v14, v13
	v_fmac_f32_e32 v14, v15, v12
	v_fma_f32 v11, -v11, v14, v13
	v_div_fmas_f32 v11, v11, v12, v14
	v_div_fixup_f32 v1, v11, v10, v1
	v_cvt_pk_bf16_f32 v1, v7, v1
	v_cvt_f32_f16_e32 v7, v2
	v_cvt_f32_f16_sdwa v2, v2 dst_sel:DWORD dst_unused:UNUSED_PAD src0_sel:WORD_1
	v_mul_f32_e32 v10, 0xbfb8aa3b, v7
	v_exp_f32_e32 v10, v10
	s_nop 0
	v_add_f32_e32 v10, 1.0, v10
	v_div_scale_f32 v11, s[0:1], v10, v10, v7
	v_rcp_f32_e32 v12, v11
	s_nop 0
	v_fma_f32 v13, -v11, v12, 1.0
	v_fmac_f32_e32 v12, v13, v12
	v_div_scale_f32 v13, vcc, v7, v10, v7
	v_mul_f32_e32 v14, v13, v12
	v_fma_f32 v15, -v11, v14, v13
	v_fmac_f32_e32 v14, v15, v12
	v_fma_f32 v11, -v11, v14, v13
	v_div_fmas_f32 v11, v11, v12, v14
	v_div_fixup_f32 v7, v11, v10, v7
	v_mul_f32_e32 v10, 0xbfb8aa3b, v2
	v_exp_f32_e32 v10, v10
	s_nop 0
	v_add_f32_e32 v10, 1.0, v10
	v_div_scale_f32 v11, s[0:1], v10, v10, v2
	v_rcp_f32_e32 v12, v11
	s_nop 0
	v_fma_f32 v13, -v11, v12, 1.0
	v_fmac_f32_e32 v12, v13, v12
	v_div_scale_f32 v13, vcc, v2, v10, v2
	v_mul_f32_e32 v14, v13, v12
	v_fma_f32 v15, -v11, v14, v13
	v_fmac_f32_e32 v14, v15, v12
	v_fma_f32 v11, -v11, v14, v13
	v_div_fmas_f32 v11, v11, v12, v14
	v_div_fixup_f32 v2, v11, v10, v2
	v_cvt_pk_bf16_f32 v2, v7, v2
	v_cvt_f32_f16_e32 v7, v3
	v_cvt_f32_f16_sdwa v3, v3 dst_sel:DWORD dst_unused:UNUSED_PAD src0_sel:WORD_1
	v_mul_f32_e32 v10, 0xbfb8aa3b, v7
	v_exp_f32_e32 v10, v10
	s_nop 0
	v_add_f32_e32 v10, 1.0, v10
	v_div_scale_f32 v11, s[0:1], v10, v10, v7
	v_rcp_f32_e32 v12, v11
	s_nop 0
	v_fma_f32 v13, -v11, v12, 1.0
	v_fmac_f32_e32 v12, v13, v12
	v_div_scale_f32 v13, vcc, v7, v10, v7
	v_mul_f32_e32 v14, v13, v12
	v_fma_f32 v15, -v11, v14, v13
	v_fmac_f32_e32 v14, v15, v12
	v_fma_f32 v11, -v11, v14, v13
	v_div_fmas_f32 v11, v11, v12, v14
	v_div_fixup_f32 v7, v11, v10, v7
	v_mul_f32_e32 v10, 0xbfb8aa3b, v3
	v_exp_f32_e32 v10, v10
	s_nop 0
	v_add_f32_e32 v10, 1.0, v10
	v_div_scale_f32 v11, s[0:1], v10, v10, v3
	v_rcp_f32_e32 v12, v11
	s_nop 0
	v_fma_f32 v13, -v11, v12, 1.0
	v_fmac_f32_e32 v12, v13, v12
	v_div_scale_f32 v13, vcc, v3, v10, v3
	v_mul_f32_e32 v14, v13, v12
	v_fma_f32 v15, -v11, v14, v13
	v_fmac_f32_e32 v14, v15, v12
	v_fma_f32 v11, -v11, v14, v13
	v_div_fmas_f32 v11, v11, v12, v14
	v_div_fixup_f32 v3, v11, v10, v3
	v_cvt_pk_bf16_f32 v3, v7, v3
	v_add_u32_e32 v10, s17, v6
	v_mov_b64_e32 v[6:7], s[6:7]
	v_mad_i64_i32 v[10:11], s[0:1], v10, s35, v[6:7]
	v_lshl_add_u64 v[8:9], v[10:11], 0, v[8:9]
	global_store_dwordx4 v[8:9], v[0:3], off
	s_nop 1
	v_add_u32_e32 v0, 0x200, v55
	v_mul_hi_i32 v1, v0, s38
	v_lshrrev_b32_e32 v2, 31, v1
	v_ashrrev_i32_e32 v1, 3, v1
	v_add_u32_e32 v10, v1, v2
	v_mul_lo_u32 v1, v10, 48
	v_sub_u32_e32 v2, v0, v1
	v_lshlrev_b32_e32 v2, 3, v2
	v_ashrrev_i32_e32 v3, 31, v2
	v_mad_i64_i32 v[0:1], s[0:1], v10, s23, v[4:5]
	v_lshlrev_b64 v[8:9], 1, v[2:3]
	v_lshl_add_u64 v[0:1], v[0:1], 0, v[8:9]
	global_load_dwordx4 v[0:3], v[0:1], off offset:704
	v_add_u32_e32 v10, s17, v10
	s_waitcnt vmcnt(0)
; DEVI unsigned cvtpk(float lo, float hi) { unsigned r; asm volatile("v_cvt_pk_bf16_f32 %0, %1, %2" : "=v"(r) : "v"(lo), "v"(hi)); return r; }
; DEVI float siluf_(float x) { return x / (1.f + __expf(-x)); }
; DEVI void prepMLA_tile(const Params& p, int l, int g, int tile, char* lds) {
;     ...
; #pragma unroll
;   for (int i = 0; i < 6; ++i) {
;     int it = tid + i * 512; int tok = it / 48, ch = it % 48;
;     h16x8 z = *(const h16x8*)(Z + (size_t)tok * NBC + 352 + ch * 8);
;     u32x4 w; w.x = cvtpk(siluf_((float)z[0]), siluf_((float)z[1])); w.y = cvtpk(siluf_((float)z[2]), siluf_((float)z[3]));
;     w.z = cvtpk(siluf_((float)z[4]), siluf_((float)z[5])); w.w = cvtpk(siluf_((float)z[6]), siluf_((float)z[7]));
;     *(u32x4*)(Yb + (size_t)(t0 + tok) * 384 + ch * 8) = w;
;   }
	v_cvt_f32_f16_e32 v11, v0
	v_cvt_f32_f16_sdwa v0, v0 dst_sel:DWORD dst_unused:UNUSED_PAD src0_sel:WORD_1
	v_mul_f32_e32 v12, 0xbfb8aa3b, v11
	v_exp_f32_e32 v12, v12
	s_nop 0
	v_add_f32_e32 v12, 1.0, v12
	v_div_scale_f32 v13, s[0:1], v12, v12, v11
	v_rcp_f32_e32 v14, v13
	s_nop 0
	v_fma_f32 v15, -v13, v14, 1.0
	v_fmac_f32_e32 v14, v15, v14
	v_div_scale_f32 v15, vcc, v11, v12, v11
	v_mul_f32_e32 v16, v15, v14
	v_fma_f32 v17, -v13, v16, v15
	v_fmac_f32_e32 v16, v17, v14
	v_fma_f32 v13, -v13, v16, v15
	v_div_fmas_f32 v13, v13, v14, v16
	v_div_fixup_f32 v11, v13, v12, v11
	v_mul_f32_e32 v12, 0xbfb8aa3b, v0
	v_exp_f32_e32 v12, v12
	s_nop 0
	v_add_f32_e32 v12, 1.0, v12
	v_div_scale_f32 v13, s[0:1], v12, v12, v0
	v_rcp_f32_e32 v14, v13
	s_nop 0
	v_fma_f32 v15, -v13, v14, 1.0
	v_fmac_f32_e32 v14, v15, v14
	v_div_scale_f32 v15, vcc, v0, v12, v0
	v_mul_f32_e32 v16, v15, v14
	v_fma_f32 v17, -v13, v16, v15
	v_fmac_f32_e32 v16, v17, v14
	v_fma_f32 v13, -v13, v16, v15
	v_div_fmas_f32 v13, v13, v14, v16
	v_div_fixup_f32 v0, v13, v12, v0
	v_cvt_pk_bf16_f32 v0, v11, v0
	v_cvt_f32_f16_e32 v11, v1
	v_cvt_f32_f16_sdwa v1, v1 dst_sel:DWORD dst_unused:UNUSED_PAD src0_sel:WORD_1
	v_mul_f32_e32 v12, 0xbfb8aa3b, v11
	v_exp_f32_e32 v12, v12
	s_nop 0
	v_add_f32_e32 v12, 1.0, v12
	v_div_scale_f32 v13, s[0:1], v12, v12, v11
	v_rcp_f32_e32 v14, v13
	s_nop 0
	v_fma_f32 v15, -v13, v14, 1.0
	v_fmac_f32_e32 v14, v15, v14
	v_div_scale_f32 v15, vcc, v11, v12, v11
	v_mul_f32_e32 v16, v15, v14
	v_fma_f32 v17, -v13, v16, v15
	v_fmac_f32_e32 v16, v17, v14
	v_fma_f32 v13, -v13, v16, v15
	v_div_fmas_f32 v13, v13, v14, v16
	v_div_fixup_f32 v11, v13, v12, v11
	v_mul_f32_e32 v12, 0xbfb8aa3b, v1
	v_exp_f32_e32 v12, v12
	s_nop 0
	v_add_f32_e32 v12, 1.0, v12
	v_div_scale_f32 v13, s[0:1], v12, v12, v1
	v_rcp_f32_e32 v14, v13
	s_nop 0
	v_fma_f32 v15, -v13, v14, 1.0
	v_fmac_f32_e32 v14, v15, v14
	v_div_scale_f32 v15, vcc, v1, v12, v1
	v_mul_f32_e32 v16, v15, v14
	v_fma_f32 v17, -v13, v16, v15
	v_fmac_f32_e32 v16, v17, v14
	v_fma_f32 v13, -v13, v16, v15
	v_div_fmas_f32 v13, v13, v14, v16
	v_div_fixup_f32 v1, v13, v12, v1
	v_cvt_pk_bf16_f32 v1, v11, v1
	v_cvt_f32_f16_e32 v11, v2
	v_cvt_f32_f16_sdwa v2, v2 dst_sel:DWORD dst_unused:UNUSED_PAD src0_sel:WORD_1
	v_mul_f32_e32 v12, 0xbfb8aa3b, v11
	v_exp_f32_e32 v12, v12
	s_nop 0
	v_add_f32_e32 v12, 1.0, v12
	v_div_scale_f32 v13, s[0:1], v12, v12, v11
	v_rcp_f32_e32 v14, v13
	s_nop 0
	v_fma_f32 v15, -v13, v14, 1.0
	v_fmac_f32_e32 v14, v15, v14
	v_div_scale_f32 v15, vcc, v11, v12, v11
	v_mul_f32_e32 v16, v15, v14
	v_fma_f32 v17, -v13, v16, v15
	v_fmac_f32_e32 v16, v17, v14
	v_fma_f32 v13, -v13, v16, v15
	v_div_fmas_f32 v13, v13, v14, v16
	v_div_fixup_f32 v11, v13, v12, v11
	v_mul_f32_e32 v12, 0xbfb8aa3b, v2
	v_exp_f32_e32 v12, v12
	s_nop 0
	v_add_f32_e32 v12, 1.0, v12
	v_div_scale_f32 v13, s[0:1], v12, v12, v2
	v_rcp_f32_e32 v14, v13
	s_nop 0
	v_fma_f32 v15, -v13, v14, 1.0
	v_fmac_f32_e32 v14, v15, v14
	v_div_scale_f32 v15, vcc, v2, v12, v2
	v_mul_f32_e32 v16, v15, v14
	v_fma_f32 v17, -v13, v16, v15
	v_fmac_f32_e32 v16, v17, v14
	v_fma_f32 v13, -v13, v16, v15
	v_div_fmas_f32 v13, v13, v14, v16
	v_div_fixup_f32 v2, v13, v12, v2
	v_cvt_pk_bf16_f32 v2, v11, v2
	v_cvt_f32_f16_e32 v11, v3
	v_cvt_f32_f16_sdwa v3, v3 dst_sel:DWORD dst_unused:UNUSED_PAD src0_sel:WORD_1
	v_mul_f32_e32 v12, 0xbfb8aa3b, v11
	v_exp_f32_e32 v12, v12
	s_nop 0
	v_add_f32_e32 v12, 1.0, v12
	v_div_scale_f32 v13, s[0:1], v12, v12, v11
	v_rcp_f32_e32 v14, v13
	s_nop 0
	v_fma_f32 v15, -v13, v14, 1.0
	v_fmac_f32_e32 v14, v15, v14
	v_div_scale_f32 v15, vcc, v11, v12, v11
	v_mul_f32_e32 v16, v15, v14
	v_fma_f32 v17, -v13, v16, v15
	v_fmac_f32_e32 v16, v17, v14
	v_fma_f32 v13, -v13, v16, v15
	v_div_fmas_f32 v13, v13, v14, v16
	v_div_fixup_f32 v11, v13, v12, v11
	v_mul_f32_e32 v12, 0xbfb8aa3b, v3
	v_exp_f32_e32 v12, v12
	s_nop 0
	v_add_f32_e32 v12, 1.0, v12
	v_div_scale_f32 v13, s[0:1], v12, v12, v3
	v_rcp_f32_e32 v14, v13
	s_nop 0
	v_fma_f32 v15, -v13, v14, 1.0
	v_fmac_f32_e32 v14, v15, v14
	v_div_scale_f32 v15, vcc, v3, v12, v3
	v_mul_f32_e32 v16, v15, v14
	v_fma_f32 v17, -v13, v16, v15
	v_fmac_f32_e32 v16, v17, v14
	v_fma_f32 v13, -v13, v16, v15
	v_div_fmas_f32 v13, v13, v14, v16
	v_div_fixup_f32 v3, v13, v12, v3
	v_cvt_pk_bf16_f32 v3, v11, v3
	v_mad_i64_i32 v[10:11], s[0:1], v10, s35, v[6:7]
	v_lshl_add_u64 v[8:9], v[10:11], 0, v[8:9]
	global_store_dwordx4 v[8:9], v[0:3], off
	s_nop 1
	v_add_u32_e32 v0, 0x400, v55
	v_mul_hi_i32 v1, v0, s38
	v_lshrrev_b32_e32 v2, 31, v1
	v_ashrrev_i32_e32 v1, 3, v1
	v_add_u32_e32 v10, v1, v2
	v_mul_lo_u32 v1, v10, 48
	v_sub_u32_e32 v2, v0, v1
	v_lshlrev_b32_e32 v2, 3, v2
	v_ashrrev_i32_e32 v3, 31, v2
	v_mad_i64_i32 v[0:1], s[0:1], v10, s23, v[4:5]
	v_lshlrev_b64 v[8:9], 1, v[2:3]
	v_lshl_add_u64 v[0:1], v[0:1], 0, v[8:9]
	global_load_dwordx4 v[0:3], v[0:1], off offset:704
	v_add_u32_e32 v10, s17, v10
	s_waitcnt vmcnt(0)
; DEVI unsigned cvtpk(float lo, float hi) { unsigned r; asm volatile("v_cvt_pk_bf16_f32 %0, %1, %2" : "=v"(r) : "v"(lo), "v"(hi)); return r; }
; DEVI float siluf_(float x) { return x / (1.f + __expf(-x)); }
; DEVI void prepMLA_tile(const Params& p, int l, int g, int tile, char* lds) {
;     ...
; #pragma unroll
;   for (int i = 0; i < 6; ++i) {
;     int it = tid + i * 512; int tok = it / 48, ch = it % 48;
;     h16x8 z = *(const h16x8*)(Z + (size_t)tok * NBC + 352 + ch * 8);
;     u32x4 w; w.x = cvtpk(siluf_((float)z[0]), siluf_((float)z[1])); w.y = cvtpk(siluf_((float)z[2]), siluf_((float)z[3]));
;     w.z = cvtpk(siluf_((float)z[4]), siluf_((float)z[5])); w.w = cvtpk(siluf_((float)z[6]), siluf_((float)z[7]));
;     *(u32x4*)(Yb + (size_t)(t0 + tok) * 384 + ch * 8) = w;
;   }
	v_cvt_f32_f16_e32 v11, v0
	v_cvt_f32_f16_sdwa v0, v0 dst_sel:DWORD dst_unused:UNUSED_PAD src0_sel:WORD_1
	v_mul_f32_e32 v12, 0xbfb8aa3b, v11
	v_exp_f32_e32 v12, v12
	s_nop 0
	v_add_f32_e32 v12, 1.0, v12
	v_div_scale_f32 v13, s[0:1], v12, v12, v11
	v_rcp_f32_e32 v14, v13
	s_nop 0
	v_fma_f32 v15, -v13, v14, 1.0
	v_fmac_f32_e32 v14, v15, v14
	v_div_scale_f32 v15, vcc, v11, v12, v11
	v_mul_f32_e32 v16, v15, v14
	v_fma_f32 v17, -v13, v16, v15
	v_fmac_f32_e32 v16, v17, v14
	v_fma_f32 v13, -v13, v16, v15
	v_div_fmas_f32 v13, v13, v14, v16
	v_div_fixup_f32 v11, v13, v12, v11
	v_mul_f32_e32 v12, 0xbfb8aa3b, v0
	v_exp_f32_e32 v12, v12
	s_nop 0
	v_add_f32_e32 v12, 1.0, v12
	v_div_scale_f32 v13, s[0:1], v12, v12, v0
	v_rcp_f32_e32 v14, v13
	s_nop 0
	v_fma_f32 v15, -v13, v14, 1.0
	v_fmac_f32_e32 v14, v15, v14
	v_div_scale_f32 v15, vcc, v0, v12, v0
	v_mul_f32_e32 v16, v15, v14
	v_fma_f32 v17, -v13, v16, v15
	v_fmac_f32_e32 v16, v17, v14
	v_fma_f32 v13, -v13, v16, v15
	v_div_fmas_f32 v13, v13, v14, v16
	v_div_fixup_f32 v0, v13, v12, v0
	v_cvt_pk_bf16_f32 v0, v11, v0
	v_cvt_f32_f16_e32 v11, v1
	v_cvt_f32_f16_sdwa v1, v1 dst_sel:DWORD dst_unused:UNUSED_PAD src0_sel:WORD_1
	v_mul_f32_e32 v12, 0xbfb8aa3b, v11
	v_exp_f32_e32 v12, v12
	s_nop 0
	v_add_f32_e32 v12, 1.0, v12
	v_div_scale_f32 v13, s[0:1], v12, v12, v11
	v_rcp_f32_e32 v14, v13
	s_nop 0
	v_fma_f32 v15, -v13, v14, 1.0
	v_fmac_f32_e32 v14, v15, v14
	v_div_scale_f32 v15, vcc, v11, v12, v11
	v_mul_f32_e32 v16, v15, v14
	v_fma_f32 v17, -v13, v16, v15
	v_fmac_f32_e32 v16, v17, v14
	v_fma_f32 v13, -v13, v16, v15
	v_div_fmas_f32 v13, v13, v14, v16
	v_div_fixup_f32 v11, v13, v12, v11
	v_mul_f32_e32 v12, 0xbfb8aa3b, v1
	v_exp_f32_e32 v12, v12
	s_nop 0
	v_add_f32_e32 v12, 1.0, v12
	v_div_scale_f32 v13, s[0:1], v12, v12, v1
	v_rcp_f32_e32 v14, v13
	s_nop 0
	v_fma_f32 v15, -v13, v14, 1.0
	v_fmac_f32_e32 v14, v15, v14
	v_div_scale_f32 v15, vcc, v1, v12, v1
	v_mul_f32_e32 v16, v15, v14
	v_fma_f32 v17, -v13, v16, v15
	v_fmac_f32_e32 v16, v17, v14
	v_fma_f32 v13, -v13, v16, v15
	v_div_fmas_f32 v13, v13, v14, v16
	v_div_fixup_f32 v1, v13, v12, v1
	v_cvt_pk_bf16_f32 v1, v11, v1
	v_cvt_f32_f16_e32 v11, v2
	v_cvt_f32_f16_sdwa v2, v2 dst_sel:DWORD dst_unused:UNUSED_PAD src0_sel:WORD_1
	v_mul_f32_e32 v12, 0xbfb8aa3b, v11
	v_exp_f32_e32 v12, v12
	s_nop 0
	v_add_f32_e32 v12, 1.0, v12
	v_div_scale_f32 v13, s[0:1], v12, v12, v11
	v_rcp_f32_e32 v14, v13
	s_nop 0
	v_fma_f32 v15, -v13, v14, 1.0
	v_fmac_f32_e32 v14, v15, v14
	v_div_scale_f32 v15, vcc, v11, v12, v11
	v_mul_f32_e32 v16, v15, v14
	v_fma_f32 v17, -v13, v16, v15
	v_fmac_f32_e32 v16, v17, v14
	v_fma_f32 v13, -v13, v16, v15
	v_div_fmas_f32 v13, v13, v14, v16
	v_div_fixup_f32 v11, v13, v12, v11
	v_mul_f32_e32 v12, 0xbfb8aa3b, v2
	v_exp_f32_e32 v12, v12
	s_nop 0
	v_add_f32_e32 v12, 1.0, v12
	v_div_scale_f32 v13, s[0:1], v12, v12, v2
	v_rcp_f32_e32 v14, v13
	s_nop 0
	v_fma_f32 v15, -v13, v14, 1.0
	v_fmac_f32_e32 v14, v15, v14
	v_div_scale_f32 v15, vcc, v2, v12, v2
	v_mul_f32_e32 v16, v15, v14
	v_fma_f32 v17, -v13, v16, v15
	v_fmac_f32_e32 v16, v17, v14
	v_fma_f32 v13, -v13, v16, v15
	v_div_fmas_f32 v13, v13, v14, v16
	v_div_fixup_f32 v2, v13, v12, v2
	v_cvt_pk_bf16_f32 v2, v11, v2
	v_cvt_f32_f16_e32 v11, v3
	v_cvt_f32_f16_sdwa v3, v3 dst_sel:DWORD dst_unused:UNUSED_PAD src0_sel:WORD_1
	v_mul_f32_e32 v12, 0xbfb8aa3b, v11
	v_exp_f32_e32 v12, v12
	s_nop 0
	v_add_f32_e32 v12, 1.0, v12
	v_div_scale_f32 v13, s[0:1], v12, v12, v11
	v_rcp_f32_e32 v14, v13
	s_nop 0
	v_fma_f32 v15, -v13, v14, 1.0
	v_fmac_f32_e32 v14, v15, v14
	v_div_scale_f32 v15, vcc, v11, v12, v11
	v_mul_f32_e32 v16, v15, v14
	v_fma_f32 v17, -v13, v16, v15
	v_fmac_f32_e32 v16, v17, v14
	v_fma_f32 v13, -v13, v16, v15
	v_div_fmas_f32 v13, v13, v14, v16
	v_div_fixup_f32 v11, v13, v12, v11
	v_mul_f32_e32 v12, 0xbfb8aa3b, v3
	v_exp_f32_e32 v12, v12
	s_nop 0
	v_add_f32_e32 v12, 1.0, v12
	v_div_scale_f32 v13, s[0:1], v12, v12, v3
	v_rcp_f32_e32 v14, v13
	s_nop 0
	v_fma_f32 v15, -v13, v14, 1.0
	v_fmac_f32_e32 v14, v15, v14
	v_div_scale_f32 v15, vcc, v3, v12, v3
	v_mul_f32_e32 v16, v15, v14
	v_fma_f32 v17, -v13, v16, v15
	v_fmac_f32_e32 v16, v17, v14
	v_fma_f32 v13, -v13, v16, v15
	v_div_fmas_f32 v13, v13, v14, v16
	v_div_fixup_f32 v3, v13, v12, v3
	v_cvt_pk_bf16_f32 v3, v11, v3
	v_mad_i64_i32 v[10:11], s[0:1], v10, s35, v[6:7]
	v_lshl_add_u64 v[8:9], v[10:11], 0, v[8:9]
	global_store_dwordx4 v[8:9], v[0:3], off
	s_nop 1
	v_add_u32_e32 v0, 0x600, v55
	v_mul_hi_i32 v1, v0, s38
	v_lshrrev_b32_e32 v2, 31, v1
	v_ashrrev_i32_e32 v1, 3, v1
	v_add_u32_e32 v10, v1, v2
	v_mul_lo_u32 v1, v10, 48
	v_sub_u32_e32 v2, v0, v1
	v_lshlrev_b32_e32 v2, 3, v2
	v_ashrrev_i32_e32 v3, 31, v2
	v_mad_i64_i32 v[0:1], s[0:1], v10, s23, v[4:5]
	v_lshlrev_b64 v[8:9], 1, v[2:3]
	v_lshl_add_u64 v[0:1], v[0:1], 0, v[8:9]
	global_load_dwordx4 v[0:3], v[0:1], off offset:704
	v_add_u32_e32 v10, s17, v10
	s_waitcnt vmcnt(0)
; DEVI unsigned cvtpk(float lo, float hi) { unsigned r; asm volatile("v_cvt_pk_bf16_f32 %0, %1, %2" : "=v"(r) : "v"(lo), "v"(hi)); return r; }
; DEVI float siluf_(float x) { return x / (1.f + __expf(-x)); }
; DEVI void prepMLA_tile(const Params& p, int l, int g, int tile, char* lds) {
;     ...
; #pragma unroll
;   for (int i = 0; i < 6; ++i) {
;     int it = tid + i * 512; int tok = it / 48, ch = it % 48;
;     h16x8 z = *(const h16x8*)(Z + (size_t)tok * NBC + 352 + ch * 8);
;     u32x4 w; w.x = cvtpk(siluf_((float)z[0]), siluf_((float)z[1])); w.y = cvtpk(siluf_((float)z[2]), siluf_((float)z[3]));
;     w.z = cvtpk(siluf_((float)z[4]), siluf_((float)z[5])); w.w = cvtpk(siluf_((float)z[6]), siluf_((float)z[7]));
;     *(u32x4*)(Yb + (size_t)(t0 + tok) * 384 + ch * 8) = w;
;   }
	v_cvt_f32_f16_e32 v11, v0
	v_cvt_f32_f16_sdwa v0, v0 dst_sel:DWORD dst_unused:UNUSED_PAD src0_sel:WORD_1
	v_mul_f32_e32 v12, 0xbfb8aa3b, v11
	v_exp_f32_e32 v12, v12
	s_nop 0
	v_add_f32_e32 v12, 1.0, v12
	v_div_scale_f32 v13, s[0:1], v12, v12, v11
	v_rcp_f32_e32 v14, v13
	s_nop 0
	v_fma_f32 v15, -v13, v14, 1.0
	v_fmac_f32_e32 v14, v15, v14
	v_div_scale_f32 v15, vcc, v11, v12, v11
	v_mul_f32_e32 v16, v15, v14
	v_fma_f32 v17, -v13, v16, v15
	v_fmac_f32_e32 v16, v17, v14
	v_fma_f32 v13, -v13, v16, v15
	v_div_fmas_f32 v13, v13, v14, v16
	v_div_fixup_f32 v11, v13, v12, v11
	v_mul_f32_e32 v12, 0xbfb8aa3b, v0
	v_exp_f32_e32 v12, v12
	s_nop 0
	v_add_f32_e32 v12, 1.0, v12
	v_div_scale_f32 v13, s[0:1], v12, v12, v0
	v_rcp_f32_e32 v14, v13
	s_nop 0
	v_fma_f32 v15, -v13, v14, 1.0
	v_fmac_f32_e32 v14, v15, v14
	v_div_scale_f32 v15, vcc, v0, v12, v0
	v_mul_f32_e32 v16, v15, v14
	v_fma_f32 v17, -v13, v16, v15
	v_fmac_f32_e32 v16, v17, v14
	v_fma_f32 v13, -v13, v16, v15
	v_div_fmas_f32 v13, v13, v14, v16
	v_div_fixup_f32 v0, v13, v12, v0
	v_cvt_pk_bf16_f32 v0, v11, v0
	v_cvt_f32_f16_e32 v11, v1
	v_cvt_f32_f16_sdwa v1, v1 dst_sel:DWORD dst_unused:UNUSED_PAD src0_sel:WORD_1
	v_mul_f32_e32 v12, 0xbfb8aa3b, v11
	v_exp_f32_e32 v12, v12
	s_nop 0
	v_add_f32_e32 v12, 1.0, v12
	v_div_scale_f32 v13, s[0:1], v12, v12, v11
	v_rcp_f32_e32 v14, v13
	s_nop 0
	v_fma_f32 v15, -v13, v14, 1.0
	v_fmac_f32_e32 v14, v15, v14
	v_div_scale_f32 v15, vcc, v11, v12, v11
	v_mul_f32_e32 v16, v15, v14
	v_fma_f32 v17, -v13, v16, v15
	v_fmac_f32_e32 v16, v17, v14
	v_fma_f32 v13, -v13, v16, v15
	v_div_fmas_f32 v13, v13, v14, v16
	v_div_fixup_f32 v11, v13, v12, v11
	v_mul_f32_e32 v12, 0xbfb8aa3b, v1
	v_exp_f32_e32 v12, v12
	s_nop 0
	v_add_f32_e32 v12, 1.0, v12
	v_div_scale_f32 v13, s[0:1], v12, v12, v1
	v_rcp_f32_e32 v14, v13
	s_nop 0
	v_fma_f32 v15, -v13, v14, 1.0
	v_fmac_f32_e32 v14, v15, v14
	v_div_scale_f32 v15, vcc, v1, v12, v1
	v_mul_f32_e32 v16, v15, v14
	v_fma_f32 v17, -v13, v16, v15
	v_fmac_f32_e32 v16, v17, v14
	v_fma_f32 v13, -v13, v16, v15
	v_div_fmas_f32 v13, v13, v14, v16
	v_div_fixup_f32 v1, v13, v12, v1
	v_cvt_pk_bf16_f32 v1, v11, v1
	v_cvt_f32_f16_e32 v11, v2
	v_cvt_f32_f16_sdwa v2, v2 dst_sel:DWORD dst_unused:UNUSED_PAD src0_sel:WORD_1
	v_mul_f32_e32 v12, 0xbfb8aa3b, v11
	v_exp_f32_e32 v12, v12
	s_nop 0
	v_add_f32_e32 v12, 1.0, v12
	v_div_scale_f32 v13, s[0:1], v12, v12, v11
	v_rcp_f32_e32 v14, v13
	s_nop 0
	v_fma_f32 v15, -v13, v14, 1.0
	v_fmac_f32_e32 v14, v15, v14
	v_div_scale_f32 v15, vcc, v11, v12, v11
	v_mul_f32_e32 v16, v15, v14
	v_fma_f32 v17, -v13, v16, v15
	v_fmac_f32_e32 v16, v17, v14
	v_fma_f32 v13, -v13, v16, v15
	v_div_fmas_f32 v13, v13, v14, v16
	v_div_fixup_f32 v11, v13, v12, v11
	v_mul_f32_e32 v12, 0xbfb8aa3b, v2
	v_exp_f32_e32 v12, v12
	s_nop 0
	v_add_f32_e32 v12, 1.0, v12
	v_div_scale_f32 v13, s[0:1], v12, v12, v2
	v_rcp_f32_e32 v14, v13
	s_nop 0
	v_fma_f32 v15, -v13, v14, 1.0
	v_fmac_f32_e32 v14, v15, v14
	v_div_scale_f32 v15, vcc, v2, v12, v2
	v_mul_f32_e32 v16, v15, v14
	v_fma_f32 v17, -v13, v16, v15
	v_fmac_f32_e32 v16, v17, v14
	v_fma_f32 v13, -v13, v16, v15
	v_div_fmas_f32 v13, v13, v14, v16
	v_div_fixup_f32 v2, v13, v12, v2
	v_cvt_pk_bf16_f32 v2, v11, v2
	v_cvt_f32_f16_e32 v11, v3
	v_cvt_f32_f16_sdwa v3, v3 dst_sel:DWORD dst_unused:UNUSED_PAD src0_sel:WORD_1
	v_mul_f32_e32 v12, 0xbfb8aa3b, v11
	v_exp_f32_e32 v12, v12
	s_nop 0
	v_add_f32_e32 v12, 1.0, v12
	v_div_scale_f32 v13, s[0:1], v12, v12, v11
	v_rcp_f32_e32 v14, v13
	s_nop 0
	v_fma_f32 v15, -v13, v14, 1.0
	v_fmac_f32_e32 v14, v15, v14
	v_div_scale_f32 v15, vcc, v11, v12, v11
	v_mul_f32_e32 v16, v15, v14
	v_fma_f32 v17, -v13, v16, v15
	v_fmac_f32_e32 v16, v17, v14
	v_fma_f32 v13, -v13, v16, v15
	v_div_fmas_f32 v13, v13, v14, v16
	v_div_fixup_f32 v11, v13, v12, v11
	v_mul_f32_e32 v12, 0xbfb8aa3b, v3
	v_exp_f32_e32 v12, v12
	s_nop 0
	v_add_f32_e32 v12, 1.0, v12
	v_div_scale_f32 v13, s[0:1], v12, v12, v3
	v_rcp_f32_e32 v14, v13
	s_nop 0
	v_fma_f32 v15, -v13, v14, 1.0
	v_fmac_f32_e32 v14, v15, v14
	v_div_scale_f32 v15, vcc, v3, v12, v3
	v_mul_f32_e32 v16, v15, v14
	v_fma_f32 v17, -v13, v16, v15
	v_fmac_f32_e32 v16, v17, v14
	v_fma_f32 v13, -v13, v16, v15
	v_div_fmas_f32 v13, v13, v14, v16
	v_div_fixup_f32 v3, v13, v12, v3
	v_cvt_pk_bf16_f32 v3, v11, v3
	v_mad_i64_i32 v[10:11], s[0:1], v10, s35, v[6:7]
	v_lshl_add_u64 v[8:9], v[10:11], 0, v[8:9]
	global_store_dwordx4 v[8:9], v[0:3], off
	s_nop 1
	v_add_u32_e32 v0, 0x800, v55
	v_mul_hi_i32 v1, v0, s38
	v_lshrrev_b32_e32 v2, 31, v1
	v_ashrrev_i32_e32 v1, 3, v1
	v_add_u32_e32 v10, v1, v2
	v_mul_lo_u32 v1, v10, 48
	v_sub_u32_e32 v2, v0, v1
	v_lshlrev_b32_e32 v2, 3, v2
	v_ashrrev_i32_e32 v3, 31, v2
	v_mad_i64_i32 v[0:1], s[0:1], v10, s23, v[4:5]
	v_lshlrev_b64 v[8:9], 1, v[2:3]
	v_lshl_add_u64 v[0:1], v[0:1], 0, v[8:9]
	global_load_dwordx4 v[0:3], v[0:1], off offset:704
	v_add_u32_e32 v10, s17, v10
	s_waitcnt vmcnt(0)
; DEVI unsigned cvtpk(float lo, float hi) { unsigned r; asm volatile("v_cvt_pk_bf16_f32 %0, %1, %2" : "=v"(r) : "v"(lo), "v"(hi)); return r; }
; DEVI float siluf_(float x) { return x / (1.f + __expf(-x)); }
; DEVI void prepMLA_tile(const Params& p, int l, int g, int tile, char* lds) {
;     ...
; #pragma unroll
;   for (int i = 0; i < 6; ++i) {
;     int it = tid + i * 512; int tok = it / 48, ch = it % 48;
;     h16x8 z = *(const h16x8*)(Z + (size_t)tok * NBC + 352 + ch * 8);
;     u32x4 w; w.x = cvtpk(siluf_((float)z[0]), siluf_((float)z[1])); w.y = cvtpk(siluf_((float)z[2]), siluf_((float)z[3]));
;     w.z = cvtpk(siluf_((float)z[4]), siluf_((float)z[5])); w.w = cvtpk(siluf_((float)z[6]), siluf_((float)z[7]));
;     *(u32x4*)(Yb + (size_t)(t0 + tok) * 384 + ch * 8) = w;
;   }
	v_cvt_f32_f16_e32 v11, v0
	v_cvt_f32_f16_sdwa v0, v0 dst_sel:DWORD dst_unused:UNUSED_PAD src0_sel:WORD_1
	v_mul_f32_e32 v12, 0xbfb8aa3b, v11
	v_exp_f32_e32 v12, v12
	s_nop 0
	v_add_f32_e32 v12, 1.0, v12
	v_div_scale_f32 v13, s[0:1], v12, v12, v11
	v_rcp_f32_e32 v14, v13
	s_nop 0
	v_fma_f32 v15, -v13, v14, 1.0
	v_fmac_f32_e32 v14, v15, v14
	v_div_scale_f32 v15, vcc, v11, v12, v11
	v_mul_f32_e32 v16, v15, v14
	v_fma_f32 v17, -v13, v16, v15
	v_fmac_f32_e32 v16, v17, v14
	v_fma_f32 v13, -v13, v16, v15
	v_div_fmas_f32 v13, v13, v14, v16
	v_div_fixup_f32 v11, v13, v12, v11
	v_mul_f32_e32 v12, 0xbfb8aa3b, v0
	v_exp_f32_e32 v12, v12
	s_nop 0
	v_add_f32_e32 v12, 1.0, v12
	v_div_scale_f32 v13, s[0:1], v12, v12, v0
	v_rcp_f32_e32 v14, v13
	s_nop 0
	v_fma_f32 v15, -v13, v14, 1.0
	v_fmac_f32_e32 v14, v15, v14
	v_div_scale_f32 v15, vcc, v0, v12, v0
	v_mul_f32_e32 v16, v15, v14
	v_fma_f32 v17, -v13, v16, v15
	v_fmac_f32_e32 v16, v17, v14
	v_fma_f32 v13, -v13, v16, v15
	v_div_fmas_f32 v13, v13, v14, v16
	v_div_fixup_f32 v0, v13, v12, v0
	v_cvt_pk_bf16_f32 v0, v11, v0
	v_cvt_f32_f16_e32 v11, v1
	v_cvt_f32_f16_sdwa v1, v1 dst_sel:DWORD dst_unused:UNUSED_PAD src0_sel:WORD_1
	v_mul_f32_e32 v12, 0xbfb8aa3b, v11
	v_exp_f32_e32 v12, v12
	s_nop 0
	v_add_f32_e32 v12, 1.0, v12
	v_div_scale_f32 v13, s[0:1], v12, v12, v11
	v_rcp_f32_e32 v14, v13
	s_nop 0
	v_fma_f32 v15, -v13, v14, 1.0
	v_fmac_f32_e32 v14, v15, v14
	v_div_scale_f32 v15, vcc, v11, v12, v11
	v_mul_f32_e32 v16, v15, v14
	v_fma_f32 v17, -v13, v16, v15
	v_fmac_f32_e32 v16, v17, v14
	v_fma_f32 v13, -v13, v16, v15
	v_div_fmas_f32 v13, v13, v14, v16
	v_div_fixup_f32 v11, v13, v12, v11
	v_mul_f32_e32 v12, 0xbfb8aa3b, v1
	v_exp_f32_e32 v12, v12
	s_nop 0
	v_add_f32_e32 v12, 1.0, v12
	v_div_scale_f32 v13, s[0:1], v12, v12, v1
	v_rcp_f32_e32 v14, v13
	s_nop 0
	v_fma_f32 v15, -v13, v14, 1.0
	v_fmac_f32_e32 v14, v15, v14
	v_div_scale_f32 v15, vcc, v1, v12, v1
	v_mul_f32_e32 v16, v15, v14
	v_fma_f32 v17, -v13, v16, v15
	v_fmac_f32_e32 v16, v17, v14
	v_fma_f32 v13, -v13, v16, v15
	v_div_fmas_f32 v13, v13, v14, v16
	v_div_fixup_f32 v1, v13, v12, v1
	v_cvt_pk_bf16_f32 v1, v11, v1
	v_cvt_f32_f16_e32 v11, v2
	v_cvt_f32_f16_sdwa v2, v2 dst_sel:DWORD dst_unused:UNUSED_PAD src0_sel:WORD_1
	v_mul_f32_e32 v12, 0xbfb8aa3b, v11
	v_exp_f32_e32 v12, v12
	s_nop 0
	v_add_f32_e32 v12, 1.0, v12
	v_div_scale_f32 v13, s[0:1], v12, v12, v11
	v_rcp_f32_e32 v14, v13
	s_nop 0
	v_fma_f32 v15, -v13, v14, 1.0
	v_fmac_f32_e32 v14, v15, v14
	v_div_scale_f32 v15, vcc, v11, v12, v11
	v_mul_f32_e32 v16, v15, v14
	v_fma_f32 v17, -v13, v16, v15
	v_fmac_f32_e32 v16, v17, v14
	v_fma_f32 v13, -v13, v16, v15
	v_div_fmas_f32 v13, v13, v14, v16
	v_div_fixup_f32 v11, v13, v12, v11
	v_mul_f32_e32 v12, 0xbfb8aa3b, v2
	v_exp_f32_e32 v12, v12
	s_nop 0
	v_add_f32_e32 v12, 1.0, v12
	v_div_scale_f32 v13, s[0:1], v12, v12, v2
	v_rcp_f32_e32 v14, v13
	s_nop 0
	v_fma_f32 v15, -v13, v14, 1.0
	v_fmac_f32_e32 v14, v15, v14
	v_div_scale_f32 v15, vcc, v2, v12, v2
	v_mul_f32_e32 v16, v15, v14
	v_fma_f32 v17, -v13, v16, v15
	v_fmac_f32_e32 v16, v17, v14
	v_fma_f32 v13, -v13, v16, v15
	v_div_fmas_f32 v13, v13, v14, v16
	v_div_fixup_f32 v2, v13, v12, v2
	v_cvt_pk_bf16_f32 v2, v11, v2
	v_cvt_f32_f16_e32 v11, v3
	v_cvt_f32_f16_sdwa v3, v3 dst_sel:DWORD dst_unused:UNUSED_PAD src0_sel:WORD_1
	v_mul_f32_e32 v12, 0xbfb8aa3b, v11
	v_exp_f32_e32 v12, v12
	s_nop 0
	v_add_f32_e32 v12, 1.0, v12
	v_div_scale_f32 v13, s[0:1], v12, v12, v11
	v_rcp_f32_e32 v14, v13
	s_nop 0
	v_fma_f32 v15, -v13, v14, 1.0
	v_fmac_f32_e32 v14, v15, v14
	v_div_scale_f32 v15, vcc, v11, v12, v11
	v_mul_f32_e32 v16, v15, v14
	v_fma_f32 v17, -v13, v16, v15
	v_fmac_f32_e32 v16, v17, v14
	v_fma_f32 v13, -v13, v16, v15
	v_div_fmas_f32 v13, v13, v14, v16
	v_div_fixup_f32 v11, v13, v12, v11
	v_mul_f32_e32 v12, 0xbfb8aa3b, v3
	v_exp_f32_e32 v12, v12
	s_nop 0
	v_add_f32_e32 v12, 1.0, v12
	v_div_scale_f32 v13, s[0:1], v12, v12, v3
	v_rcp_f32_e32 v14, v13
	s_nop 0
	v_fma_f32 v15, -v13, v14, 1.0
	v_fmac_f32_e32 v14, v15, v14
	v_div_scale_f32 v15, vcc, v3, v12, v3
	v_mul_f32_e32 v16, v15, v14
	v_fma_f32 v17, -v13, v16, v15
	v_fmac_f32_e32 v16, v17, v14
	v_fma_f32 v13, -v13, v16, v15
	v_div_fmas_f32 v13, v13, v14, v16
	v_div_fixup_f32 v3, v13, v12, v3
	v_cvt_pk_bf16_f32 v3, v11, v3
	v_mad_i64_i32 v[10:11], s[0:1], v10, s35, v[6:7]
	v_lshl_add_u64 v[8:9], v[10:11], 0, v[8:9]
	global_store_dwordx4 v[8:9], v[0:3], off
	s_nop 1
	v_add_u32_e32 v0, 0xa00, v55
	v_mul_hi_i32 v1, v0, s38
	v_lshrrev_b32_e32 v2, 31, v1
	v_ashrrev_i32_e32 v1, 3, v1
	v_add_u32_e32 v8, v1, v2
	v_mul_lo_u32 v1, v8, 48
	v_sub_u32_e32 v2, v0, v1
	v_lshlrev_b32_e32 v2, 3, v2
	v_ashrrev_i32_e32 v3, 31, v2
	v_mad_i64_i32 v[0:1], s[0:1], v8, s23, v[4:5]
	v_lshlrev_b64 v[4:5], 1, v[2:3]
	v_lshl_add_u64 v[0:1], v[0:1], 0, v[4:5]
	global_load_dwordx4 v[0:3], v[0:1], off offset:704
	v_add_u32_e32 v8, s17, v8
	v_mad_i64_i32 v[6:7], s[0:1], v8, s35, v[6:7]
	v_lshl_add_u64 v[4:5], v[6:7], 0, v[4:5]
	s_mov_b32 s38, 0
	s_waitcnt vmcnt(0)
; DEVI unsigned cvtpk(float lo, float hi) { unsigned r; asm volatile("v_cvt_pk_bf16_f32 %0, %1, %2" : "=v"(r) : "v"(lo), "v"(hi)); return r; }
; DEVI u16 f2bf(float f) { return (u16)(cvtpk(f, 0.f) & 0xffffu); }
; DEVI float siluf_(float x) { return x / (1.f + __expf(-x)); }
; DEVI void prepMLA_tile(const Params& p, int l, int g, int tile, char* lds) {
;     ...
; #pragma unroll
;   for (int i = 0; i < 6; ++i) {
;     int it = tid + i * 512; int tok = it / 48, ch = it % 48;
;     h16x8 z = *(const h16x8*)(Z + (size_t)tok * NBC + 352 + ch * 8);
;     u32x4 w; w.x = cvtpk(siluf_((float)z[0]), siluf_((float)z[1])); w.y = cvtpk(siluf_((float)z[2]), siluf_((float)z[3]));
;     w.z = cvtpk(siluf_((float)z[4]), siluf_((float)z[5])); w.w = cvtpk(siluf_((float)z[6]), siluf_((float)z[7]));
;     *(u32x4*)(Yb + (size_t)(t0 + tok) * 384 + ch * 8) = w;
;   }
;   {
;     const float* qnw = p.q_norm_w + l * 192; const float* kvnw = p.kv_norm_w + l * 128;
; #pragma unroll 1
;     for (int i = 0; i < 8; ++i) {
;       int tok = wid * 8 + i; const h16* zr = Z + (size_t)tok * NBC;
;       float e0 = (float)zr[lane], e1 = (float)zr[64 + lane], e2 = (float)zr[128 + lane];
;       float f0 = (float)zr[192 + lane], f1 = (float)zr[256 + lane];
;       float sq = wave_sum(e0 * e0 + e1 * e1 + e2 * e2), sk = wave_sum(f0 * f0 + f1 * f1);
;       float rq = rsqrtf(sq * (1.f / 192.f) + 1e-6f), rk = rsqrtf(sk * (1.f / 128.f) + 1e-6f);
;       u16* aq = (u16*)(Aq + tok * RSQ); u16* ak = (u16*)(Akv + tok * RSKV);
;       aq[lane] = f2bf(e0 * rq * qnw[lane]); aq[64 + lane] = f2bf(e1 * rq * qnw[64 + lane]); aq[128 + lane] = f2bf(e2 * rq * qnw[128 + lane]);
;       ak[lane] = f2bf(f0 * rk * kvnw[lane]); ak[64 + lane] = f2bf(f1 * rk * kvnw[64 + lane]);
	v_cvt_f32_f16_e32 v9, v0
	v_cvt_f32_f16_sdwa v0, v0 dst_sel:DWORD dst_unused:UNUSED_PAD src0_sel:WORD_1
	v_mul_f32_e32 v10, 0xbfb8aa3b, v9
	v_exp_f32_e32 v10, v10
	s_nop 0
	v_add_f32_e32 v10, 1.0, v10
	v_div_scale_f32 v11, s[0:1], v10, v10, v9
	v_rcp_f32_e32 v12, v11
	s_nop 0
	v_fma_f32 v13, -v11, v12, 1.0
	v_fmac_f32_e32 v12, v13, v12
	v_div_scale_f32 v13, vcc, v9, v10, v9
	v_mul_f32_e32 v14, v13, v12
	v_fma_f32 v15, -v11, v14, v13
	v_fmac_f32_e32 v14, v15, v12
	v_fma_f32 v11, -v11, v14, v13
	v_div_fmas_f32 v11, v11, v12, v14
	v_div_fixup_f32 v9, v11, v10, v9
	v_mul_f32_e32 v10, 0xbfb8aa3b, v0
	v_exp_f32_e32 v10, v10
	s_nop 0
	v_add_f32_e32 v10, 1.0, v10
	v_div_scale_f32 v11, s[0:1], v10, v10, v0
	v_rcp_f32_e32 v12, v11
	s_nop 0
	v_fma_f32 v13, -v11, v12, 1.0
	v_fmac_f32_e32 v12, v13, v12
	v_div_scale_f32 v13, vcc, v0, v10, v0
	v_mul_f32_e32 v14, v13, v12
	v_fma_f32 v15, -v11, v14, v13
	v_fmac_f32_e32 v14, v15, v12
	v_fma_f32 v11, -v11, v14, v13
	v_div_fmas_f32 v11, v11, v12, v14
	v_div_fixup_f32 v0, v11, v10, v0
	v_cvt_pk_bf16_f32 v0, v9, v0
	v_cvt_f32_f16_e32 v9, v1
	v_cvt_f32_f16_sdwa v1, v1 dst_sel:DWORD dst_unused:UNUSED_PAD src0_sel:WORD_1
	v_mul_f32_e32 v10, 0xbfb8aa3b, v9
	v_exp_f32_e32 v10, v10
	s_nop 0
	v_add_f32_e32 v10, 1.0, v10
	v_div_scale_f32 v11, s[0:1], v10, v10, v9
	v_rcp_f32_e32 v12, v11
	s_nop 0
	v_fma_f32 v13, -v11, v12, 1.0
	v_fmac_f32_e32 v12, v13, v12
	v_div_scale_f32 v13, vcc, v9, v10, v9
	v_mul_f32_e32 v14, v13, v12
	v_fma_f32 v15, -v11, v14, v13
	v_fmac_f32_e32 v14, v15, v12
	v_fma_f32 v11, -v11, v14, v13
	v_div_fmas_f32 v11, v11, v12, v14
	v_div_fixup_f32 v9, v11, v10, v9
	v_mul_f32_e32 v10, 0xbfb8aa3b, v1
	v_exp_f32_e32 v10, v10
	s_nop 0
	v_add_f32_e32 v10, 1.0, v10
	v_div_scale_f32 v11, s[0:1], v10, v10, v1
	v_rcp_f32_e32 v12, v11
	s_nop 0
	v_fma_f32 v13, -v11, v12, 1.0
	v_fmac_f32_e32 v12, v13, v12
	v_div_scale_f32 v13, vcc, v1, v10, v1
	v_mul_f32_e32 v14, v13, v12
	v_fma_f32 v15, -v11, v14, v13
	v_fmac_f32_e32 v14, v15, v12
	v_fma_f32 v11, -v11, v14, v13
	v_div_fmas_f32 v11, v11, v12, v14
	v_div_fixup_f32 v1, v11, v10, v1
	v_cvt_pk_bf16_f32 v1, v9, v1
	v_cvt_f32_f16_e32 v9, v2
	v_cvt_f32_f16_sdwa v2, v2 dst_sel:DWORD dst_unused:UNUSED_PAD src0_sel:WORD_1
	v_mul_f32_e32 v10, 0xbfb8aa3b, v9
	v_exp_f32_e32 v10, v10
	s_nop 0
	v_add_f32_e32 v10, 1.0, v10
	v_div_scale_f32 v11, s[0:1], v10, v10, v9
	v_rcp_f32_e32 v12, v11
	s_nop 0
	v_fma_f32 v13, -v11, v12, 1.0
	v_fmac_f32_e32 v12, v13, v12
	v_div_scale_f32 v13, vcc, v9, v10, v9
	v_mul_f32_e32 v14, v13, v12
	v_fma_f32 v15, -v11, v14, v13
	v_fmac_f32_e32 v14, v15, v12
	v_fma_f32 v11, -v11, v14, v13
	v_div_fmas_f32 v11, v11, v12, v14
	v_div_fixup_f32 v9, v11, v10, v9
	v_mul_f32_e32 v10, 0xbfb8aa3b, v2
	v_exp_f32_e32 v10, v10
	s_nop 0
	v_add_f32_e32 v10, 1.0, v10
	v_div_scale_f32 v11, s[0:1], v10, v10, v2
	v_rcp_f32_e32 v12, v11
	s_nop 0
	v_fma_f32 v13, -v11, v12, 1.0
	v_fmac_f32_e32 v12, v13, v12
	v_div_scale_f32 v13, vcc, v2, v10, v2
	v_mul_f32_e32 v14, v13, v12
	v_fma_f32 v15, -v11, v14, v13
	v_fmac_f32_e32 v14, v15, v12
	v_fma_f32 v11, -v11, v14, v13
	v_div_fmas_f32 v11, v11, v12, v14
	v_div_fixup_f32 v2, v11, v10, v2
	v_cvt_pk_bf16_f32 v2, v9, v2
	v_cvt_f32_f16_e32 v9, v3
	v_cvt_f32_f16_sdwa v3, v3 dst_sel:DWORD dst_unused:UNUSED_PAD src0_sel:WORD_1
	v_mul_f32_e32 v10, 0xbfb8aa3b, v9
	v_exp_f32_e32 v10, v10
	s_nop 0
	v_add_f32_e32 v10, 1.0, v10
	v_div_scale_f32 v11, s[0:1], v10, v10, v9
	v_rcp_f32_e32 v12, v11
	s_nop 0
	v_fma_f32 v13, -v11, v12, 1.0
	v_fmac_f32_e32 v12, v13, v12
	v_div_scale_f32 v13, vcc, v9, v10, v9
	v_mul_f32_e32 v14, v13, v12
	v_fma_f32 v15, -v11, v14, v13
	v_fmac_f32_e32 v14, v15, v12
	v_fma_f32 v11, -v11, v14, v13
	v_div_fmas_f32 v11, v11, v12, v14
	v_div_fixup_f32 v9, v11, v10, v9
	v_mul_f32_e32 v10, 0xbfb8aa3b, v3
	v_exp_f32_e32 v10, v10
	s_nop 0
	v_add_f32_e32 v10, 1.0, v10
	v_div_scale_f32 v11, s[0:1], v10, v10, v3
	v_rcp_f32_e32 v12, v11
	v_readlane_b32 s0, v220, 48
	v_fma_f32 v13, -v11, v12, 1.0
	v_fmac_f32_e32 v12, v13, v12
	v_div_scale_f32 v13, vcc, v3, v10, v3
	v_mul_f32_e32 v14, v13, v12
	v_fma_f32 v15, -v11, v14, v13
	v_fmac_f32_e32 v14, v15, v12
	v_fma_f32 v11, -v11, v14, v13
	v_div_fmas_f32 v11, v11, v12, v14
	v_div_fixup_f32 v3, v11, v10, v3
	v_cvt_pk_bf16_f32 v3, v9, v3
	global_store_dwordx4 v[4:5], v[0:3], off
	v_lshl_or_b32 v5, v52, 10, v128
	v_add_u32_e32 v6, s0, v5
	s_movk_i32 s0, 0x880
	v_mul_lo_u32 v5, v52, s0
	v_readlane_b32 s0, v220, 49
	v_lshlrev_b32_e32 v4, 3, v52
	v_lshl_add_u64 v[0:1], s[50:51], 0, v[128:129]
	v_add_u32_e32 v7, s0, v5
	s_movk_i32 s0, 0xc80
	v_mul_lo_u32 v5, v52, s0
	v_add_u32_e32 v8, 16, v5
	v_mad_i64_i32 v[4:5], s[0:1], v4, s23, 0
	v_lshl_add_u64 v[2:3], s[10:11], 0, v[128:129]
	v_lshlrev_b32_e32 v128, 1, v54
	v_mad_i64_i32 v[4:5], s[0:1], s16, v142, v[4:5]
	v_lshl_add_u64 v[4:5], v[4:5], 0, v[128:129]
	v_cmp_gt_u32_e32 vcc, 32, v54
	v_lshl_add_u64 v[4:5], s[30:31], 0, v[4:5]
	global_load_dword v162, v[0:1], off
	global_load_dword v163, v[0:1], off offset:256
	global_load_dword v164, v[0:1], off offset:512
	global_load_dword v165, v[2:3], off
	global_load_dword v166, v[2:3], off offset:256
	s_branch .LBB0_782

; DEVI u16 f2bf(float f) { return (u16)(cvtpk(f, 0.f) & 0xffffu); }
; DEVI void prepMLA_tile(const Params& p, int l, int g, int tile, char* lds) {
;     ...
;     for (int i = 0; i < 8; ++i) {
;       int tok = wid * 8 + i; const h16* zr = Z + (size_t)tok * NBC;
;       float e0 = (float)zr[lane], e1 = (float)zr[64 + lane], e2 = (float)zr[128 + lane];
;       float f0 = (float)zr[192 + lane], f1 = (float)zr[256 + lane];
;       float sq = wave_sum(e0 * e0 + e1 * e1 + e2 * e2), sk = wave_sum(f0 * f0 + f1 * f1);
;       float rq = rsqrtf(sq * (1.f / 192.f) + 1e-6f), rk = rsqrtf(sk * (1.f / 128.f) + 1e-6f);
;       u16* aq = (u16*)(Aq + tok * RSQ); u16* ak = (u16*)(Akv + tok * RSKV);
;       aq[lane] = f2bf(e0 * rq * qnw[lane]); aq[64 + lane] = f2bf(e1 * rq * qnw[64 + lane]); aq[128 + lane] = f2bf(e2 * rq * qnw[128 + lane]);
;       ak[lane] = f2bf(f0 * rk * kvnw[lane]); ak[64 + lane] = f2bf(f1 * rk * kvnw[64 + lane]);
;       if (lane < 32) kro[tok * 32 + lane] = (float)zr[320 + lane];
;     }
.LBB0_782:
	global_load_ushort v9, v[4:5], off offset:-256
	global_load_ushort v10, v[4:5], off offset:128
	global_load_ushort v14, v[4:5], off offset:-128
	global_load_ushort v15, v[4:5], off offset:-384
	global_load_ushort v16, v[4:5], off
	global_load_ushort v167, v[4:5], off offset:256
	s_brev_b32 s0, 60
	s_mov_b32 s1, 0x3baaaaab
	s_waitcnt vmcnt(5)
	v_cvt_f32_f16_e32 v9, v9
	s_waitcnt vmcnt(4)
	v_cvt_f32_f16_e32 v18, v10
	v_mul_f32_e32 v10, v9, v9
	v_mul_f32_e32 v11, v18, v18
	s_waitcnt vmcnt(2)
	v_fma_mix_f32 v10, v15, v15, v10 op_sel_hi:[1,1,0]
	s_waitcnt vmcnt(1)
	v_fma_mix_f32 v11, v16, v16, v11 op_sel_hi:[1,1,0]
	v_fma_mix_f32 v10, v14, v14, v10 op_sel_hi:[1,1,0]
	s_nop 0
	v_add_f32_dpp v11, v11, v11 quad_perm:[1,0,3,2] row_mask:0xf bank_mask:0xf bound_ctrl:1
	v_add_f32_dpp v10, v10, v10 quad_perm:[1,0,3,2] row_mask:0xf bank_mask:0xf bound_ctrl:1
	s_nop 0
	v_add_f32_dpp v11, v11, v11 quad_perm:[2,3,0,1] row_mask:0xf bank_mask:0xf bound_ctrl:1
	v_add_f32_dpp v10, v10, v10 quad_perm:[2,3,0,1] row_mask:0xf bank_mask:0xf bound_ctrl:1
	s_nop 0
	v_add_f32_dpp v11, v11, v11 row_half_mirror row_mask:0xf bank_mask:0xf bound_ctrl:1
	v_add_f32_dpp v10, v10, v10 row_half_mirror row_mask:0xf bank_mask:0xf bound_ctrl:1
	s_nop 0
	v_add_f32_dpp v11, v11, v11 row_mirror row_mask:0xf bank_mask:0xf bound_ctrl:1
	v_add_f32_dpp v12, v10, v10 row_mirror row_mask:0xf bank_mask:0xf bound_ctrl:1
	v_mov_b32_e32 v10, v11
	v_mov_b32_e32 v13, v12
	s_nop 0
	v_permlane16_swap_b32_e32 v11, v10
	v_permlane16_swap_b32_e32 v12, v13
	v_add_f32_e32 v10, v11, v10
	v_add_f32_e32 v11, v12, v13
	v_mov_b32_e32 v12, v10
	v_mov_b32_e32 v13, v11
	s_nop 0
	v_permlane32_swap_b32_e32 v10, v12
	v_permlane32_swap_b32_e32 v11, v13
	v_pk_add_f32 v[10:11], v[10:11], v[12:13]
	s_nop 0
	v_pk_fma_f32 v[10:11], v[10:11], s[0:1], v[130:131] op_sel_hi:[1,1,0]
	s_nop 0
	v_mul_f32_e32 v12, 0x4b800000, v11
	v_cmp_gt_f32_e64 s[0:1], s26, v11
	s_nop 1
	v_cndmask_b32_e64 v11, v11, v12, s[0:1]
	v_rsq_f32_e32 v11, v11
	v_cvt_f32_f16_e32 v12, v15
	v_add_u32_e32 v15, v8, v128
	v_mul_f32_e32 v13, 0x45800000, v11
	v_cndmask_b32_e64 v11, v11, v13, s[0:1]
	v_mul_f32_e32 v12, v11, v12
	s_waitcnt vmcnt(0)
	v_mul_f32_e32 v12, v162, v12
	v_cvt_pk_bf16_f32 v12, v12, v129
	v_mul_f32_e32 v9, v11, v9
	ds_write_b16 v15, v12
	v_cmp_gt_f32_e64 s[0:1], s26, v10
	s_waitcnt vmcnt(0)
	v_mul_f32_e32 v9, v163, v9
	v_cvt_pk_bf16_f32 v9, v9, v129
	v_cvt_f32_f16_e32 v13, v14
	ds_write_b16 v15, v9 offset:128
	v_mul_f32_e32 v11, v11, v13
	s_waitcnt vmcnt(0)
	v_mul_f32_e32 v9, v11, v164
	v_cvt_pk_bf16_f32 v9, v9, v129
	v_mul_f32_e32 v12, 0x4b800000, v10
	v_cndmask_b32_e64 v10, v10, v12, s[0:1]
	v_rsq_f32_e32 v10, v10
	v_cvt_f32_f16_e32 v12, v16
	ds_write_b16 v15, v9 offset:256
	v_mul_f32_e32 v13, 0x45800000, v10
	v_cndmask_b32_e64 v10, v10, v13, s[0:1]
	v_mul_f32_e32 v12, v10, v12
	s_waitcnt vmcnt(0)
	v_mul_f32_e32 v9, v165, v12
	v_cvt_pk_bf16_f32 v9, v9, v129
	v_add_u32_e32 v12, v7, v128
	ds_write_b16 v12, v9
	v_mul_f32_e32 v9, v10, v18
	s_waitcnt vmcnt(0)
	v_mul_f32_e32 v9, v9, v166
	v_cvt_pk_bf16_f32 v9, v9, v129
	ds_write_b16 v12, v9 offset:128
	s_and_saveexec_b64 s[0:1], vcc
	s_cbranch_execz .LBB0_781
	v_add_u32_e32 v9, s38, v6
	s_waitcnt vmcnt(0)
	v_cvt_f32_f16_e32 v10, v167
	ds_write_b32 v9, v10
	s_branch .LBB0_781

; DEVI void prepMLA_tile(const Params& p, int l, int g, int tile, char* lds) {
;     ...
;       const u16* Wt = (const u16*)(p.ws + OFF_WUQ) + ((size_t)l * 576 + h * 96) * 192;
; #pragma unroll 1
;       for (int mh = 0; mh < 2; ++mh) {
;       f32x4 acc[2][6];
; #pragma unroll
;       for (int mb = 0; mb < 2; ++mb)
; #pragma unroll
;         for (int nb = 0; nb < 6; ++nb) acc[mb][nb] = (f32x4){0.f, 0.f, 0.f, 0.f};
; #pragma unroll 1
;       for (int ks = 0; ks < 6; ++ks) {
;         bf16x8 bfr[6];
; #pragma unroll
;         for (int nb = 0; nb < 6; ++nb) bfr[nb] = *(const bf16x8*)(Wt + (size_t)(nb * 16 + l15) * 192 + ks * 32 + l4 * 8);
; #pragma unroll
;         for (int mb = 0; mb < 2; ++mb) {
;           bf16x8 a = *(const bf16x8*)(Aq + ((mh * 2 + mb) * 16 + l15) * RSQ + ks * 64 + l4 * 16);
; #pragma unroll
;           for (int nb = 0; nb < 6; ++nb) acc[mb][nb] = __builtin_amdgcn_mfma_f32_16x16x32_bf16(a, bfr[nb], acc[mb][nb], 0, 0, 0);
;         }
;       }
.LBB0_786:
	s_xor_b64 s[38:39], s[40:41], -1
	v_or_b32_e32 v0, s17, v48
	s_movk_i32 s40, 0x190
	v_mov_b32_e32 v24, 0
	v_mad_u32_u24 v92, v0, s40, v104
	s_mov_b64 s[40:41], 0
	v_mov_b32_e32 v25, v24
	v_mov_b32_e32 v26, v24
	v_mov_b32_e32 v27, v24
	v_mov_b32_e32 v28, v24
	v_mov_b32_e32 v29, v24
	v_mov_b32_e32 v30, v24
	v_mov_b32_e32 v31, v24
	v_mov_b32_e32 v32, v24
	v_mov_b32_e32 v33, v24
	v_mov_b32_e32 v34, v24
	v_mov_b32_e32 v35, v24
	v_mov_b32_e32 v36, v24
	v_mov_b32_e32 v37, v24
	v_mov_b32_e32 v38, v24
	v_mov_b32_e32 v39, v24
	v_mov_b32_e32 v40, v24
	v_mov_b32_e32 v41, v24
	v_mov_b32_e32 v42, v24
	v_mov_b32_e32 v43, v24
	v_mov_b32_e32 v44, v24
	v_mov_b32_e32 v45, v24
	v_mov_b32_e32 v46, v24
	v_mov_b32_e32 v47, v24
	v_mov_b32_e32 v0, v24
	v_mov_b32_e32 v1, v24
	v_mov_b32_e32 v2, v24
	v_mov_b32_e32 v3, v24
	v_mov_b32_e32 v4, v24
	v_mov_b32_e32 v5, v24
	v_mov_b32_e32 v6, v24
	v_mov_b32_e32 v7, v24
	v_mov_b32_e32 v8, v24
	v_mov_b32_e32 v9, v24
	v_mov_b32_e32 v10, v24
	v_mov_b32_e32 v11, v24
	v_mov_b32_e32 v12, v24
	v_mov_b32_e32 v13, v24
	v_mov_b32_e32 v14, v24
	v_mov_b32_e32 v15, v24
	v_mov_b32_e32 v16, v24
	v_mov_b32_e32 v17, v24
	v_mov_b32_e32 v18, v24
	v_mov_b32_e32 v19, v24
	v_mov_b32_e32 v20, v24
	v_mov_b32_e32 v21, v24
	v_mov_b32_e32 v22, v24
	v_mov_b32_e32 v23, v24
	v_add_co_u32_e32 v238, vcc, 0x2200000, v88
	s_nop 1
	v_addc_co_u32_e32 v239, vcc, 0, v89, vcc
	v_add_co_u32_e32 v240, vcc, 0x2201000, v88
	s_nop 1
	v_addc_co_u32_e32 v241, vcc, 0, v89, vcc
	v_add_co_u32_e32 v242, vcc, 0x2203000, v88
	s_nop 1
	v_addc_co_u32_e32 v243, vcc, 0, v89, vcc
	v_add_co_u32_e32 v244, vcc, 0x2204000, v88
	s_nop 1
	v_addc_co_u32_e32 v245, vcc, 0, v89, vcc
	v_add_co_u32_e32 v246, vcc, 0x2206000, v88
	s_nop 1
	v_addc_co_u32_e32 v247, vcc, 0, v89, vcc
	global_load_dwordx4 v[162:165], v[238:239], off
	global_load_dwordx4 v[166:169], v[240:241], off offset:2048
	global_load_dwordx4 v[170:173], v[242:243], off
	global_load_dwordx4 v[174:177], v[244:245], off offset:2048
	global_load_dwordx4 v[178:181], v[246:247], off
	global_load_dwordx4 v[182:185], v[90:91], off
	global_load_dwordx4 v[186:189], v[238:239], off offset:64
	global_load_dwordx4 v[190:193], v[240:241], off offset:2112
	global_load_dwordx4 v[194:197], v[242:243], off offset:64
	global_load_dwordx4 v[198:201], v[244:245], off offset:2112
	global_load_dwordx4 v[202:205], v[246:247], off offset:64
	global_load_dwordx4 v[206:209], v[90:91], off offset:64
	global_load_dwordx4 v[210:213], v[238:239], off offset:128
	global_load_dwordx4 v[214:217], v[240:241], off offset:2176
	global_load_dwordx4 v[222:225], v[242:243], off offset:128
	global_load_dwordx4 v[226:229], v[244:245], off offset:2176
	global_load_dwordx4 v[230:233], v[246:247], off offset:128
	global_load_dwordx4 v[234:237], v[90:91], off offset:128
	ds_read_b128 v[158:161], v92
	ds_read_b128 v[248:251], v92 offset:6400
	s_waitcnt vmcnt(12) lgkmcnt(1)
	v_mfma_f32_16x16x32_bf16 v[24:27], v[158:161], v[162:165], v[24:27]
	v_mfma_f32_16x16x32_bf16 v[28:31], v[158:161], v[166:169], v[28:31]
	v_mfma_f32_16x16x32_bf16 v[32:35], v[158:161], v[170:173], v[32:35]
	v_mfma_f32_16x16x32_bf16 v[36:39], v[158:161], v[174:177], v[36:39]
	v_mfma_f32_16x16x32_bf16 v[40:43], v[158:161], v[178:181], v[40:43]
	v_mfma_f32_16x16x32_bf16 v[44:47], v[158:161], v[182:185], v[44:47]
	s_waitcnt lgkmcnt(0)
	v_mfma_f32_16x16x32_bf16 v[0:3], v[248:251], v[162:165], v[0:3]
	v_mfma_f32_16x16x32_bf16 v[4:7], v[248:251], v[166:169], v[4:7]
	v_mfma_f32_16x16x32_bf16 v[8:11], v[248:251], v[170:173], v[8:11]
	v_mfma_f32_16x16x32_bf16 v[12:15], v[248:251], v[174:177], v[12:15]
	v_mfma_f32_16x16x32_bf16 v[16:19], v[248:251], v[178:181], v[16:19]
	v_mfma_f32_16x16x32_bf16 v[20:23], v[248:251], v[182:185], v[20:23]
	global_load_dwordx4 v[162:165], v[238:239], off offset:192
	global_load_dwordx4 v[166:169], v[240:241], off offset:2240
	global_load_dwordx4 v[170:173], v[242:243], off offset:192
	global_load_dwordx4 v[174:177], v[244:245], off offset:2240
	global_load_dwordx4 v[178:181], v[246:247], off offset:192
	global_load_dwordx4 v[182:185], v[90:91], off offset:192
	ds_read_b128 v[158:161], v92 offset:64
	ds_read_b128 v[248:251], v92 offset:6464
	s_waitcnt vmcnt(12) lgkmcnt(1)
	v_mfma_f32_16x16x32_bf16 v[24:27], v[158:161], v[186:189], v[24:27]
	v_mfma_f32_16x16x32_bf16 v[28:31], v[158:161], v[190:193], v[28:31]
	v_mfma_f32_16x16x32_bf16 v[32:35], v[158:161], v[194:197], v[32:35]
	v_mfma_f32_16x16x32_bf16 v[36:39], v[158:161], v[198:201], v[36:39]
	v_mfma_f32_16x16x32_bf16 v[40:43], v[158:161], v[202:205], v[40:43]
	v_mfma_f32_16x16x32_bf16 v[44:47], v[158:161], v[206:209], v[44:47]
	s_waitcnt lgkmcnt(0)
	v_mfma_f32_16x16x32_bf16 v[0:3], v[248:251], v[186:189], v[0:3]
	v_mfma_f32_16x16x32_bf16 v[4:7], v[248:251], v[190:193], v[4:7]
	v_mfma_f32_16x16x32_bf16 v[8:11], v[248:251], v[194:197], v[8:11]
	v_mfma_f32_16x16x32_bf16 v[12:15], v[248:251], v[198:201], v[12:15]
	v_mfma_f32_16x16x32_bf16 v[16:19], v[248:251], v[202:205], v[16:19]
	v_mfma_f32_16x16x32_bf16 v[20:23], v[248:251], v[206:209], v[20:23]
	global_load_dwordx4 v[186:189], v[238:239], off offset:256
	global_load_dwordx4 v[190:193], v[240:241], off offset:2304
	global_load_dwordx4 v[194:197], v[242:243], off offset:256
	global_load_dwordx4 v[198:201], v[244:245], off offset:2304
	global_load_dwordx4 v[202:205], v[246:247], off offset:256
	global_load_dwordx4 v[206:209], v[90:91], off offset:256
	ds_read_b128 v[158:161], v92 offset:128
	ds_read_b128 v[248:251], v92 offset:6528
	s_waitcnt vmcnt(12) lgkmcnt(1)
; DEVI void prepMLA_tile(const Params& p, int l, int g, int tile, char* lds) {
;     ...
;       for (int ks = 0; ks < 6; ++ks) {
;         bf16x8 bfr[6];
; #pragma unroll
;         for (int nb = 0; nb < 6; ++nb) bfr[nb] = *(const bf16x8*)(Wt + (size_t)(nb * 16 + l15) * 192 + ks * 32 + l4 * 8);
; #pragma unroll
;         for (int mb = 0; mb < 2; ++mb) {
;           bf16x8 a = *(const bf16x8*)(Aq + ((mh * 2 + mb) * 16 + l15) * RSQ + ks * 64 + l4 * 16);
; #pragma unroll
;           for (int nb = 0; nb < 6; ++nb) acc[mb][nb] = __builtin_amdgcn_mfma_f32_16x16x32_bf16(a, bfr[nb], acc[mb][nb], 0, 0, 0);
;         }
;       }
;       const float* nw = p.qk_q_norm_w + l * 96;
;       float wv[6];
; #pragma unroll
;       for (int nb = 0; nb < 6; ++nb) wv[nb] = nw[nb * 16 + l15];
;       u16* Q = (u16*)(p.ws + OFF_Q) + ((size_t)s0 * 6 + (size_t)h * len + pos0) * 96;
; #pragma unroll
;       for (int mb = 0; mb < 2; ++mb)
; #pragma unroll
;         for (int j = 0; j < 4; ++j) {
;           int rowi = (mh * 2 + mb) * 16 + l4 * 4 + j;
;           float ss = 0.f;
; #pragma unroll
;           for (int nb = 0; nb < 6; ++nb) ss += acc[mb][nb][j] * acc[mb][nb][j];
;           ss = rowreduce<16>(ss);
;           float rstd = rsqrtf(ss * (1.f / 96.f) + 1e-6f);
;           float x[6];
; #pragma unroll
;           for (int nb = 0; nb < 6; ++nb) x[nb] = acc[mb][nb][j] * (rstd * 0.14724445f) * wv[nb];
	v_mfma_f32_16x16x32_bf16 v[24:27], v[158:161], v[210:213], v[24:27]
	v_mfma_f32_16x16x32_bf16 v[28:31], v[158:161], v[214:217], v[28:31]
	v_mfma_f32_16x16x32_bf16 v[32:35], v[158:161], v[222:225], v[32:35]
	v_mfma_f32_16x16x32_bf16 v[36:39], v[158:161], v[226:229], v[36:39]
	v_mfma_f32_16x16x32_bf16 v[40:43], v[158:161], v[230:233], v[40:43]
	v_mfma_f32_16x16x32_bf16 v[44:47], v[158:161], v[234:237], v[44:47]
	s_waitcnt lgkmcnt(0)
	v_mfma_f32_16x16x32_bf16 v[0:3], v[248:251], v[210:213], v[0:3]
	v_mfma_f32_16x16x32_bf16 v[4:7], v[248:251], v[214:217], v[4:7]
	v_mfma_f32_16x16x32_bf16 v[8:11], v[248:251], v[222:225], v[8:11]
	v_mfma_f32_16x16x32_bf16 v[12:15], v[248:251], v[226:229], v[12:15]
	v_mfma_f32_16x16x32_bf16 v[16:19], v[248:251], v[230:233], v[16:19]
	v_mfma_f32_16x16x32_bf16 v[20:23], v[248:251], v[234:237], v[20:23]
	global_load_dwordx4 v[210:213], v[238:239], off offset:320
	global_load_dwordx4 v[214:217], v[240:241], off offset:2368
	global_load_dwordx4 v[222:225], v[242:243], off offset:320
	global_load_dwordx4 v[226:229], v[244:245], off offset:2368
	global_load_dwordx4 v[230:233], v[246:247], off offset:320
	global_load_dwordx4 v[234:237], v[90:91], off offset:320
	ds_read_b128 v[158:161], v92 offset:192
	ds_read_b128 v[248:251], v92 offset:6592
	s_waitcnt vmcnt(12) lgkmcnt(1)
	v_mfma_f32_16x16x32_bf16 v[24:27], v[158:161], v[162:165], v[24:27]
	v_mfma_f32_16x16x32_bf16 v[28:31], v[158:161], v[166:169], v[28:31]
	v_mfma_f32_16x16x32_bf16 v[32:35], v[158:161], v[170:173], v[32:35]
	v_mfma_f32_16x16x32_bf16 v[36:39], v[158:161], v[174:177], v[36:39]
	v_mfma_f32_16x16x32_bf16 v[40:43], v[158:161], v[178:181], v[40:43]
	v_mfma_f32_16x16x32_bf16 v[44:47], v[158:161], v[182:185], v[44:47]
	s_waitcnt lgkmcnt(0)
	v_mfma_f32_16x16x32_bf16 v[0:3], v[248:251], v[162:165], v[0:3]
	v_mfma_f32_16x16x32_bf16 v[4:7], v[248:251], v[166:169], v[4:7]
	v_mfma_f32_16x16x32_bf16 v[8:11], v[248:251], v[170:173], v[8:11]
	v_mfma_f32_16x16x32_bf16 v[12:15], v[248:251], v[174:177], v[12:15]
	v_mfma_f32_16x16x32_bf16 v[16:19], v[248:251], v[178:181], v[16:19]
	v_mfma_f32_16x16x32_bf16 v[20:23], v[248:251], v[182:185], v[20:23]
	ds_read_b128 v[158:161], v92 offset:256
	ds_read_b128 v[248:251], v92 offset:6656
	s_waitcnt vmcnt(6) lgkmcnt(1)
	v_mfma_f32_16x16x32_bf16 v[24:27], v[158:161], v[186:189], v[24:27]
	v_mfma_f32_16x16x32_bf16 v[28:31], v[158:161], v[190:193], v[28:31]
	v_mfma_f32_16x16x32_bf16 v[32:35], v[158:161], v[194:197], v[32:35]
	v_mfma_f32_16x16x32_bf16 v[36:39], v[158:161], v[198:201], v[36:39]
	v_mfma_f32_16x16x32_bf16 v[40:43], v[158:161], v[202:205], v[40:43]
	v_mfma_f32_16x16x32_bf16 v[44:47], v[158:161], v[206:209], v[44:47]
	s_waitcnt lgkmcnt(0)
	v_mfma_f32_16x16x32_bf16 v[0:3], v[248:251], v[186:189], v[0:3]
	v_mfma_f32_16x16x32_bf16 v[4:7], v[248:251], v[190:193], v[4:7]
	v_mfma_f32_16x16x32_bf16 v[8:11], v[248:251], v[194:197], v[8:11]
	v_mfma_f32_16x16x32_bf16 v[12:15], v[248:251], v[198:201], v[12:15]
	v_mfma_f32_16x16x32_bf16 v[16:19], v[248:251], v[202:205], v[16:19]
	v_mfma_f32_16x16x32_bf16 v[20:23], v[248:251], v[206:209], v[20:23]
	ds_read_b128 v[158:161], v92 offset:320
	ds_read_b128 v[248:251], v92 offset:6720
	s_waitcnt vmcnt(0) lgkmcnt(1)
	v_mfma_f32_16x16x32_bf16 v[24:27], v[158:161], v[210:213], v[24:27]
	v_mfma_f32_16x16x32_bf16 v[28:31], v[158:161], v[214:217], v[28:31]
	v_mfma_f32_16x16x32_bf16 v[32:35], v[158:161], v[222:225], v[32:35]
	v_mfma_f32_16x16x32_bf16 v[36:39], v[158:161], v[226:229], v[36:39]
	v_mfma_f32_16x16x32_bf16 v[40:43], v[158:161], v[230:233], v[40:43]
	v_mfma_f32_16x16x32_bf16 v[44:47], v[158:161], v[234:237], v[44:47]
	s_waitcnt lgkmcnt(0)
	v_mfma_f32_16x16x32_bf16 v[0:3], v[248:251], v[210:213], v[0:3]
	v_mfma_f32_16x16x32_bf16 v[4:7], v[248:251], v[214:217], v[4:7]
	v_mfma_f32_16x16x32_bf16 v[8:11], v[248:251], v[222:225], v[8:11]
	v_mfma_f32_16x16x32_bf16 v[12:15], v[248:251], v[226:229], v[12:15]
	v_mfma_f32_16x16x32_bf16 v[16:19], v[248:251], v[230:233], v[16:19]
	v_mfma_f32_16x16x32_bf16 v[20:23], v[248:251], v[234:237], v[20:23]
	v_mov_b32_e32 v112, v24
	v_mov_b32_e32 v113, v28
	v_pk_mul_f32 v[112:113], v[112:113], v[112:113]
	v_mov_b32_e32 v114, v32
	v_mov_b32_e32 v115, v36
	v_pk_mul_f32 v[114:115], v[114:115], v[114:115]
	v_add_f32_e32 v93, v112, v113
	v_mov_b32_e32 v116, v40
	v_mov_b32_e32 v117, v44
	v_add_f32_e32 v93, v93, v114
	v_pk_mul_f32 v[116:117], v[116:117], v[116:117]
	v_add_f32_e32 v93, v93, v115
	v_add_f32_e32 v93, v93, v116
	v_add_f32_e32 v93, v93, v117
	v_or_b32_e32 v92, s17, v53
	global_load_dword v111, v[74:75], off
	global_load_dword v110, v[74:75], off offset:64
	global_load_dword v109, v[74:75], off offset:128
	global_load_dword v108, v[74:75], off offset:192
	global_load_dword v107, v[74:75], off offset:256
	global_load_dword v106, v[74:75], off offset:320
	v_add_f32_dpp v93, v93, v93 quad_perm:[1,0,3,2] row_mask:0xf bank_mask:0xf bound_ctrl:1
	s_mov_b64 s[40:41], 0
	s_nop 0
	v_add_f32_dpp v93, v93, v93 quad_perm:[2,3,0,1] row_mask:0xf bank_mask:0xf bound_ctrl:1
	s_nop 1
	v_add_f32_dpp v93, v93, v93 row_half_mirror row_mask:0xf bank_mask:0xf bound_ctrl:1
	s_nop 1
	v_add_f32_dpp v93, v93, v93 row_mirror row_mask:0xf bank_mask:0xf bound_ctrl:1
	v_fmamk_f32 v93, v93, 0x3c2aaaab, v130
	v_cmp_gt_f32_e32 vcc, s26, v93
	v_mul_f32_e32 v112, 0x4b800000, v93
	s_nop 0
	v_cndmask_b32_e32 v93, v93, v112, vcc
	v_rsq_f32_e32 v93, v93
	s_nop 0
	v_mul_f32_e32 v112, 0x45800000, v93
	v_cndmask_b32_e32 v93, v93, v112, vcc
	v_mul_f32_e32 v93, 0x3e16c740, v93
	v_mul_f32_e32 v24, v24, v93
	v_mul_f32_e32 v28, v28, v93
	v_mul_f32_e32 v32, v32, v93
	v_mul_f32_e32 v36, v36, v93
; DEVI u16 f2bf(float f) { return (u16)(cvtpk(f, 0.f) & 0xffffu); }
; DEVI void prepMLA_tile(const Params& p, int l, int g, int tile, char* lds) {
;     ...
;           int rowi = (mh * 2 + mb) * 16 + l4 * 4 + j;
;           float ss = 0.f;
; #pragma unroll
;           for (int nb = 0; nb < 6; ++nb) ss += acc[mb][nb][j] * acc[mb][nb][j];
;           ss = rowreduce<16>(ss);
;           float rstd = rsqrtf(ss * (1.f / 96.f) + 1e-6f);
;           float x[6];
; #pragma unroll
;           for (int nb = 0; nb < 6; ++nb) x[nb] = acc[mb][nb][j] * (rstd * 0.14724445f) * wv[nb];
;           const float* cs = rope + ((size_t)(pos0 + rowi) * 16 + l15) * 2;
;           float c = cs[0], s = cs[1];
;           float y1 = x[4] * c - x[5] * s, y2 = x[5] * c + x[4] * s;
;           x[4] = y1; x[5] = y2;
;           u16* qs = (u16*)(WS + (mb * 16 + l4 * 4 + j) * 208) + l15;
; #pragma unroll
;           for (int nb = 0; nb < 6; ++nb) qs[nb * 16] = f2bf(x[nb]);
	v_mul_f32_e32 v40, v40, v93
	v_mul_f32_e32 v44, v44, v93
	v_ashrrev_i32_e32 v93, 31, v92
	v_lshlrev_b64 v[112:113], 7, v[92:93]
	v_lshl_add_u64 v[112:113], v[50:51], 0, v[112:113]
	global_load_dwordx2 v[112:113], v[112:113], off
	v_or_b32_e32 v176, 1, v92
	v_ashrrev_i32_e32 v177, 31, v176
	v_lshlrev_b64 v[176:177], 7, v[176:177]
	v_lshl_add_u64 v[176:177], v[50:51], 0, v[176:177]
	global_load_dwordx2 v[162:163], v[176:177], off
	v_or_b32_e32 v176, 2, v92
	v_ashrrev_i32_e32 v177, 31, v176
	v_lshlrev_b64 v[176:177], 7, v[176:177]
	v_lshl_add_u64 v[176:177], v[50:51], 0, v[176:177]
	global_load_dwordx2 v[164:165], v[176:177], off
	v_or_b32_e32 v176, 3, v92
	v_ashrrev_i32_e32 v177, 31, v176
	v_lshlrev_b64 v[176:177], 7, v[176:177]
	v_lshl_add_u64 v[176:177], v[50:51], 0, v[176:177]
	global_load_dwordx2 v[166:167], v[176:177], off
	v_or_b32_e32 v176, 16, v92
	v_ashrrev_i32_e32 v177, 31, v176
	v_lshlrev_b64 v[176:177], 7, v[176:177]
	v_lshl_add_u64 v[176:177], v[50:51], 0, v[176:177]
	global_load_dwordx2 v[168:169], v[176:177], off
	v_or_b32_e32 v176, 17, v92
	v_ashrrev_i32_e32 v177, 31, v176
	v_lshlrev_b64 v[176:177], 7, v[176:177]
	v_lshl_add_u64 v[176:177], v[50:51], 0, v[176:177]
	global_load_dwordx2 v[170:171], v[176:177], off
	v_or_b32_e32 v176, 18, v92
	v_ashrrev_i32_e32 v177, 31, v176
	v_lshlrev_b64 v[176:177], 7, v[176:177]
	v_lshl_add_u64 v[176:177], v[50:51], 0, v[176:177]
	global_load_dwordx2 v[172:173], v[176:177], off
	v_or_b32_e32 v176, 19, v92
	v_ashrrev_i32_e32 v177, 31, v176
	v_lshlrev_b64 v[176:177], 7, v[176:177]
	v_lshl_add_u64 v[176:177], v[50:51], 0, v[176:177]
	global_load_dwordx2 v[174:175], v[176:177], off
	s_waitcnt vmcnt(6)
	v_mul_f32_e32 v24, v111, v24
	v_cvt_pk_bf16_f32 v24, v24, v129
	s_waitcnt vmcnt(5)
	v_mul_f32_e32 v28, v110, v28
	ds_write_b16 v63, v24 offset:51200
	v_cvt_pk_bf16_f32 v24, v28, v129
	s_waitcnt vmcnt(4)
	v_mul_f32_e32 v32, v109, v32
	s_waitcnt vmcnt(1)
	v_mul_f32_e32 v44, v106, v44
	ds_write_b16 v63, v24 offset:51232
	v_cvt_pk_bf16_f32 v24, v32, v129
	v_mul_f32_e32 v36, v108, v36
	v_mul_f32_e32 v40, v107, v40
	ds_write_b16 v63, v24 offset:51264
	v_cvt_pk_bf16_f32 v24, v36, v129
	ds_write_b16 v63, v24 offset:51296
	v_mov_b32_e32 v28, v25
	v_mov_b32_e32 v36, v33
	v_pk_mul_f32 v[114:115], v[36:37], v[36:37]
	s_waitcnt vmcnt(0)
	v_mul_f32_e32 v93, v113, v44
	v_fma_f32 v93, v112, v40, -v93
	v_mul_f32_e32 v40, v113, v40
	v_cvt_pk_bf16_f32 v24, v93, v129
	v_fmac_f32_e32 v40, v112, v44
	ds_write_b16 v63, v24 offset:51328
	v_cvt_pk_bf16_f32 v24, v40, v129
	v_pk_mul_f32 v[112:113], v[28:29], v[28:29]
	ds_write_b16 v63, v24 offset:51360
	v_add_f32_e32 v24, v112, v113
	v_mov_b32_e32 v44, v41
	v_add_f32_e32 v24, v24, v114
	v_pk_mul_f32 v[116:117], v[44:45], v[44:45]
	v_add_f32_e32 v24, v24, v115
	v_add_f32_e32 v24, v24, v116
	v_add_f32_e32 v24, v24, v117
	s_nop 1
	v_add_f32_dpp v24, v24, v24 quad_perm:[1,0,3,2] row_mask:0xf bank_mask:0xf bound_ctrl:1
	s_nop 1
	v_add_f32_dpp v24, v24, v24 quad_perm:[2,3,0,1] row_mask:0xf bank_mask:0xf bound_ctrl:1
	s_nop 1
	v_add_f32_dpp v24, v24, v24 row_half_mirror row_mask:0xf bank_mask:0xf bound_ctrl:1
	s_nop 1
	v_add_f32_dpp v24, v24, v24 row_mirror row_mask:0xf bank_mask:0xf bound_ctrl:1
	v_fmamk_f32 v24, v24, 0x3c2aaaab, v130
	v_cmp_gt_f32_e32 vcc, s26, v24
	v_mul_f32_e32 v28, 0x4b800000, v24
	s_nop 0
	v_cndmask_b32_e32 v24, v24, v28, vcc
	v_rsq_f32_e32 v24, v24
	s_nop 0
	v_mul_f32_e32 v28, 0x45800000, v24
	v_cndmask_b32_e32 v24, v24, v28, vcc
	v_mul_f32_e32 v24, 0x3e16c740, v24
	v_mul_f32_e32 v25, v25, v24
	v_mul_f32_e32 v28, v111, v25
	v_mul_f32_e32 v25, v29, v24
	v_mul_f32_e32 v29, v110, v25
	v_mul_f32_e32 v25, v33, v24
	v_mul_f32_e32 v32, v109, v25
	v_mul_f32_e32 v25, v37, v24
	v_mul_f32_e32 v33, v108, v25
	v_mul_f32_e32 v25, v41, v24
	v_mul_f32_e32 v24, v45, v24
	v_mul_f32_e32 v37, v106, v24
	v_or_b32_e32 v24, 1, v92
	v_mul_f32_e32 v36, v107, v25
	v_ashrrev_i32_e32 v25, 31, v24
	v_lshlrev_b64 v[24:25], 7, v[24:25]
	v_lshl_add_u64 v[24:25], v[50:51], 0, v[24:25]
	v_mov_b32_e32 v24, v162
	v_mov_b32_e32 v25, v163
	s_waitcnt vmcnt(0)
	v_mul_f32_e32 v40, v25, v37
	v_mul_f32_e32 v25, v25, v36
	v_fma_f32 v40, v24, v36, -v40
	v_fmac_f32_e32 v25, v24, v37
	v_cvt_pk_bf16_f32 v24, v28, v129
	ds_write_b16 v63, v24 offset:51408
	v_cvt_pk_bf16_f32 v24, v29, v129
	ds_write_b16 v63, v24 offset:51440
	v_cvt_pk_bf16_f32 v24, v32, v129
	ds_write_b16 v63, v24 offset:51472
	v_cvt_pk_bf16_f32 v24, v33, v129
	ds_write_b16 v63, v24 offset:51504
	v_cvt_pk_bf16_f32 v24, v40, v129
	ds_write_b16 v63, v24 offset:51536
	v_cvt_pk_bf16_f32 v24, v25, v129
	ds_write_b16 v63, v24 offset:51568
	v_mov_b32_e32 v24, v26
	v_mov_b32_e32 v25, v30
	v_pk_mul_f32 v[24:25], v[24:25], v[24:25]
	v_mov_b32_e32 v28, v34
	v_mov_b32_e32 v29, v38
	v_pk_mul_f32 v[28:29], v[28:29], v[28:29]
	v_add_f32_e32 v24, v24, v25
	v_mov_b32_e32 v32, v42
	v_mov_b32_e32 v33, v46
	v_add_f32_e32 v24, v24, v28
	v_pk_mul_f32 v[32:33], v[32:33], v[32:33]
	v_add_f32_e32 v24, v24, v29
	v_add_f32_e32 v24, v24, v32
	v_add_f32_e32 v24, v24, v33
	s_nop 1
	v_add_f32_dpp v24, v24, v24 quad_perm:[1,0,3,2] row_mask:0xf bank_mask:0xf bound_ctrl:1
	s_nop 1
	v_add_f32_dpp v24, v24, v24 quad_perm:[2,3,0,1] row_mask:0xf bank_mask:0xf bound_ctrl:1
	s_nop 1
	v_add_f32_dpp v24, v24, v24 row_half_mirror row_mask:0xf bank_mask:0xf bound_ctrl:1
	s_nop 1
	v_add_f32_dpp v24, v24, v24 row_mirror row_mask:0xf bank_mask:0xf bound_ctrl:1
	v_fmamk_f32 v24, v24, 0x3c2aaaab, v130
	v_cmp_gt_f32_e32 vcc, s26, v24
	v_mul_f32_e32 v25, 0x4b800000, v24
	s_nop 0
	v_cndmask_b32_e32 v24, v24, v25, vcc
	v_rsq_f32_e32 v24, v24
	s_nop 0
	v_mul_f32_e32 v25, 0x45800000, v24
	v_cndmask_b32_e32 v24, v24, v25, vcc
	v_mul_f32_e32 v24, 0x3e16c740, v24
	v_mul_f32_e32 v25, v26, v24
	v_mul_f32_e32 v26, v111, v25
	v_mul_f32_e32 v25, v30, v24
	v_mul_f32_e32 v28, v110, v25
	v_mul_f32_e32 v25, v34, v24
	v_mul_f32_e32 v29, v109, v25
	v_mul_f32_e32 v25, v38, v24
	v_mul_f32_e32 v30, v108, v25
	v_mul_f32_e32 v25, v42, v24
	v_mul_f32_e32 v24, v46, v24
	v_mul_f32_e32 v33, v106, v24
	v_or_b32_e32 v24, 2, v92
	v_mul_f32_e32 v32, v107, v25
	v_ashrrev_i32_e32 v25, 31, v24
	v_lshlrev_b64 v[24:25], 7, v[24:25]
	v_lshl_add_u64 v[24:25], v[50:51], 0, v[24:25]
	v_mov_b32_e32 v24, v164
	v_mov_b32_e32 v25, v165
	v_mov_b32_e32 v38, v35
	v_mov_b32_e32 v46, v43
	s_waitcnt vmcnt(0)
; DEVI u16 f2bf(float f) { return (u16)(cvtpk(f, 0.f) & 0xffffu); }
; DEVI void prepMLA_tile(const Params& p, int l, int g, int tile, char* lds) {
;     ...
;           int rowi = (mh * 2 + mb) * 16 + l4 * 4 + j;
;           float ss = 0.f;
; #pragma unroll
;           for (int nb = 0; nb < 6; ++nb) ss += acc[mb][nb][j] * acc[mb][nb][j];
;           ss = rowreduce<16>(ss);
;           float rstd = rsqrtf(ss * (1.f / 96.f) + 1e-6f);
;           float x[6];
; #pragma unroll
;           for (int nb = 0; nb < 6; ++nb) x[nb] = acc[mb][nb][j] * (rstd * 0.14724445f) * wv[nb];
;           const float* cs = rope + ((size_t)(pos0 + rowi) * 16 + l15) * 2;
;           float c = cs[0], s = cs[1];
;           float y1 = x[4] * c - x[5] * s, y2 = x[5] * c + x[4] * s;
;           x[4] = y1; x[5] = y2;
;           u16* qs = (u16*)(WS + (mb * 16 + l4 * 4 + j) * 208) + l15;
; #pragma unroll
;           for (int nb = 0; nb < 6; ++nb) qs[nb * 16] = f2bf(x[nb]);
	v_mul_f32_e32 v34, v25, v33
	v_mul_f32_e32 v25, v25, v32
	v_fma_f32 v34, v24, v32, -v34
	v_fmac_f32_e32 v25, v24, v33
	v_cvt_pk_bf16_f32 v24, v26, v129
	ds_write_b16 v63, v24 offset:51616
	v_cvt_pk_bf16_f32 v24, v28, v129
	ds_write_b16 v63, v24 offset:51648
	v_cvt_pk_bf16_f32 v24, v29, v129
	ds_write_b16 v63, v24 offset:51680
	v_cvt_pk_bf16_f32 v24, v30, v129
	ds_write_b16 v63, v24 offset:51712
	v_cvt_pk_bf16_f32 v24, v34, v129
	ds_write_b16 v63, v24 offset:51744
	v_cvt_pk_bf16_f32 v24, v25, v129
	v_mov_b32_e32 v30, v27
	ds_write_b16 v63, v24 offset:51776
	v_pk_mul_f32 v[24:25], v[30:31], v[30:31]
	v_pk_mul_f32 v[28:29], v[38:39], v[38:39]
	v_add_f32_e32 v24, v24, v25
	v_add_f32_e32 v24, v24, v28
	v_pk_mul_f32 v[32:33], v[46:47], v[46:47]
	v_add_f32_e32 v24, v24, v29
	v_add_f32_e32 v24, v24, v32
	v_add_f32_e32 v24, v24, v33
	s_nop 1
	v_add_f32_dpp v24, v24, v24 quad_perm:[1,0,3,2] row_mask:0xf bank_mask:0xf bound_ctrl:1
	s_nop 1
	v_add_f32_dpp v24, v24, v24 quad_perm:[2,3,0,1] row_mask:0xf bank_mask:0xf bound_ctrl:1
	s_nop 1
	v_add_f32_dpp v24, v24, v24 row_half_mirror row_mask:0xf bank_mask:0xf bound_ctrl:1
	s_nop 1
	v_add_f32_dpp v24, v24, v24 row_mirror row_mask:0xf bank_mask:0xf bound_ctrl:1
	v_fmamk_f32 v24, v24, 0x3c2aaaab, v130
	v_cmp_gt_f32_e32 vcc, s26, v24
	v_mul_f32_e32 v25, 0x4b800000, v24
	s_nop 0
	v_cndmask_b32_e32 v24, v24, v25, vcc
	v_rsq_f32_e32 v24, v24
	s_nop 0
	v_mul_f32_e32 v25, 0x45800000, v24
	v_cndmask_b32_e32 v24, v24, v25, vcc
	v_mul_f32_e32 v24, 0x3e16c740, v24
	v_mul_f32_e32 v25, v27, v24
	v_mul_f32_e32 v26, v111, v25
	v_mul_f32_e32 v25, v31, v24
	v_mul_f32_e32 v27, v110, v25
	v_mul_f32_e32 v25, v35, v24
	v_mul_f32_e32 v28, v109, v25
	v_mul_f32_e32 v25, v39, v24
	v_mul_f32_e32 v29, v108, v25
	v_mul_f32_e32 v25, v43, v24
	v_mul_f32_e32 v24, v47, v24
	v_mul_f32_e32 v31, v106, v24
	v_or_b32_e32 v24, 3, v92
	v_mul_f32_e32 v30, v107, v25
	v_ashrrev_i32_e32 v25, 31, v24
	v_lshlrev_b64 v[24:25], 7, v[24:25]
	v_lshl_add_u64 v[24:25], v[50:51], 0, v[24:25]
	v_mov_b32_e32 v24, v166
	v_mov_b32_e32 v25, v167
	s_waitcnt vmcnt(0)
	v_mul_f32_e32 v32, v25, v31
	v_mul_f32_e32 v25, v25, v30
	v_fma_f32 v32, v24, v30, -v32
	v_fmac_f32_e32 v25, v24, v31
	v_cvt_pk_bf16_f32 v24, v26, v129
	ds_write_b16 v63, v24 offset:51824
	v_cvt_pk_bf16_f32 v24, v27, v129
	ds_write_b16 v63, v24 offset:51856
	v_cvt_pk_bf16_f32 v24, v28, v129
	ds_write_b16 v63, v24 offset:51888
	v_cvt_pk_bf16_f32 v24, v29, v129
	v_mov_b32_e32 v26, v0
	v_mov_b32_e32 v27, v4
	ds_write_b16 v63, v24 offset:51920
	v_cvt_pk_bf16_f32 v24, v32, v129
	v_pk_mul_f32 v[26:27], v[26:27], v[26:27]
	v_mov_b32_e32 v28, v8
	v_mov_b32_e32 v29, v12
	ds_write_b16 v63, v24 offset:51952
	v_cvt_pk_bf16_f32 v24, v25, v129
	v_pk_mul_f32 v[28:29], v[28:29], v[28:29]
	v_add_f32_e32 v25, v26, v27
	v_mov_b32_e32 v30, v16
	v_mov_b32_e32 v31, v20
	v_add_f32_e32 v25, v25, v28
	v_pk_mul_f32 v[30:31], v[30:31], v[30:31]
	v_add_f32_e32 v25, v25, v29
	v_add_f32_e32 v25, v25, v30
	v_add_f32_e32 v25, v25, v31
	ds_write_b16 v63, v24 offset:51984
	v_or_b32_e32 v24, 16, v92
	v_add_f32_dpp v25, v25, v25 quad_perm:[1,0,3,2] row_mask:0xf bank_mask:0xf bound_ctrl:1
	s_nop 1
	v_add_f32_dpp v25, v25, v25 quad_perm:[2,3,0,1] row_mask:0xf bank_mask:0xf bound_ctrl:1
	s_nop 1
	v_add_f32_dpp v25, v25, v25 row_half_mirror row_mask:0xf bank_mask:0xf bound_ctrl:1
	s_nop 1
	v_add_f32_dpp v25, v25, v25 row_mirror row_mask:0xf bank_mask:0xf bound_ctrl:1
	v_fmamk_f32 v25, v25, 0x3c2aaaab, v130
	v_cmp_gt_f32_e32 vcc, s26, v25
	v_mul_f32_e32 v26, 0x4b800000, v25
	s_nop 0
	v_cndmask_b32_e32 v25, v25, v26, vcc
	v_rsq_f32_e32 v25, v25
	s_nop 0
	v_mul_f32_e32 v26, 0x45800000, v25
	v_cndmask_b32_e32 v25, v25, v26, vcc
	v_mul_f32_e32 v25, 0x3e16c740, v25
	v_mul_f32_e32 v0, v0, v25
	v_mul_f32_e32 v4, v4, v25
	v_mul_f32_e32 v8, v8, v25
	v_mul_f32_e32 v12, v12, v25
	v_mul_f32_e32 v16, v16, v25
	v_mul_f32_e32 v20, v20, v25
	v_ashrrev_i32_e32 v25, 31, v24
	v_lshlrev_b64 v[24:25], 7, v[24:25]
	v_lshl_add_u64 v[24:25], v[50:51], 0, v[24:25]
	v_mov_b32_e32 v24, v168
	v_mov_b32_e32 v25, v169
	v_mul_f32_e32 v0, v111, v0
	v_cvt_pk_bf16_f32 v0, v0, v129
	v_mul_f32_e32 v4, v110, v4
	ds_write_b16 v63, v0 offset:54528
	v_cvt_pk_bf16_f32 v0, v4, v129
	v_mul_f32_e32 v8, v109, v8
	v_mul_f32_e32 v20, v106, v20
	ds_write_b16 v63, v0 offset:54560
	v_cvt_pk_bf16_f32 v0, v8, v129
	v_mul_f32_e32 v12, v108, v12
	v_mul_f32_e32 v16, v107, v16
	ds_write_b16 v63, v0 offset:54592
	v_cvt_pk_bf16_f32 v0, v12, v129
	ds_write_b16 v63, v0 offset:54624
	v_mov_b32_e32 v4, v1
	v_mov_b32_e32 v12, v9
	s_waitcnt vmcnt(0)
	v_mul_f32_e32 v26, v25, v20
	v_fma_f32 v26, v24, v16, -v26
	v_mul_f32_e32 v16, v25, v16
	v_cvt_pk_bf16_f32 v0, v26, v129
	v_fmac_f32_e32 v16, v24, v20
	ds_write_b16 v63, v0 offset:54656
	v_cvt_pk_bf16_f32 v0, v16, v129
	v_pk_mul_f32 v[24:25], v[4:5], v[4:5]
	ds_write_b16 v63, v0 offset:54688
	v_pk_mul_f32 v[26:27], v[12:13], v[12:13]
	v_add_f32_e32 v0, v24, v25
	v_mov_b32_e32 v20, v17
	v_add_f32_e32 v0, v0, v26
	v_pk_mul_f32 v[28:29], v[20:21], v[20:21]
	v_add_f32_e32 v0, v0, v27
	v_add_f32_e32 v0, v0, v28
	v_add_f32_e32 v0, v0, v29
	s_nop 1
	v_add_f32_dpp v0, v0, v0 quad_perm:[1,0,3,2] row_mask:0xf bank_mask:0xf bound_ctrl:1
	s_nop 1
	v_add_f32_dpp v0, v0, v0 quad_perm:[2,3,0,1] row_mask:0xf bank_mask:0xf bound_ctrl:1
	s_nop 1
	v_add_f32_dpp v0, v0, v0 row_half_mirror row_mask:0xf bank_mask:0xf bound_ctrl:1
	s_nop 1
	v_add_f32_dpp v0, v0, v0 row_mirror row_mask:0xf bank_mask:0xf bound_ctrl:1
	v_fmamk_f32 v0, v0, 0x3c2aaaab, v130
	v_cmp_gt_f32_e32 vcc, s26, v0
	v_mul_f32_e32 v4, 0x4b800000, v0
	s_nop 0
	v_cndmask_b32_e32 v0, v0, v4, vcc
	v_rsq_f32_e32 v0, v0
	s_nop 0
	v_mul_f32_e32 v4, 0x45800000, v0
	v_cndmask_b32_e32 v0, v0, v4, vcc
	v_mul_f32_e32 v0, 0x3e16c740, v0
	v_mul_f32_e32 v1, v1, v0
	v_mul_f32_e32 v4, v111, v1
	v_mul_f32_e32 v1, v5, v0
	v_mul_f32_e32 v5, v110, v1
	v_mul_f32_e32 v1, v9, v0
	v_mul_f32_e32 v8, v109, v1
	v_mul_f32_e32 v1, v13, v0
	v_mul_f32_e32 v9, v108, v1
	v_mul_f32_e32 v1, v17, v0
	v_mul_f32_e32 v0, v21, v0
	v_mul_f32_e32 v13, v106, v0
	v_or_b32_e32 v0, 17, v92
	v_mul_f32_e32 v12, v107, v1
	v_ashrrev_i32_e32 v1, 31, v0
	v_lshlrev_b64 v[0:1], 7, v[0:1]
	v_lshl_add_u64 v[0:1], v[50:51], 0, v[0:1]
	v_mov_b32_e32 v0, v170
	v_mov_b32_e32 v1, v171
	s_waitcnt vmcnt(0)
; DEVI u16 f2bf(float f) { return (u16)(cvtpk(f, 0.f) & 0xffffu); }
; DEVI void prepMLA_tile(const Params& p, int l, int g, int tile, char* lds) {
;     ...
;           int rowi = (mh * 2 + mb) * 16 + l4 * 4 + j;
;           float ss = 0.f;
; #pragma unroll
;           for (int nb = 0; nb < 6; ++nb) ss += acc[mb][nb][j] * acc[mb][nb][j];
;           ss = rowreduce<16>(ss);
;           float rstd = rsqrtf(ss * (1.f / 96.f) + 1e-6f);
;           float x[6];
; #pragma unroll
;           for (int nb = 0; nb < 6; ++nb) x[nb] = acc[mb][nb][j] * (rstd * 0.14724445f) * wv[nb];
;           const float* cs = rope + ((size_t)(pos0 + rowi) * 16 + l15) * 2;
;           float c = cs[0], s = cs[1];
;           float y1 = x[4] * c - x[5] * s, y2 = x[5] * c + x[4] * s;
;           x[4] = y1; x[5] = y2;
;           u16* qs = (u16*)(WS + (mb * 16 + l4 * 4 + j) * 208) + l15;
; #pragma unroll
;           for (int nb = 0; nb < 6; ++nb) qs[nb * 16] = f2bf(x[nb]);
;         }
; #pragma unroll
;       for (int i = 0; i < 6; ++i) {
;         int c = lane + i * 64; int rr_ = c / 12, ch = c % 12;
;         *(u32x4*)(Q + (size_t)(mh * 32 + rr_) * 96 + ch * 8) = *(const u32x4*)(WS + rr_ * 208 + ch * 16);
;       }
	v_mul_f32_e32 v16, v1, v13
	v_mul_f32_e32 v1, v1, v12
	v_fma_f32 v16, v0, v12, -v16
	v_fmac_f32_e32 v1, v0, v13
	v_cvt_pk_bf16_f32 v0, v4, v129
	ds_write_b16 v63, v0 offset:54736
	v_cvt_pk_bf16_f32 v0, v5, v129
	ds_write_b16 v63, v0 offset:54768
	v_cvt_pk_bf16_f32 v0, v8, v129
	ds_write_b16 v63, v0 offset:54800
	v_cvt_pk_bf16_f32 v0, v9, v129
	ds_write_b16 v63, v0 offset:54832
	v_cvt_pk_bf16_f32 v0, v16, v129
	ds_write_b16 v63, v0 offset:54864
	v_cvt_pk_bf16_f32 v0, v1, v129
	ds_write_b16 v63, v0 offset:54896
	v_mov_b32_e32 v0, v2
	v_mov_b32_e32 v1, v6
	v_pk_mul_f32 v[0:1], v[0:1], v[0:1]
	v_mov_b32_e32 v4, v10
	v_mov_b32_e32 v5, v14
	v_pk_mul_f32 v[4:5], v[4:5], v[4:5]
	v_add_f32_e32 v0, v0, v1
	v_mov_b32_e32 v8, v18
	v_mov_b32_e32 v9, v22
	v_add_f32_e32 v0, v0, v4
	v_pk_mul_f32 v[8:9], v[8:9], v[8:9]
	v_add_f32_e32 v0, v0, v5
	v_add_f32_e32 v0, v0, v8
	v_add_f32_e32 v0, v0, v9
	s_nop 1
	v_add_f32_dpp v0, v0, v0 quad_perm:[1,0,3,2] row_mask:0xf bank_mask:0xf bound_ctrl:1
	s_nop 1
	v_add_f32_dpp v0, v0, v0 quad_perm:[2,3,0,1] row_mask:0xf bank_mask:0xf bound_ctrl:1
	s_nop 1
	v_add_f32_dpp v0, v0, v0 row_half_mirror row_mask:0xf bank_mask:0xf bound_ctrl:1
	s_nop 1
	v_add_f32_dpp v0, v0, v0 row_mirror row_mask:0xf bank_mask:0xf bound_ctrl:1
	v_fmamk_f32 v0, v0, 0x3c2aaaab, v130
	v_cmp_gt_f32_e32 vcc, s26, v0
	v_mul_f32_e32 v1, 0x4b800000, v0
	s_nop 0
	v_cndmask_b32_e32 v0, v0, v1, vcc
	v_rsq_f32_e32 v0, v0
	s_nop 0
	v_mul_f32_e32 v1, 0x45800000, v0
	v_cndmask_b32_e32 v0, v0, v1, vcc
	v_mul_f32_e32 v0, 0x3e16c740, v0
	v_mul_f32_e32 v1, v2, v0
	v_mul_f32_e32 v2, v111, v1
	v_mul_f32_e32 v1, v6, v0
	v_mul_f32_e32 v4, v110, v1
	v_mul_f32_e32 v1, v10, v0
	v_mul_f32_e32 v5, v109, v1
	v_mul_f32_e32 v1, v14, v0
	v_mul_f32_e32 v6, v108, v1
	v_mul_f32_e32 v1, v18, v0
	v_mul_f32_e32 v0, v22, v0
	v_mul_f32_e32 v9, v106, v0
	v_or_b32_e32 v0, 18, v92
	v_mul_f32_e32 v8, v107, v1
	v_ashrrev_i32_e32 v1, 31, v0
	v_lshlrev_b64 v[0:1], 7, v[0:1]
	v_lshl_add_u64 v[0:1], v[50:51], 0, v[0:1]
	v_mov_b32_e32 v0, v172
	v_mov_b32_e32 v1, v173
	v_mov_b32_e32 v14, v11
	v_mov_b32_e32 v22, v19
	s_waitcnt vmcnt(0)
	v_mul_f32_e32 v10, v1, v9
	v_mul_f32_e32 v1, v1, v8
	v_fma_f32 v10, v0, v8, -v10
	v_fmac_f32_e32 v1, v0, v9
	v_cvt_pk_bf16_f32 v0, v2, v129
	ds_write_b16 v63, v0 offset:54944
	v_cvt_pk_bf16_f32 v0, v4, v129
	ds_write_b16 v63, v0 offset:54976
	v_cvt_pk_bf16_f32 v0, v5, v129
	ds_write_b16 v63, v0 offset:55008
	v_cvt_pk_bf16_f32 v0, v6, v129
	ds_write_b16 v63, v0 offset:55040
	v_cvt_pk_bf16_f32 v0, v10, v129
	ds_write_b16 v63, v0 offset:55072
	v_cvt_pk_bf16_f32 v0, v1, v129
	v_mov_b32_e32 v6, v3
	ds_write_b16 v63, v0 offset:55104
	v_pk_mul_f32 v[0:1], v[6:7], v[6:7]
	v_pk_mul_f32 v[4:5], v[14:15], v[14:15]
	v_add_f32_e32 v0, v0, v1
	v_add_f32_e32 v0, v0, v4
	v_pk_mul_f32 v[8:9], v[22:23], v[22:23]
	v_add_f32_e32 v0, v0, v5
	v_add_f32_e32 v0, v0, v8
	v_add_f32_e32 v0, v0, v9
	s_nop 1
	v_add_f32_dpp v0, v0, v0 quad_perm:[1,0,3,2] row_mask:0xf bank_mask:0xf bound_ctrl:1
	s_nop 1
	v_add_f32_dpp v0, v0, v0 quad_perm:[2,3,0,1] row_mask:0xf bank_mask:0xf bound_ctrl:1
	s_nop 1
	v_add_f32_dpp v0, v0, v0 row_half_mirror row_mask:0xf bank_mask:0xf bound_ctrl:1
	s_nop 1
	v_add_f32_dpp v0, v0, v0 row_mirror row_mask:0xf bank_mask:0xf bound_ctrl:1
	v_fmamk_f32 v0, v0, 0x3c2aaaab, v130
	v_cmp_gt_f32_e32 vcc, s26, v0
	v_mul_f32_e32 v1, 0x4b800000, v0
	s_nop 0
	v_cndmask_b32_e32 v0, v0, v1, vcc
	v_rsq_f32_e32 v0, v0
	s_nop 0
	v_mul_f32_e32 v1, 0x45800000, v0
	v_cndmask_b32_e32 v0, v0, v1, vcc
	v_mul_f32_e32 v0, 0x3e16c740, v0
	v_mul_f32_e32 v1, v3, v0
	v_mul_f32_e32 v2, v111, v1
	v_mul_f32_e32 v1, v7, v0
	v_mul_f32_e32 v3, v110, v1
	v_mul_f32_e32 v1, v11, v0
	v_mul_f32_e32 v4, v109, v1
	v_mul_f32_e32 v1, v15, v0
	v_mul_f32_e32 v5, v108, v1
	v_mul_f32_e32 v1, v19, v0
	v_mul_f32_e32 v0, v23, v0
	v_mul_f32_e32 v7, v106, v0
	v_or_b32_e32 v0, 19, v92
	v_mul_f32_e32 v6, v107, v1
	v_ashrrev_i32_e32 v1, 31, v0
	v_lshlrev_b64 v[0:1], 7, v[0:1]
	v_lshl_add_u64 v[0:1], v[50:51], 0, v[0:1]
	v_mov_b32_e32 v0, v174
	v_mov_b32_e32 v1, v175
	s_and_b64 vcc, exec, s[38:39]
	s_waitcnt vmcnt(0)
	v_mul_f32_e32 v8, v1, v7
	v_mul_f32_e32 v1, v1, v6
	v_fma_f32 v8, v0, v6, -v8
	v_fmac_f32_e32 v1, v0, v7
	v_cvt_pk_bf16_f32 v0, v2, v129
	ds_write_b16 v63, v0 offset:55152
	v_cvt_pk_bf16_f32 v0, v3, v129
	ds_write_b16 v63, v0 offset:55184
	v_cvt_pk_bf16_f32 v0, v4, v129
	ds_write_b16 v63, v0 offset:55216
	v_cvt_pk_bf16_f32 v0, v5, v129
	ds_write_b16 v63, v0 offset:55248
	v_cvt_pk_bf16_f32 v0, v8, v129
	ds_write_b16 v63, v0 offset:55280
	v_cvt_pk_bf16_f32 v0, v1, v129
	ds_write_b16 v63, v0 offset:55312
	ds_read_b128 v[0:3], v95 offset:51200
	v_or_b32_e32 v4, s17, v61
	v_mul_u32_u24_e32 v4, 0x60, v4
	v_lshlrev_b32_e32 v128, 1, v4
	v_lshl_add_u64 v[4:5], v[76:77], 0, v[128:129]
	s_waitcnt lgkmcnt(0)
	global_store_dwordx4 v[4:5], v[0:3], off
	ds_read_b128 v[0:3], v96 offset:51200
	v_or_b32_e32 v4, s17, v65
	v_mul_u32_u24_e32 v4, 0x60, v4
	v_lshlrev_b32_e32 v128, 1, v4
	v_lshl_add_u64 v[4:5], v[78:79], 0, v[128:129]
	s_waitcnt lgkmcnt(0)
	global_store_dwordx4 v[4:5], v[0:3], off
	ds_read_b128 v[0:3], v97 offset:51200
	v_or_b32_e32 v4, s17, v67
	v_mul_u32_u24_e32 v4, 0x60, v4
	v_lshlrev_b32_e32 v128, 1, v4
	v_lshl_add_u64 v[4:5], v[80:81], 0, v[128:129]
	s_waitcnt lgkmcnt(0)
	global_store_dwordx4 v[4:5], v[0:3], off
	ds_read_b128 v[0:3], v98 offset:51200
	v_or_b32_e32 v4, s17, v69
	v_mul_u32_u24_e32 v4, 0x60, v4
	v_lshlrev_b32_e32 v128, 1, v4
	v_lshl_add_u64 v[4:5], v[82:83], 0, v[128:129]
	s_waitcnt lgkmcnt(0)
	global_store_dwordx4 v[4:5], v[0:3], off
	ds_read_b128 v[0:3], v99 offset:51200
	v_or_b32_e32 v4, s17, v71
	v_mul_u32_u24_e32 v4, 0x60, v4
	v_lshlrev_b32_e32 v128, 1, v4
	v_lshl_add_u64 v[4:5], v[84:85], 0, v[128:129]
	s_waitcnt lgkmcnt(0)
	global_store_dwordx4 v[4:5], v[0:3], off
	ds_read_b128 v[0:3], v94
	v_or_b32_e32 v4, s17, v73
	v_mul_u32_u24_e32 v4, 0x60, v4
	v_lshlrev_b32_e32 v128, 1, v4
	v_lshl_add_u64 v[4:5], v[86:87], 0, v[128:129]
	s_mov_b32 s17, 32
	s_waitcnt lgkmcnt(0)
	global_store_dwordx4 v[4:5], v[0:3], off
	s_cbranch_vccz .LBB0_786
; DEVI void prepMLA_tile(const Params& p, int l, int g, int tile, char* lds) {
;     ...
;     {
;       const u16* Wt = (const u16*)(p.ws + OFF_WUKV) + ((size_t)l * 768 + h * 128) * 128;
; #pragma unroll 1
;       for (int pm = 0; pm < 4; ++pm) {
;         const int part = pm >> 1, mh = pm & 1;
;         f32x4 acc[2][4];
; #pragma unroll
;         for (int mb = 0; mb < 2; ++mb)
; #pragma unroll
;           for (int nb = 0; nb < 4; ++nb) acc[mb][nb] = (f32x4){0.f, 0.f, 0.f, 0.f};
; #pragma unroll 1
;         for (int ks = 0; ks < 4; ++ks) {
;           bf16x8 bfr[4];
; #pragma unroll
;           for (int nb = 0; nb < 4; ++nb) bfr[nb] = *(const bf16x8*)(Wt + (size_t)(part * 64 + nb * 16 + l15) * 128 + ks * 32 + l4 * 8);
; #pragma unroll
;           for (int mb = 0; mb < 2; ++mb) {
;             bf16x8 a = *(const bf16x8*)(Akv + ((mh * 2 + mb) * 16 + l15) * RSKV + ks * 64 + l4 * 16);
; #pragma unroll
;             for (int nb = 0; nb < 4; ++nb) acc[mb][nb] = __builtin_amdgcn_mfma_f32_16x16x32_bf16(a, bfr[nb], acc[mb][nb], 0, 0, 0);
;           }
;         }
;         if (part == 0) {
;           const float* nw = p.qk_k_norm_w + l * 96;
;           float wv[6];
; #pragma unroll
;           for (int nb = 0; nb < 6; ++nb) wv[nb] = nw[nb * 16 + l15];
;           u16* Kp = (u16*)(p.ws + OFF_K) + ((size_t)s0 * 6 + (size_t)h * len + pos0) * 96;
	s_nop 0
	v_lshlrev_b64 v[2:3], 7, v[58:59]
	v_lshlrev_b32_e32 v4, 4, v55
	v_and_b32_e32 v128, 0x70, v4
	v_lshl_add_u64 v[2:3], s[58:59], 0, v[2:3]
	v_add_u32_e32 v4, v103, v128
	v_lshl_add_u64 v[32:33], v[2:3], 0, v[128:129]
	v_lshlrev_b32_e32 v128, 2, v48
	v_lshrrev_b32_e32 v5, 3, v54
	v_lshl_add_u64 v[34:35], s[54:55], 0, v[128:129]
	v_lshl_add_u64 v[2:3], s[60:61], 0, v[56:57]
	v_lshlrev_b32_e32 v128, 1, v60
	v_mul_u32_u24_e32 v6, 0xd0, v5
	v_lshlrev_b32_e32 v59, 6, v5
	v_lshrrev_b32_e32 v5, 3, v102
	v_lshl_add_u64 v[36:37], v[2:3], 0, v[128:129]
	v_lshlrev_b32_e32 v128, 1, v62
	v_lshlrev_b32_e32 v0, 7, v52
	v_mul_u32_u24_e32 v7, 0xd0, v5
	v_lshlrev_b32_e32 v74, 6, v5
	v_lshrrev_b32_e32 v5, 3, v101
	v_lshl_add_u64 v[38:39], v[2:3], 0, v[128:129]
	v_lshlrev_b32_e32 v128, 1, v64
	v_ashrrev_i32_e32 v1, 31, v0
	v_mul_u32_u24_e32 v8, 0xd0, v5
	v_lshlrev_b32_e32 v75, 6, v5
	v_lshrrev_b32_e32 v5, 3, v105
	v_lshl_add_u64 v[40:41], v[2:3], 0, v[128:129]
	v_lshlrev_b32_e32 v128, 1, v66
	v_mul_u32_u24_e32 v9, 0xd0, v5
	s_mov_b32 s17, 0xc800
	v_lshl_add_u64 v[42:43], v[2:3], 0, v[128:129]
	v_lshlrev_b32_e32 v128, 1, v68
	v_lshlrev_b64 v[0:1], 8, v[0:1]
	v_readlane_b32 s38, v219, 61
	v_add3_u32 v76, v4, v9, s17
	v_lshl_add_u64 v[44:45], v[2:3], 0, v[128:129]
	v_lshlrev_b32_e32 v128, 1, v70
	v_readlane_b32 s17, v220, 49
	v_or_b32_e32 v0, v0, v72
	v_readlane_b32 s39, v219, 62
	v_lshl_add_u32 v58, v48, 2, 16
	v_lshlrev_b32_e32 v77, 6, v5
	v_lshl_add_u64 v[46:47], v[2:3], 0, v[128:129]
	v_add_u32_e32 v56, s17, v100
	v_lshl_add_u64 v[52:53], s[38:39], 0, v[0:1]
	v_lshlrev_b32_e32 v57, 7, v48
	s_mov_b32 s40, 0
	v_add_u32_e32 v60, v4, v6
	v_add_u32_e32 v62, v4, v7
	v_add_u32_e32 v64, v4, v8
	s_mov_b32 s41, 0
	s_branch .LBB0_791

; DEVI void prepMLA_tile(const Params& p, int l, int g, int tile, char* lds) {
;     ...
;       for (int pm = 0; pm < 4; ++pm) {
;         const int part = pm >> 1, mh = pm & 1;
;         f32x4 acc[2][4];
; #pragma unroll
;         for (int mb = 0; mb < 2; ++mb)
; #pragma unroll
;           for (int nb = 0; nb < 4; ++nb) acc[mb][nb] = (f32x4){0.f, 0.f, 0.f, 0.f};
; #pragma unroll 1
;         for (int ks = 0; ks < 4; ++ks) {
;           bf16x8 bfr[4];
; #pragma unroll
;           for (int nb = 0; nb < 4; ++nb) bfr[nb] = *(const bf16x8*)(Wt + (size_t)(part * 64 + nb * 16 + l15) * 128 + ks * 32 + l4 * 8);
; #pragma unroll
;           for (int mb = 0; mb < 2; ++mb) {
;             bf16x8 a = *(const bf16x8*)(Akv + ((mh * 2 + mb) * 16 + l15) * RSKV + ks * 64 + l4 * 16);
; #pragma unroll
;             for (int nb = 0; nb < 4; ++nb) acc[mb][nb] = __builtin_amdgcn_mfma_f32_16x16x32_bf16(a, bfr[nb], acc[mb][nb], 0, 0, 0);
;           }
;         }
.LBB0_791:
	s_lshl_b32 s17, s40, 7
	s_and_b32 s17, s17, 0xffffe000
	v_or_b32_e32 v128, s17, v57
	s_and_b32 s17, s41, 1
	v_lshl_or_b32 v0, s17, 5, v48
	v_mad_u32_u24 v66, v0, s27, v56
	v_mov_b32_e32 v0, 0
	v_lshl_add_u64 v[54:55], v[128:129], 1, v[52:53]
	s_mov_b64 s[38:39], 0
	v_mov_b32_e32 v1, v0
	v_mov_b32_e32 v2, v0
	v_mov_b32_e32 v3, v0
	v_mov_b32_e32 v4, v0
	v_mov_b32_e32 v5, v0
	v_mov_b32_e32 v6, v0
	v_mov_b32_e32 v7, v0
	v_mov_b32_e32 v8, v0
	v_mov_b32_e32 v9, v0
	v_mov_b32_e32 v10, v0
	v_mov_b32_e32 v11, v0
	v_mov_b32_e32 v12, v0
	v_mov_b32_e32 v13, v0
	v_mov_b32_e32 v14, v0
	v_mov_b32_e32 v15, v0
	v_mov_b32_e32 v16, v0
	v_mov_b32_e32 v17, v0
	v_mov_b32_e32 v18, v0
	v_mov_b32_e32 v19, v0
	v_mov_b32_e32 v20, v0
	v_mov_b32_e32 v21, v0
	v_mov_b32_e32 v22, v0
	v_mov_b32_e32 v23, v0
	v_mov_b32_e32 v24, v0
	v_mov_b32_e32 v25, v0
	v_mov_b32_e32 v26, v0
	v_mov_b32_e32 v27, v0
	v_mov_b32_e32 v28, v0
	v_mov_b32_e32 v29, v0
	v_mov_b32_e32 v30, v0
	v_mov_b32_e32 v31, v0
	v_add_co_u32_e32 v238, vcc, 0x22d9000, v54
	s_nop 1
	v_addc_co_u32_e32 v239, vcc, 0, v55, vcc
	v_add_co_u32_e32 v240, vcc, 0x22db000, v54
	s_nop 1
	v_addc_co_u32_e32 v241, vcc, 0, v55, vcc
	global_load_dwordx4 v[162:165], v[238:239], off offset:-4096
	global_load_dwordx4 v[166:169], v[238:239], off
	global_load_dwordx4 v[170:173], v[240:241], off offset:-4096
	global_load_dwordx4 v[174:177], v[240:241], off
	global_load_dwordx4 v[178:181], v[238:239], off offset:-4032
	global_load_dwordx4 v[182:185], v[238:239], off offset:64
	global_load_dwordx4 v[186:189], v[240:241], off offset:-4032
	global_load_dwordx4 v[190:193], v[240:241], off offset:64
	global_load_dwordx4 v[194:197], v[238:239], off offset:-3968
	global_load_dwordx4 v[198:201], v[238:239], off offset:128
	global_load_dwordx4 v[202:205], v[240:241], off offset:-3968
	global_load_dwordx4 v[206:209], v[240:241], off offset:128
	global_load_dwordx4 v[210:213], v[238:239], off offset:-3904
	global_load_dwordx4 v[214:217], v[238:239], off offset:192
	global_load_dwordx4 v[222:225], v[240:241], off offset:-3904
	global_load_dwordx4 v[226:229], v[240:241], off offset:192
	ds_read_b128 v[100:103], v66
	ds_read_b128 v[248:251], v66 offset:4352
	s_waitcnt vmcnt(12) lgkmcnt(1)
	v_mfma_f32_16x16x32_bf16 v[28:31], v[100:103], v[162:165], v[28:31]
	v_mfma_f32_16x16x32_bf16 v[24:27], v[100:103], v[166:169], v[24:27]
	v_mfma_f32_16x16x32_bf16 v[20:23], v[100:103], v[170:173], v[20:23]
	v_mfma_f32_16x16x32_bf16 v[16:19], v[100:103], v[174:177], v[16:19]
	s_waitcnt lgkmcnt(0)
	v_mfma_f32_16x16x32_bf16 v[12:15], v[248:251], v[162:165], v[12:15]
	v_mfma_f32_16x16x32_bf16 v[8:11], v[248:251], v[166:169], v[8:11]
	v_mfma_f32_16x16x32_bf16 v[4:7], v[248:251], v[170:173], v[4:7]
	v_mfma_f32_16x16x32_bf16 v[0:3], v[248:251], v[174:177], v[0:3]
	ds_read_b128 v[100:103], v66 offset:64
	ds_read_b128 v[248:251], v66 offset:4416
	s_waitcnt vmcnt(8) lgkmcnt(1)
	v_mfma_f32_16x16x32_bf16 v[28:31], v[100:103], v[178:181], v[28:31]
	v_mfma_f32_16x16x32_bf16 v[24:27], v[100:103], v[182:185], v[24:27]
	v_mfma_f32_16x16x32_bf16 v[20:23], v[100:103], v[186:189], v[20:23]
	v_mfma_f32_16x16x32_bf16 v[16:19], v[100:103], v[190:193], v[16:19]
	s_waitcnt lgkmcnt(0)
	v_mfma_f32_16x16x32_bf16 v[12:15], v[248:251], v[178:181], v[12:15]
	v_mfma_f32_16x16x32_bf16 v[8:11], v[248:251], v[182:185], v[8:11]
	v_mfma_f32_16x16x32_bf16 v[4:7], v[248:251], v[186:189], v[4:7]
	v_mfma_f32_16x16x32_bf16 v[0:3], v[248:251], v[190:193], v[0:3]
	ds_read_b128 v[100:103], v66 offset:128
	ds_read_b128 v[248:251], v66 offset:4480
	s_waitcnt vmcnt(4) lgkmcnt(1)
	v_mfma_f32_16x16x32_bf16 v[28:31], v[100:103], v[194:197], v[28:31]
	v_mfma_f32_16x16x32_bf16 v[24:27], v[100:103], v[198:201], v[24:27]
	v_mfma_f32_16x16x32_bf16 v[20:23], v[100:103], v[202:205], v[20:23]
	v_mfma_f32_16x16x32_bf16 v[16:19], v[100:103], v[206:209], v[16:19]
	s_waitcnt lgkmcnt(0)
	v_mfma_f32_16x16x32_bf16 v[12:15], v[248:251], v[194:197], v[12:15]
	v_mfma_f32_16x16x32_bf16 v[8:11], v[248:251], v[198:201], v[8:11]
	v_mfma_f32_16x16x32_bf16 v[4:7], v[248:251], v[202:205], v[4:7]
	v_mfma_f32_16x16x32_bf16 v[0:3], v[248:251], v[206:209], v[0:3]
	ds_read_b128 v[100:103], v66 offset:192
	ds_read_b128 v[248:251], v66 offset:4544
	s_waitcnt vmcnt(0) lgkmcnt(1)
	v_mfma_f32_16x16x32_bf16 v[28:31], v[100:103], v[210:213], v[28:31]
	v_mfma_f32_16x16x32_bf16 v[24:27], v[100:103], v[214:217], v[24:27]
	v_mfma_f32_16x16x32_bf16 v[20:23], v[100:103], v[222:225], v[20:23]
	v_mfma_f32_16x16x32_bf16 v[16:19], v[100:103], v[226:229], v[16:19]
	s_waitcnt lgkmcnt(0)
	v_mfma_f32_16x16x32_bf16 v[12:15], v[248:251], v[210:213], v[12:15]
	v_mfma_f32_16x16x32_bf16 v[8:11], v[248:251], v[214:217], v[8:11]
	v_mfma_f32_16x16x32_bf16 v[4:7], v[248:251], v[222:225], v[4:7]
	v_mfma_f32_16x16x32_bf16 v[0:3], v[248:251], v[226:229], v[0:3]
	s_cmp_gt_u32 s41, 1
	s_mov_b64 s[38:39], -1
	s_cbranch_scc0 .LBB0_795
; DEVI void prepMLA_tile(const Params& p, int l, int g, int tile, char* lds) {
;     ...
;         if (part == 0) {
;           const float* nw = p.qk_k_norm_w + l * 96;
;           float wv[6];
; #pragma unroll
;           for (int nb = 0; nb < 6; ++nb) wv[nb] = nw[nb * 16 + l15];
;           u16* Kp = (u16*)(p.ws + OFF_K) + ((size_t)s0 * 6 + (size_t)h * len + pos0) * 96;
; #pragma unroll
;           for (int mb = 0; mb < 2; ++mb)
; #pragma unroll
;             for (int j = 0; j < 4; ++j) {
;               int rowi = (mh * 2 + mb) * 16 + l4 * 4 + j;
;               float x1 = kro[rowi * 32 + l15], x2 = kro[rowi * 32 + 16 + l15];
;               float ss = x1 * x1 + x2 * x2;
; #pragma unroll
;               for (int nb = 0; nb < 4; ++nb) ss += acc[mb][nb][j] * acc[mb][nb][j];
;               ss = rowreduce<16>(ss);
;               float rstd = rsqrtf(ss * (1.f / 96.f) + 1e-6f);
;               const float* cs = rope + ((size_t)(pos0 + rowi) * 16 + l15) * 2;
;               float c = cs[0], s = cs[1];
;               float a1 = x1 * rstd * wv[4], a2 = x2 * rstd * wv[5];
;               u16* kr = (u16*)(WS + (mb * 16 + l4 * 4 + j) * 208) + l15;
; #pragma unroll
;               for (int nb = 0; nb < 4; ++nb) kr[nb * 16] = f2bf(acc[mb][nb][j] * rstd * wv[nb]);
;               kr[64] = f2bf(a1 * c - a2 * s);
;               kr[80] = f2bf(a2 * c + a1 * s);
;             }
; #pragma unroll
;           for (int i = 0; i < 6; ++i) {
;             int c = lane + i * 64; int rr_ = c / 12, ch = c % 12;
;             *(u32x4*)(Kp + (size_t)(mh * 32 + rr_) * 96 + ch * 8) = *(const u32x4*)(WS + rr_ * 208 + ch * 16);
;           }
;         } else {
;           u16* Vp = (u16*)(p.ws + OFF_V) + ((size_t)s0 * 6 + (size_t)h * len + pos0) * 64;
; #pragma unroll
;           for (int mb = 0; mb < 2; ++mb)
; #pragma unroll
;             for (int j = 0; j < 4; ++j) {
;               int rowi = (mh * 2 + mb) * 16 + l4 * 4 + j;
;               u16* vr = (u16*)(WS + (mb * 16 + l4 * 4 + j) * 208) + l15;
; #pragma unroll
;               for (int nb = 0; nb < 4; ++nb) vr[nb * 16] = f2bf(acc[mb][nb][j]);
;             }
; #pragma unroll
;           for (int i = 0; i < 4; ++i) {
;             int c = lane + i * 64; int rr_ = c >> 3, ch = c & 7;
;             *(u32x4*)(Vp + (size_t)(mh * 32 + rr_) * 64 + ch * 8) = *(const u32x4*)(WS + rr_ * 208 + ch * 16);
	v_cvt_pk_bf16_f32 v54, v28, v129
	ds_write_b16 v63, v54 offset:51200
	v_cvt_pk_bf16_f32 v54, v24, v129
	ds_write_b16 v63, v54 offset:51232
	v_cvt_pk_bf16_f32 v54, v20, v129
	ds_write_b16 v63, v54 offset:51264
	v_cvt_pk_bf16_f32 v54, v16, v129
	ds_write_b16 v63, v54 offset:51296
	v_cvt_pk_bf16_f32 v54, v29, v129
	ds_write_b16 v63, v54 offset:51408
	v_cvt_pk_bf16_f32 v54, v25, v129
	ds_write_b16 v63, v54 offset:51440
	v_cvt_pk_bf16_f32 v54, v21, v129
	ds_write_b16 v63, v54 offset:51472
	v_cvt_pk_bf16_f32 v54, v17, v129
	ds_write_b16 v63, v54 offset:51504
	v_cvt_pk_bf16_f32 v54, v30, v129
	ds_write_b16 v63, v54 offset:51616
	v_cvt_pk_bf16_f32 v54, v26, v129
	ds_write_b16 v63, v54 offset:51648
	v_cvt_pk_bf16_f32 v54, v22, v129
	ds_write_b16 v63, v54 offset:51680
	v_cvt_pk_bf16_f32 v54, v18, v129
	ds_write_b16 v63, v54 offset:51712
	v_cvt_pk_bf16_f32 v54, v31, v129
	ds_write_b16 v63, v54 offset:51824
	v_cvt_pk_bf16_f32 v54, v27, v129
	ds_write_b16 v63, v54 offset:51856
	v_cvt_pk_bf16_f32 v54, v23, v129
	ds_write_b16 v63, v54 offset:51888
	v_cvt_pk_bf16_f32 v54, v19, v129
	ds_write_b16 v63, v54 offset:51920
	v_cvt_pk_bf16_f32 v54, v12, v129
	ds_write_b16 v63, v54 offset:54528
	v_cvt_pk_bf16_f32 v54, v8, v129
	ds_write_b16 v63, v54 offset:54560
	v_cvt_pk_bf16_f32 v54, v4, v129
	ds_write_b16 v63, v54 offset:54592
	v_cvt_pk_bf16_f32 v54, v0, v129
	ds_write_b16 v63, v54 offset:54624
	v_cvt_pk_bf16_f32 v54, v13, v129
	ds_write_b16 v63, v54 offset:54736
	v_cvt_pk_bf16_f32 v54, v9, v129
	ds_write_b16 v63, v54 offset:54768
	v_cvt_pk_bf16_f32 v54, v5, v129
	ds_write_b16 v63, v54 offset:54800
	v_cvt_pk_bf16_f32 v54, v1, v129
	ds_write_b16 v63, v54 offset:54832
	v_cvt_pk_bf16_f32 v54, v14, v129
	ds_write_b16 v63, v54 offset:54944
	v_cvt_pk_bf16_f32 v54, v10, v129
	ds_write_b16 v63, v54 offset:54976
	v_cvt_pk_bf16_f32 v54, v6, v129
	ds_write_b16 v63, v54 offset:55008
	v_cvt_pk_bf16_f32 v54, v2, v129
	ds_write_b16 v63, v54 offset:55040
	v_cvt_pk_bf16_f32 v54, v15, v129
	ds_write_b16 v63, v54 offset:55152
	v_cvt_pk_bf16_f32 v54, v11, v129
	ds_write_b16 v63, v54 offset:55184
	v_cvt_pk_bf16_f32 v54, v7, v129
	ds_write_b16 v63, v54 offset:55216
	v_cvt_pk_bf16_f32 v54, v3, v129
	ds_write_b16 v63, v54 offset:55248
	ds_read_b128 v[78:81], v60 offset:51200
	s_lshl_b32 s17, s17, 11
	v_or_b32_e32 v54, s17, v59
	v_lshlrev_b32_e32 v128, 1, v54
	v_lshl_add_u64 v[54:55], v[32:33], 0, v[128:129]
	s_waitcnt lgkmcnt(0)
	global_store_dwordx4 v[54:55], v[78:81], off
	ds_read_b128 v[78:81], v62 offset:51200
	v_or_b32_e32 v54, s17, v74
	v_lshlrev_b32_e32 v128, 1, v54
	v_lshl_add_u64 v[54:55], v[32:33], 0, v[128:129]
	s_mov_b64 s[38:39], 0
	s_waitcnt lgkmcnt(0)
	global_store_dwordx4 v[54:55], v[78:81], off
	ds_read_b128 v[78:81], v64 offset:51200
	v_or_b32_e32 v54, s17, v75
	v_lshlrev_b32_e32 v128, 1, v54
	v_lshl_add_u64 v[54:55], v[32:33], 0, v[128:129]
	v_or_b32_e32 v128, s17, v77
	s_waitcnt lgkmcnt(0)
	global_store_dwordx4 v[54:55], v[78:81], off
.LBB0_795:
	s_andn2_b64 vcc, exec, s[38:39]
	v_mov_b64_e32 v[54:55], v[32:33]
	v_mov_b32_e32 v66, v76
	s_cbranch_vccnz .LBB0_790
	s_lshl_b32 s17, s41, 5
	v_or_b32_e32 v80, s17, v49
	v_lshl_add_u32 v54, v80, 7, v58
	v_add_u32_e32 v54, 0xa800, v54
	global_load_dword v79, v[34:35], off
	global_load_dword v78, v[34:35], off offset:64
	global_load_dword v72, v[34:35], off offset:128
	global_load_dword v70, v[34:35], off offset:192
	global_load_dword v66, v[34:35], off offset:256
	global_load_dword v68, v[34:35], off offset:320
	ds_read2_b32 v[54:55], v54 offset1:16
	v_mov_b32_e32 v84, v24
	v_mov_b32_e32 v85, v28
	v_pk_mul_f32 v[84:85], v[84:85], v[84:85]
	v_mov_b32_e32 v86, v16
	s_waitcnt lgkmcnt(0)
	v_pk_mul_f32 v[82:83], v[54:55], v[54:55]
	v_mov_b32_e32 v87, v20
	v_add_f32_e32 v81, v82, v83
	v_add_f32_e32 v81, v85, v81
	v_pk_mul_f32 v[86:87], v[86:87], v[86:87]
	v_add_f32_e32 v81, v84, v81
	v_add_f32_e32 v81, v87, v81
	v_add_f32_e32 v81, v86, v81
	s_nop 1
	v_add_f32_dpp v81, v81, v81 quad_perm:[1,0,3,2] row_mask:0xf bank_mask:0xf bound_ctrl:1
	s_nop 1
	v_add_f32_dpp v81, v81, v81 quad_perm:[2,3,0,1] row_mask:0xf bank_mask:0xf bound_ctrl:1
	s_nop 1
	v_add_f32_dpp v81, v81, v81 row_half_mirror row_mask:0xf bank_mask:0xf bound_ctrl:1
	s_nop 1
	v_add_f32_dpp v81, v81, v81 row_mirror row_mask:0xf bank_mask:0xf bound_ctrl:1
	v_fmamk_f32 v81, v81, 0x3c2aaaab, v130
	v_cmp_gt_f32_e32 vcc, s26, v81
	v_mul_f32_e32 v82, 0x4b800000, v81
	s_nop 0
	v_cndmask_b32_e32 v81, v81, v82, vcc
	v_rsq_f32_e32 v81, v81
	s_nop 0
	v_mul_f32_e32 v82, 0x45800000, v81
	v_cndmask_b32_e32 v81, v81, v82, vcc
	v_or_b32_e32 v82, s85, v80
	v_ashrrev_i32_e32 v83, 31, v82
	v_lshlrev_b64 v[82:83], 7, v[82:83]
	v_lshl_add_u64 v[82:83], v[50:51], 0, v[82:83]
	global_load_dwordx2 v[82:83], v[82:83], off
	v_or_b32_e32 v176, 1, v80
	v_or_b32_e32 v176, s85, v176
	v_ashrrev_i32_e32 v177, 31, v176
	v_lshlrev_b64 v[176:177], 7, v[176:177]
	v_lshl_add_u64 v[176:177], v[50:51], 0, v[176:177]
	global_load_dwordx2 v[162:163], v[176:177], off
	v_or_b32_e32 v176, 2, v80
	v_or_b32_e32 v176, s85, v176
	v_ashrrev_i32_e32 v177, 31, v176
	v_lshlrev_b64 v[176:177], 7, v[176:177]
	v_lshl_add_u64 v[176:177], v[50:51], 0, v[176:177]
	global_load_dwordx2 v[164:165], v[176:177], off
	v_or_b32_e32 v176, 3, v80
	v_or_b32_e32 v176, s85, v176
	v_ashrrev_i32_e32 v177, 31, v176
	v_lshlrev_b64 v[176:177], 7, v[176:177]
	v_lshl_add_u64 v[176:177], v[50:51], 0, v[176:177]
	global_load_dwordx2 v[166:167], v[176:177], off
	v_or_b32_e32 v176, 16, v80
	v_or_b32_e32 v176, s85, v176
	v_ashrrev_i32_e32 v177, 31, v176
	v_lshlrev_b64 v[176:177], 7, v[176:177]
	v_lshl_add_u64 v[176:177], v[50:51], 0, v[176:177]
	global_load_dwordx2 v[168:169], v[176:177], off
	v_or_b32_e32 v176, 17, v80
	v_or_b32_e32 v176, s85, v176
	v_ashrrev_i32_e32 v177, 31, v176
	v_lshlrev_b64 v[176:177], 7, v[176:177]
	v_lshl_add_u64 v[176:177], v[50:51], 0, v[176:177]
	global_load_dwordx2 v[170:171], v[176:177], off
	v_or_b32_e32 v176, 18, v80
	v_or_b32_e32 v176, s85, v176
	v_ashrrev_i32_e32 v177, 31, v176
	v_lshlrev_b64 v[176:177], 7, v[176:177]
	v_lshl_add_u64 v[176:177], v[50:51], 0, v[176:177]
	global_load_dwordx2 v[172:173], v[176:177], off
	v_or_b32_e32 v176, 19, v80
	v_or_b32_e32 v176, s85, v176
	v_ashrrev_i32_e32 v177, 31, v176
	v_lshlrev_b64 v[176:177], 7, v[176:177]
	v_lshl_add_u64 v[176:177], v[50:51], 0, v[176:177]
	global_load_dwordx2 v[174:175], v[176:177], off
	v_mul_f32_e32 v28, v28, v81
	v_mul_f32_e32 v24, v24, v81
	v_mul_f32_e32 v20, v20, v81
	v_mul_f32_e32 v16, v16, v81
	v_mul_f32_e32 v55, v55, v81
	v_mul_f32_e32 v54, v54, v81
	s_waitcnt vmcnt(6)
; DEVI u16 f2bf(float f) { return (u16)(cvtpk(f, 0.f) & 0xffffu); }
; DEVI void prepMLA_tile(const Params& p, int l, int g, int tile, char* lds) {
;     ...
;           for (int mb = 0; mb < 2; ++mb)
; #pragma unroll
;             for (int j = 0; j < 4; ++j) {
;               int rowi = (mh * 2 + mb) * 16 + l4 * 4 + j;
;               float x1 = kro[rowi * 32 + l15], x2 = kro[rowi * 32 + 16 + l15];
;               float ss = x1 * x1 + x2 * x2;
; #pragma unroll
;               for (int nb = 0; nb < 4; ++nb) ss += acc[mb][nb][j] * acc[mb][nb][j];
;               ss = rowreduce<16>(ss);
;               float rstd = rsqrtf(ss * (1.f / 96.f) + 1e-6f);
;               const float* cs = rope + ((size_t)(pos0 + rowi) * 16 + l15) * 2;
;               float c = cs[0], s = cs[1];
;               float a1 = x1 * rstd * wv[4], a2 = x2 * rstd * wv[5];
;               u16* kr = (u16*)(WS + (mb * 16 + l4 * 4 + j) * 208) + l15;
; #pragma unroll
;               for (int nb = 0; nb < 4; ++nb) kr[nb * 16] = f2bf(acc[mb][nb][j] * rstd * wv[nb]);
;               kr[64] = f2bf(a1 * c - a2 * s);
;               kr[80] = f2bf(a2 * c + a1 * s);
;             }
	v_mul_f32_e32 v28, v79, v28
	s_waitcnt vmcnt(5)
	v_mul_f32_e32 v24, v78, v24
	s_waitcnt vmcnt(4)
	v_mul_f32_e32 v20, v72, v20
	v_cvt_pk_bf16_f32 v28, v28, v129
	ds_write_b16 v63, v28 offset:51200
	v_cvt_pk_bf16_f32 v24, v24, v129
	ds_write_b16 v63, v24 offset:51232
	v_cvt_pk_bf16_f32 v20, v20, v129
	s_waitcnt vmcnt(3)
	v_mul_f32_e32 v16, v70, v16
	ds_write_b16 v63, v20 offset:51264
	v_cvt_pk_bf16_f32 v16, v16, v129
	s_waitcnt vmcnt(1)
	v_mul_f32_e32 v20, v68, v55
	ds_write_b16 v63, v16 offset:51296
	v_mul_f32_e32 v16, v66, v54
	v_mov_b32_e32 v28, v25
	v_pk_mul_f32 v[84:85], v[28:29], v[28:29]
	s_waitcnt vmcnt(0)
	v_mul_f32_e32 v24, v83, v20
	v_fma_f32 v24, v82, v16, -v24
	v_mul_f32_e32 v16, v83, v16
	v_fmac_f32_e32 v16, v82, v20
	v_cvt_pk_bf16_f32 v24, v24, v129
	ds_write_b16 v63, v24 offset:51328
	v_cvt_pk_bf16_f32 v16, v16, v129
	ds_write_b16 v63, v16 offset:51360
	v_or_b32_e32 v16, 1, v80
	v_lshl_add_u32 v20, v16, 7, v58
	v_add_u32_e32 v20, 0xa800, v20
	ds_read2_b32 v[54:55], v20 offset1:16
	v_mov_b32_e32 v20, v17
	v_pk_mul_f32 v[86:87], v[20:21], v[20:21]
	s_waitcnt lgkmcnt(0)
	v_pk_mul_f32 v[82:83], v[54:55], v[54:55]
	s_nop 0
	v_add_f32_e32 v20, v82, v83
	v_or_b32_e32 v82, s85, v16
	v_ashrrev_i32_e32 v83, 31, v82
	v_lshlrev_b64 v[82:83], 7, v[82:83]
	v_lshl_add_u64 v[82:83], v[50:51], 0, v[82:83]
	v_mov_b32_e32 v82, v162
	v_mov_b32_e32 v83, v163
	v_add_f32_e32 v20, v85, v20
	v_add_f32_e32 v20, v84, v20
	v_add_f32_e32 v20, v87, v20
	v_add_f32_e32 v20, v86, v20
	s_nop 1
	v_add_f32_dpp v20, v20, v20 quad_perm:[1,0,3,2] row_mask:0xf bank_mask:0xf bound_ctrl:1
	s_nop 1
	v_add_f32_dpp v20, v20, v20 quad_perm:[2,3,0,1] row_mask:0xf bank_mask:0xf bound_ctrl:1
	s_nop 1
	v_add_f32_dpp v20, v20, v20 row_half_mirror row_mask:0xf bank_mask:0xf bound_ctrl:1
	s_nop 1
	v_add_f32_dpp v20, v20, v20 row_mirror row_mask:0xf bank_mask:0xf bound_ctrl:1
	v_fmamk_f32 v20, v20, 0x3c2aaaab, v130
	v_cmp_gt_f32_e32 vcc, s26, v20
	v_mul_f32_e32 v24, 0x4b800000, v20
	s_nop 0
	v_cndmask_b32_e32 v20, v20, v24, vcc
	v_rsq_f32_e32 v20, v20
	s_nop 0
	v_mul_f32_e32 v24, 0x45800000, v20
	v_cndmask_b32_e32 v20, v20, v24, vcc
	v_mul_f32_e32 v28, v29, v20
	v_mul_f32_e32 v25, v25, v20
	v_mul_f32_e32 v21, v21, v20
	v_mul_f32_e32 v17, v17, v20
	v_mul_f32_e32 v28, v79, v28
	v_mul_f32_e32 v25, v78, v25
	v_mul_f32_e32 v21, v72, v21
	v_mul_f32_e32 v17, v70, v17
	v_mul_f32_e32 v24, v55, v20
	v_cvt_pk_bf16_f32 v28, v28, v129
	ds_write_b16 v63, v28 offset:51408
	v_cvt_pk_bf16_f32 v25, v25, v129
	ds_write_b16 v63, v25 offset:51440
	v_cvt_pk_bf16_f32 v21, v21, v129
	ds_write_b16 v63, v21 offset:51472
	v_cvt_pk_bf16_f32 v17, v17, v129
	v_mul_f32_e32 v16, v54, v20
	ds_write_b16 v63, v17 offset:51504
	v_mul_f32_e32 v17, v68, v24
	v_mul_f32_e32 v16, v66, v16
	v_or_b32_e32 v54, 2, v80
	v_mov_b32_e32 v24, v26
	v_mov_b32_e32 v25, v30
	v_pk_mul_f32 v[24:25], v[24:25], v[24:25]
	v_mov_b32_e32 v28, v18
	v_mov_b32_e32 v29, v22
	v_pk_mul_f32 v[28:29], v[28:29], v[28:29]
	s_waitcnt vmcnt(0)
	v_mul_f32_e32 v20, v83, v17
	v_fma_f32 v20, v82, v16, -v20
	v_mul_f32_e32 v16, v83, v16
	v_fmac_f32_e32 v16, v82, v17
	v_cvt_pk_bf16_f32 v20, v20, v129
	ds_write_b16 v63, v20 offset:51536
	v_cvt_pk_bf16_f32 v16, v16, v129
	ds_write_b16 v63, v16 offset:51568
	v_lshl_add_u32 v16, v54, 7, v58
	v_add_u32_e32 v16, 0xa800, v16
	ds_read2_b32 v[16:17], v16 offset1:16
	s_waitcnt lgkmcnt(0)
	v_pk_mul_f32 v[20:21], v[16:17], v[16:17]
	s_nop 0
	v_add_f32_e32 v20, v20, v21
	v_add_f32_e32 v20, v25, v20
	v_add_f32_e32 v20, v24, v20
	v_add_f32_e32 v20, v29, v20
	v_add_f32_e32 v20, v28, v20
	s_nop 1
	v_add_f32_dpp v20, v20, v20 quad_perm:[1,0,3,2] row_mask:0xf bank_mask:0xf bound_ctrl:1
	s_nop 1
	v_add_f32_dpp v20, v20, v20 quad_perm:[2,3,0,1] row_mask:0xf bank_mask:0xf bound_ctrl:1
	s_nop 1
	v_add_f32_dpp v20, v20, v20 row_half_mirror row_mask:0xf bank_mask:0xf bound_ctrl:1
	s_nop 1
	v_add_f32_dpp v20, v20, v20 row_mirror row_mask:0xf bank_mask:0xf bound_ctrl:1
	v_fmamk_f32 v20, v20, 0x3c2aaaab, v130
	v_cmp_gt_f32_e32 vcc, s26, v20
	v_mul_f32_e32 v21, 0x4b800000, v20
	s_nop 0
	v_cndmask_b32_e32 v20, v20, v21, vcc
	v_rsq_f32_e32 v20, v20
	s_nop 0
	v_mul_f32_e32 v21, 0x45800000, v20
	v_cndmask_b32_e32 v24, v20, v21, vcc
	v_or_b32_e32 v20, s85, v54
	v_ashrrev_i32_e32 v21, 31, v20
	v_lshlrev_b64 v[20:21], 7, v[20:21]
	v_lshl_add_u64 v[20:21], v[50:51], 0, v[20:21]
	v_mov_b32_e32 v20, v164
	v_mov_b32_e32 v21, v165
	v_mul_f32_e32 v25, v30, v24
	v_mul_f32_e32 v25, v79, v25
	v_cvt_pk_bf16_f32 v25, v25, v129
	ds_write_b16 v63, v25 offset:51616
	v_mul_f32_e32 v25, v26, v24
	v_mul_f32_e32 v22, v22, v24
	v_mul_f32_e32 v18, v18, v24
	v_mul_f32_e32 v17, v17, v24
	v_mul_f32_e32 v25, v78, v25
	v_mul_f32_e32 v22, v72, v22
	v_mul_f32_e32 v18, v70, v18
	v_mul_f32_e32 v16, v16, v24
	v_cvt_pk_bf16_f32 v25, v25, v129
	ds_write_b16 v63, v25 offset:51648
	v_cvt_pk_bf16_f32 v22, v22, v129
	ds_write_b16 v63, v22 offset:51680
	v_cvt_pk_bf16_f32 v18, v18, v129
	v_mul_f32_e32 v17, v68, v17
	ds_write_b16 v63, v18 offset:51712
	v_mul_f32_e32 v16, v66, v16
	v_mov_b32_e32 v30, v27
	v_pk_mul_f32 v[24:25], v[30:31], v[30:31]
	v_mov_b32_e32 v22, v19
	v_pk_mul_f32 v[28:29], v[22:23], v[22:23]
	v_mov_b64_e32 v[54:55], v[46:47]
	s_waitcnt vmcnt(0)
	v_mul_f32_e32 v18, v21, v17
	v_fma_f32 v18, v20, v16, -v18
	v_mul_f32_e32 v16, v21, v16
	v_cvt_pk_bf16_f32 v18, v18, v129
	v_fmac_f32_e32 v16, v20, v17
	ds_write_b16 v63, v18 offset:51744
	v_cvt_pk_bf16_f32 v16, v16, v129
	v_or_b32_e32 v18, 3, v80
	ds_write_b16 v63, v16 offset:51776
	v_lshl_add_u32 v16, v18, 7, v58
	v_add_u32_e32 v16, 0xa800, v16
	ds_read2_b32 v[16:17], v16 offset1:16
	s_waitcnt lgkmcnt(0)
; DEVI u16 f2bf(float f) { return (u16)(cvtpk(f, 0.f) & 0xffffu); }
; DEVI void prepMLA_tile(const Params& p, int l, int g, int tile, char* lds) {
;     ...
;             for (int j = 0; j < 4; ++j) {
;               int rowi = (mh * 2 + mb) * 16 + l4 * 4 + j;
;               float x1 = kro[rowi * 32 + l15], x2 = kro[rowi * 32 + 16 + l15];
;               float ss = x1 * x1 + x2 * x2;
; #pragma unroll
;               for (int nb = 0; nb < 4; ++nb) ss += acc[mb][nb][j] * acc[mb][nb][j];
;               ss = rowreduce<16>(ss);
;               float rstd = rsqrtf(ss * (1.f / 96.f) + 1e-6f);
;               const float* cs = rope + ((size_t)(pos0 + rowi) * 16 + l15) * 2;
;               float c = cs[0], s = cs[1];
;               float a1 = x1 * rstd * wv[4], a2 = x2 * rstd * wv[5];
;               u16* kr = (u16*)(WS + (mb * 16 + l4 * 4 + j) * 208) + l15;
; #pragma unroll
;               for (int nb = 0; nb < 4; ++nb) kr[nb * 16] = f2bf(acc[mb][nb][j] * rstd * wv[nb]);
;               kr[64] = f2bf(a1 * c - a2 * s);
;               kr[80] = f2bf(a2 * c + a1 * s);
;             }
	v_pk_mul_f32 v[20:21], v[16:17], v[16:17]
	s_nop 0
	v_add_f32_e32 v20, v20, v21
	v_add_f32_e32 v20, v25, v20
	v_add_f32_e32 v20, v24, v20
	v_add_f32_e32 v20, v29, v20
	v_add_f32_e32 v20, v28, v20
	v_or_b32_e32 v24, 16, v80
	s_nop 0
	v_add_f32_dpp v20, v20, v20 quad_perm:[1,0,3,2] row_mask:0xf bank_mask:0xf bound_ctrl:1
	s_nop 1
	v_add_f32_dpp v20, v20, v20 quad_perm:[2,3,0,1] row_mask:0xf bank_mask:0xf bound_ctrl:1
	s_nop 1
	v_add_f32_dpp v20, v20, v20 row_half_mirror row_mask:0xf bank_mask:0xf bound_ctrl:1
	s_nop 1
	v_add_f32_dpp v20, v20, v20 row_mirror row_mask:0xf bank_mask:0xf bound_ctrl:1
	v_fmamk_f32 v20, v20, 0x3c2aaaab, v130
	v_cmp_gt_f32_e32 vcc, s26, v20
	v_mul_f32_e32 v21, 0x4b800000, v20
	s_nop 0
	v_cndmask_b32_e32 v20, v20, v21, vcc
	v_rsq_f32_e32 v20, v20
	s_nop 0
	v_mul_f32_e32 v21, 0x45800000, v20
	v_cndmask_b32_e32 v22, v20, v21, vcc
	v_or_b32_e32 v20, s85, v18
	v_ashrrev_i32_e32 v21, 31, v20
	v_lshlrev_b64 v[20:21], 7, v[20:21]
	v_lshl_add_u64 v[20:21], v[50:51], 0, v[20:21]
	v_mov_b32_e32 v20, v166
	v_mov_b32_e32 v21, v167
	v_mul_f32_e32 v18, v31, v22
	v_mul_f32_e32 v18, v79, v18
	v_cvt_pk_bf16_f32 v18, v18, v129
	ds_write_b16 v63, v18 offset:51824
	v_mul_f32_e32 v18, v27, v22
	v_mul_f32_e32 v18, v78, v18
	v_cvt_pk_bf16_f32 v18, v18, v129
	ds_write_b16 v63, v18 offset:51856
	v_mul_f32_e32 v18, v23, v22
	v_mul_f32_e32 v18, v72, v18
	v_cvt_pk_bf16_f32 v18, v18, v129
	ds_write_b16 v63, v18 offset:51888
	v_mul_f32_e32 v18, v19, v22
	v_mul_f32_e32 v17, v17, v22
	v_mul_f32_e32 v18, v70, v18
	v_mul_f32_e32 v16, v16, v22
	v_cvt_pk_bf16_f32 v18, v18, v129
	v_mul_f32_e32 v17, v68, v17
	ds_write_b16 v63, v18 offset:51920
	v_mul_f32_e32 v16, v66, v16
	v_mov_b32_e32 v22, v0
	v_mov_b32_e32 v23, v4
	v_pk_mul_f32 v[22:23], v[22:23], v[22:23]
	s_waitcnt vmcnt(0)
	v_mul_f32_e32 v18, v21, v17
	v_fma_f32 v18, v20, v16, -v18
	v_mul_f32_e32 v16, v21, v16
	v_fmac_f32_e32 v16, v20, v17
	v_cvt_pk_bf16_f32 v18, v18, v129
	ds_write_b16 v63, v18 offset:51952
	v_cvt_pk_bf16_f32 v16, v16, v129
	ds_write_b16 v63, v16 offset:51984
	v_lshl_add_u32 v16, v24, 7, v58
	v_add_u32_e32 v16, 0xa800, v16
	ds_read2_b32 v[16:17], v16 offset1:16
	v_mov_b32_e32 v20, v8
	v_mov_b32_e32 v21, v12
	v_pk_mul_f32 v[20:21], v[20:21], v[20:21]
	s_waitcnt lgkmcnt(0)
	v_pk_mul_f32 v[18:19], v[16:17], v[16:17]
	s_nop 0
	v_add_f32_e32 v18, v18, v19
	v_add_f32_e32 v18, v21, v18
	v_add_f32_e32 v18, v20, v18
	v_add_f32_e32 v18, v23, v18
	v_add_f32_e32 v18, v22, v18
	s_nop 1
	v_add_f32_dpp v18, v18, v18 quad_perm:[1,0,3,2] row_mask:0xf bank_mask:0xf bound_ctrl:1
	s_nop 1
	v_add_f32_dpp v18, v18, v18 quad_perm:[2,3,0,1] row_mask:0xf bank_mask:0xf bound_ctrl:1
	s_nop 1
	v_add_f32_dpp v18, v18, v18 row_half_mirror row_mask:0xf bank_mask:0xf bound_ctrl:1
	s_nop 1
	v_add_f32_dpp v18, v18, v18 row_mirror row_mask:0xf bank_mask:0xf bound_ctrl:1
	v_fmamk_f32 v18, v18, 0x3c2aaaab, v130
	v_cmp_gt_f32_e32 vcc, s26, v18
	v_mul_f32_e32 v19, 0x4b800000, v18
	s_nop 0
	v_cndmask_b32_e32 v18, v18, v19, vcc
	v_rsq_f32_e32 v18, v18
	s_nop 0
	v_mul_f32_e32 v19, 0x45800000, v18
	v_cndmask_b32_e32 v20, v18, v19, vcc
	v_or_b32_e32 v18, s85, v24
	v_ashrrev_i32_e32 v19, 31, v18
	v_lshlrev_b64 v[18:19], 7, v[18:19]
	v_lshl_add_u64 v[18:19], v[50:51], 0, v[18:19]
	v_mov_b32_e32 v18, v168
	v_mov_b32_e32 v19, v169
	v_mul_f32_e32 v12, v12, v20
	v_mul_f32_e32 v8, v8, v20
	v_mul_f32_e32 v4, v4, v20
	v_mul_f32_e32 v12, v79, v12
	v_mul_f32_e32 v8, v78, v8
	v_mul_f32_e32 v4, v72, v4
	v_mul_f32_e32 v0, v0, v20
	v_mul_f32_e32 v17, v17, v20
	v_cvt_pk_bf16_f32 v12, v12, v129
	ds_write_b16 v63, v12 offset:54528
	v_cvt_pk_bf16_f32 v8, v8, v129
	ds_write_b16 v63, v8 offset:54560
	v_cvt_pk_bf16_f32 v4, v4, v129
	v_mul_f32_e32 v0, v70, v0
	v_mul_f32_e32 v16, v16, v20
	ds_write_b16 v63, v4 offset:54592
	v_cvt_pk_bf16_f32 v0, v0, v129
	v_mul_f32_e32 v4, v68, v17
	ds_write_b16 v63, v0 offset:54624
	v_mul_f32_e32 v0, v66, v16
	v_mov_b32_e32 v12, v9
	v_pk_mul_f32 v[20:21], v[12:13], v[12:13]
	s_waitcnt vmcnt(0)
	v_mul_f32_e32 v8, v19, v4
	v_fma_f32 v8, v18, v0, -v8
	v_mul_f32_e32 v0, v19, v0
	v_fmac_f32_e32 v0, v18, v4
	v_cvt_pk_bf16_f32 v8, v8, v129
	ds_write_b16 v63, v8 offset:54656
	v_cvt_pk_bf16_f32 v0, v0, v129
	ds_write_b16 v63, v0 offset:54688
	v_or_b32_e32 v0, 17, v80
	v_lshl_add_u32 v4, v0, 7, v58
	v_add_u32_e32 v4, 0xa800, v4
	ds_read2_b32 v[16:17], v4 offset1:16
	v_mov_b32_e32 v4, v1
	v_pk_mul_f32 v[22:23], v[4:5], v[4:5]
	s_waitcnt lgkmcnt(0)
	v_pk_mul_f32 v[18:19], v[16:17], v[16:17]
	s_nop 0
	v_add_f32_e32 v4, v18, v19
	v_or_b32_e32 v18, s85, v0
	v_ashrrev_i32_e32 v19, 31, v18
	v_lshlrev_b64 v[18:19], 7, v[18:19]
	v_lshl_add_u64 v[18:19], v[50:51], 0, v[18:19]
	v_mov_b32_e32 v18, v170
	v_mov_b32_e32 v19, v171
	v_add_f32_e32 v4, v21, v4
	v_add_f32_e32 v4, v20, v4
	v_add_f32_e32 v4, v23, v4
	v_add_f32_e32 v4, v22, v4
	s_nop 1
	v_add_f32_dpp v4, v4, v4 quad_perm:[1,0,3,2] row_mask:0xf bank_mask:0xf bound_ctrl:1
	s_nop 1
	v_add_f32_dpp v4, v4, v4 quad_perm:[2,3,0,1] row_mask:0xf bank_mask:0xf bound_ctrl:1
	s_nop 1
	v_add_f32_dpp v4, v4, v4 row_half_mirror row_mask:0xf bank_mask:0xf bound_ctrl:1
	s_nop 1
	v_add_f32_dpp v4, v4, v4 row_mirror row_mask:0xf bank_mask:0xf bound_ctrl:1
	v_fmamk_f32 v4, v4, 0x3c2aaaab, v130
	v_cmp_gt_f32_e32 vcc, s26, v4
	v_mul_f32_e32 v8, 0x4b800000, v4
	s_nop 0
	v_cndmask_b32_e32 v4, v4, v8, vcc
	v_rsq_f32_e32 v4, v4
	s_nop 0
	v_mul_f32_e32 v8, 0x45800000, v4
	v_cndmask_b32_e32 v4, v4, v8, vcc
	v_mul_f32_e32 v12, v13, v4
	v_mul_f32_e32 v9, v9, v4
	v_mul_f32_e32 v5, v5, v4
	v_mul_f32_e32 v1, v1, v4
	v_mul_f32_e32 v12, v79, v12
	v_mul_f32_e32 v9, v78, v9
	v_mul_f32_e32 v5, v72, v5
	v_mul_f32_e32 v1, v70, v1
	v_mul_f32_e32 v8, v17, v4
	v_cvt_pk_bf16_f32 v12, v12, v129
	ds_write_b16 v63, v12 offset:54736
	v_cvt_pk_bf16_f32 v9, v9, v129
	ds_write_b16 v63, v9 offset:54768
	v_cvt_pk_bf16_f32 v5, v5, v129
	ds_write_b16 v63, v5 offset:54800
	v_cvt_pk_bf16_f32 v1, v1, v129
	v_mul_f32_e32 v0, v16, v4
	ds_write_b16 v63, v1 offset:54832
	v_mul_f32_e32 v1, v68, v8
	v_mul_f32_e32 v0, v66, v0
	v_or_b32_e32 v16, 18, v80
	v_mov_b32_e32 v8, v10
	v_mov_b32_e32 v9, v14
	v_pk_mul_f32 v[8:9], v[8:9], v[8:9]
	v_mov_b32_e32 v12, v2
	v_mov_b32_e32 v13, v6
	v_pk_mul_f32 v[12:13], v[12:13], v[12:13]
	s_waitcnt vmcnt(0)
; DEVI u16 f2bf(float f) { return (u16)(cvtpk(f, 0.f) & 0xffffu); }
; DEVI void prepMLA_tile(const Params& p, int l, int g, int tile, char* lds) {
;     ...
;             for (int j = 0; j < 4; ++j) {
;               int rowi = (mh * 2 + mb) * 16 + l4 * 4 + j;
;               float x1 = kro[rowi * 32 + l15], x2 = kro[rowi * 32 + 16 + l15];
;               float ss = x1 * x1 + x2 * x2;
; #pragma unroll
;               for (int nb = 0; nb < 4; ++nb) ss += acc[mb][nb][j] * acc[mb][nb][j];
;               ss = rowreduce<16>(ss);
;               float rstd = rsqrtf(ss * (1.f / 96.f) + 1e-6f);
;               const float* cs = rope + ((size_t)(pos0 + rowi) * 16 + l15) * 2;
;               float c = cs[0], s = cs[1];
;               float a1 = x1 * rstd * wv[4], a2 = x2 * rstd * wv[5];
;               u16* kr = (u16*)(WS + (mb * 16 + l4 * 4 + j) * 208) + l15;
; #pragma unroll
;               for (int nb = 0; nb < 4; ++nb) kr[nb * 16] = f2bf(acc[mb][nb][j] * rstd * wv[nb]);
;               kr[64] = f2bf(a1 * c - a2 * s);
;               kr[80] = f2bf(a2 * c + a1 * s);
;             }
; #pragma unroll
;           for (int i = 0; i < 6; ++i) {
;             int c = lane + i * 64; int rr_ = c / 12, ch = c % 12;
;             *(u32x4*)(Kp + (size_t)(mh * 32 + rr_) * 96 + ch * 8) = *(const u32x4*)(WS + rr_ * 208 + ch * 16);
;           }
	v_mul_f32_e32 v4, v19, v1
	v_fma_f32 v4, v18, v0, -v4
	v_mul_f32_e32 v0, v19, v0
	v_fmac_f32_e32 v0, v18, v1
	v_cvt_pk_bf16_f32 v4, v4, v129
	ds_write_b16 v63, v4 offset:54864
	v_cvt_pk_bf16_f32 v0, v0, v129
	ds_write_b16 v63, v0 offset:54896
	v_lshl_add_u32 v0, v16, 7, v58
	v_add_u32_e32 v0, 0xa800, v0
	ds_read2_b32 v[0:1], v0 offset1:16
	s_waitcnt lgkmcnt(0)
	v_pk_mul_f32 v[4:5], v[0:1], v[0:1]
	s_nop 0
	v_add_f32_e32 v4, v4, v5
	v_add_f32_e32 v4, v9, v4
	v_add_f32_e32 v4, v8, v4
	v_add_f32_e32 v4, v13, v4
	v_add_f32_e32 v4, v12, v4
	s_nop 1
	v_add_f32_dpp v4, v4, v4 quad_perm:[1,0,3,2] row_mask:0xf bank_mask:0xf bound_ctrl:1
	s_nop 1
	v_add_f32_dpp v4, v4, v4 quad_perm:[2,3,0,1] row_mask:0xf bank_mask:0xf bound_ctrl:1
	s_nop 1
	v_add_f32_dpp v4, v4, v4 row_half_mirror row_mask:0xf bank_mask:0xf bound_ctrl:1
	s_nop 1
	v_add_f32_dpp v4, v4, v4 row_mirror row_mask:0xf bank_mask:0xf bound_ctrl:1
	v_fmamk_f32 v4, v4, 0x3c2aaaab, v130
	v_cmp_gt_f32_e32 vcc, s26, v4
	v_mul_f32_e32 v5, 0x4b800000, v4
	s_nop 0
	v_cndmask_b32_e32 v4, v4, v5, vcc
	v_rsq_f32_e32 v4, v4
	s_nop 0
	v_mul_f32_e32 v5, 0x45800000, v4
	v_cndmask_b32_e32 v8, v4, v5, vcc
	v_or_b32_e32 v4, s85, v16
	v_ashrrev_i32_e32 v5, 31, v4
	v_lshlrev_b64 v[4:5], 7, v[4:5]
	v_lshl_add_u64 v[4:5], v[50:51], 0, v[4:5]
	v_mov_b32_e32 v4, v172
	v_mov_b32_e32 v5, v173
	v_mul_f32_e32 v9, v14, v8
	v_mul_f32_e32 v9, v79, v9
	v_cvt_pk_bf16_f32 v9, v9, v129
	ds_write_b16 v63, v9 offset:54944
	v_mul_f32_e32 v9, v10, v8
	v_mul_f32_e32 v6, v6, v8
	v_mul_f32_e32 v2, v2, v8
	v_mul_f32_e32 v1, v1, v8
	v_mul_f32_e32 v9, v78, v9
	v_mul_f32_e32 v6, v72, v6
	v_mul_f32_e32 v2, v70, v2
	v_mul_f32_e32 v0, v0, v8
	v_cvt_pk_bf16_f32 v9, v9, v129
	ds_write_b16 v63, v9 offset:54976
	v_cvt_pk_bf16_f32 v6, v6, v129
	ds_write_b16 v63, v6 offset:55008
	v_cvt_pk_bf16_f32 v2, v2, v129
	v_mul_f32_e32 v1, v68, v1
	ds_write_b16 v63, v2 offset:55040
	v_mul_f32_e32 v0, v66, v0
	v_mov_b32_e32 v14, v11
	v_pk_mul_f32 v[8:9], v[14:15], v[14:15]
	v_mov_b32_e32 v6, v3
	v_pk_mul_f32 v[12:13], v[6:7], v[6:7]
	s_waitcnt vmcnt(0)
	v_mul_f32_e32 v2, v5, v1
	v_fma_f32 v2, v4, v0, -v2
	v_mul_f32_e32 v0, v5, v0
	v_cvt_pk_bf16_f32 v2, v2, v129
	v_fmac_f32_e32 v0, v4, v1
	ds_write_b16 v63, v2 offset:55072
	v_cvt_pk_bf16_f32 v0, v0, v129
	v_or_b32_e32 v2, 19, v80
	ds_write_b16 v63, v0 offset:55104
	v_lshl_add_u32 v0, v2, 7, v58
	v_add_u32_e32 v0, 0xa800, v0
	ds_read2_b32 v[0:1], v0 offset1:16
	s_waitcnt lgkmcnt(0)
	v_pk_mul_f32 v[4:5], v[0:1], v[0:1]
	s_nop 0
	v_add_f32_e32 v4, v4, v5
	v_add_f32_e32 v4, v9, v4
	v_add_f32_e32 v4, v8, v4
	v_add_f32_e32 v4, v13, v4
	v_add_f32_e32 v4, v12, v4
	s_nop 1
	v_add_f32_dpp v4, v4, v4 quad_perm:[1,0,3,2] row_mask:0xf bank_mask:0xf bound_ctrl:1
	s_nop 1
	v_add_f32_dpp v4, v4, v4 quad_perm:[2,3,0,1] row_mask:0xf bank_mask:0xf bound_ctrl:1
	s_nop 1
	v_add_f32_dpp v4, v4, v4 row_half_mirror row_mask:0xf bank_mask:0xf bound_ctrl:1
	s_nop 1
	v_add_f32_dpp v4, v4, v4 row_mirror row_mask:0xf bank_mask:0xf bound_ctrl:1
	v_fmamk_f32 v4, v4, 0x3c2aaaab, v130
	v_cmp_gt_f32_e32 vcc, s26, v4
	v_mul_f32_e32 v5, 0x4b800000, v4
	s_nop 0
	v_cndmask_b32_e32 v4, v4, v5, vcc
	v_rsq_f32_e32 v4, v4
	s_nop 0
	v_mul_f32_e32 v5, 0x45800000, v4
	v_cndmask_b32_e32 v6, v4, v5, vcc
	v_or_b32_e32 v4, s85, v2
	v_ashrrev_i32_e32 v5, 31, v4
	v_lshlrev_b64 v[4:5], 7, v[4:5]
	v_lshl_add_u64 v[4:5], v[50:51], 0, v[4:5]
	v_mov_b32_e32 v4, v174
	v_mov_b32_e32 v5, v175
	v_mul_f32_e32 v2, v15, v6
	v_mul_f32_e32 v2, v79, v2
	v_cvt_pk_bf16_f32 v2, v2, v129
	ds_write_b16 v63, v2 offset:55152
	v_mul_f32_e32 v2, v11, v6
	v_mul_f32_e32 v2, v78, v2
	v_cvt_pk_bf16_f32 v2, v2, v129
	ds_write_b16 v63, v2 offset:55184
	v_mul_f32_e32 v2, v7, v6
	v_mul_f32_e32 v2, v72, v2
	v_cvt_pk_bf16_f32 v2, v2, v129
	ds_write_b16 v63, v2 offset:55216
	v_mul_f32_e32 v2, v3, v6
	v_mul_f32_e32 v1, v1, v6
	v_mul_f32_e32 v2, v70, v2
	v_mul_f32_e32 v0, v0, v6
	v_cvt_pk_bf16_f32 v2, v2, v129
	v_mul_f32_e32 v1, v68, v1
	ds_write_b16 v63, v2 offset:55248
	v_mul_f32_e32 v0, v66, v0
	v_mov_b32_e32 v66, v94
	s_waitcnt vmcnt(0)
	v_mul_f32_e32 v2, v5, v1
	v_fma_f32 v2, v4, v0, -v2
	v_mul_f32_e32 v0, v5, v0
	v_fmac_f32_e32 v0, v4, v1
	v_cvt_pk_bf16_f32 v2, v2, v129
	ds_write_b16 v63, v2 offset:55280
	v_cvt_pk_bf16_f32 v0, v0, v129
	ds_write_b16 v63, v0 offset:55312
	ds_read_b128 v[0:3], v95 offset:51200
	v_or_b32_e32 v4, s17, v61
	v_mul_lo_u32 v128, v4, s22
	v_lshl_add_u64 v[4:5], v[128:129], 1, v[36:37]
	s_waitcnt lgkmcnt(0)
	global_store_dwordx4 v[4:5], v[0:3], off
	ds_read_b128 v[0:3], v96 offset:51200
	v_or_b32_e32 v4, s17, v65
	v_mul_lo_u32 v128, v4, s22
	v_lshl_add_u64 v[4:5], v[128:129], 1, v[38:39]
	s_waitcnt lgkmcnt(0)
	global_store_dwordx4 v[4:5], v[0:3], off
	ds_read_b128 v[0:3], v97 offset:51200
	v_or_b32_e32 v4, s17, v67
	v_mul_lo_u32 v128, v4, s22
	v_lshl_add_u64 v[4:5], v[128:129], 1, v[40:41]
	s_waitcnt lgkmcnt(0)
	global_store_dwordx4 v[4:5], v[0:3], off
	ds_read_b128 v[0:3], v98 offset:51200
	v_or_b32_e32 v4, s17, v69
	v_mul_lo_u32 v128, v4, s22
	v_lshl_add_u64 v[4:5], v[128:129], 1, v[42:43]
	s_waitcnt lgkmcnt(0)
	global_store_dwordx4 v[4:5], v[0:3], off
	ds_read_b128 v[0:3], v99 offset:51200
	v_or_b32_e32 v4, s17, v71
	v_mul_lo_u32 v128, v4, s22
	v_lshl_add_u64 v[4:5], v[128:129], 1, v[44:45]
	s_waitcnt lgkmcnt(0)
	global_store_dwordx4 v[4:5], v[0:3], off
	s_nop 1
	v_or_b32_e32 v0, s17, v73
	v_mul_lo_u32 v128, v0, s22
	s_branch .LBB0_790

; DEVI u16 f2bf(float f) { return (u16)(cvtpk(f, 0.f) & 0xffffu); }
; DEVI void prepSGU_tile(const Params& p, int l, int g, int tile, char* lds) {
;     ...
;   {
;     const float* lw = p.sgu_ln_w + l * 256; const float* lb = p.sgu_ln_b + l * 256;
; #pragma unroll 2
;     for (int i = 0; i < 16; ++i) {
;       int q = wid * 16 + i;
;       h16x4 z = *(const h16x4*)(Z + (size_t)q * NBC + 992 + lane * 4);
;       float x0 = (float)z[0], x1 = (float)z[1], x2 = (float)z[2], x3 = (float)z[3];
;       float mu = wave_sum(x0 + x1 + x2 + x3) * (1.f / 256.f);
;       float d0 = x0 - mu, d1 = x1 - mu, d2 = x2 - mu, d3 = x3 - mu;
;       float var = wave_sum(d0 * d0 + d1 * d1 + d2 * d2 + d3 * d3) * (1.f / 256.f);
;       float rstd = rsqrtf(var + 1e-6f);
;       int c = lane * 4;
;       *(u16*)(lds + (c + 0) * RS + q * 2) = f2bf(d0 * rstd * lw[c + 0] + lb[c + 0]);
;       *(u16*)(lds + (c + 1) * RS + q * 2) = f2bf(d1 * rstd * lw[c + 1] + lb[c + 1]);
;       *(u16*)(lds + (c + 2) * RS + q * 2) = f2bf(d2 * rstd * lw[c + 2] + lb[c + 2]);
;       *(u16*)(lds + (c + 3) * RS + q * 2) = f2bf(d3 * rstd * lw[c + 3] + lb[c + 3]);
;     }
;   }
.LBB0_798:
	s_cmpk_lt_i32 s12, 0x300
	s_cbranch_scc1 .LBB0_778
	v_mov_b32_e32 v6, v131
	v_readlane_b32 s0, v220, 61
	v_readlane_b32 s1, v220, 62
	s_waitcnt vmcnt(13)
	v_and_b32_e32 v64, 63, v6
	v_ashrrev_i32_e32 v4, 6, v6
	v_lshl_or_b32 v7, v64, 2, 1
	s_lshl_b64 s[0:1], s[0:1], 1
	v_lshlrev_b32_e32 v5, 4, v4
	v_mul_u32_u24_e32 v8, 0x440, v64
	v_mul_u32_u24_e32 v7, 0x110, v7
	v_lshlrev_b32_e32 v4, 5, v4
	v_add3_u32 v7, v7, v4, 16
	v_add3_u32 v8, v8, v4, 16
	v_mad_i64_i32 v[4:5], s[38:39], v5, s23, 0
	s_add_u32 s0, s84, s0
	v_readlane_b32 s17, v219, 63
	v_lshlrev_b32_e32 v128, 4, v64
	v_lshl_or_b32 v4, v64, 3, v4
	s_addc_u32 s1, s17, s1
	v_lshl_add_u64 v[0:1], s[8:9], 0, v[128:129]
	v_lshl_add_u64 v[2:3], s[82:83], 0, v[128:129]
	v_lshl_add_u64 v[4:5], s[0:1], 0, v[4:5]
	s_movk_i32 s0, 0xffe0
	global_load_dword v246, v[0:1], off
	global_load_dword v250, v[2:3], off
	global_load_dword v247, v[0:1], off offset:4
	global_load_dword v251, v[2:3], off offset:4
	global_load_dword v248, v[0:1], off offset:8
	global_load_dword v252, v[2:3], off offset:8
	global_load_dword v249, v[0:1], off offset:12
	global_load_dword v253, v[2:3], off offset:12
	global_load_dwordx2 v[242:243], v[4:5], off offset:-3008
	global_load_dwordx2 v[244:245], v[4:5], off
.LBB0_800:
	s_mov_b64 s[38:39], 0x1780
	s_waitcnt vmcnt(0)
	v_mov_b32_e32 v10, v242
	v_mov_b32_e32 v11, v243
	v_mov_b32_e32 v236, v244
	v_mov_b32_e32 v237, v245
	v_lshl_add_u64 v[4:5], v[4:5], 0, s[38:39]
	global_load_dwordx2 v[242:243], v[4:5], off offset:-3008
	global_load_dwordx2 v[244:245], v[4:5], off
	v_cvt_f32_f16_e32 v9, v10
	v_cvt_f32_f16_sdwa v12, v10 dst_sel:DWORD dst_unused:UNUSED_PAD src0_sel:WORD_1
	v_cvt_f32_f16_e32 v13, v11
	v_cvt_f32_f16_sdwa v14, v11 dst_sel:DWORD dst_unused:UNUSED_PAD src0_sel:WORD_1
	v_add_f32_e32 v9, v9, v12
	v_add_f32_e32 v9, v9, v13
	v_add_f32_e32 v9, v9, v14
	s_nop 1
	v_add_f32_dpp v9, v9, v9 quad_perm:[1,0,3,2] row_mask:0xf bank_mask:0xf bound_ctrl:1
	s_nop 1
	v_add_f32_dpp v9, v9, v9 quad_perm:[2,3,0,1] row_mask:0xf bank_mask:0xf bound_ctrl:1
	s_nop 1
	v_add_f32_dpp v9, v9, v9 row_half_mirror row_mask:0xf bank_mask:0xf bound_ctrl:1
	s_nop 1
	v_add_f32_dpp v9, v9, v9 row_mirror row_mask:0xf bank_mask:0xf bound_ctrl:1
	v_mov_b32_e32 v12, v9
	s_nop 1
	v_permlane16_swap_b32_e32 v9, v12
	v_add_f32_e32 v9, v9, v12
	v_mov_b32_e32 v12, v9
	s_nop 1
	v_permlane32_swap_b32_e32 v9, v12
	v_add_f32_e32 v9, v9, v12
	v_fma_mix_f32 v12, v9, s21, v10 op_sel_hi:[0,0,1]
	v_fma_mix_f32 v10, v9, s21, v10 op_sel:[0,0,1] op_sel_hi:[0,0,1]
	v_fma_mix_f32 v13, v9, s21, v11 op_sel_hi:[0,0,1]
	v_fma_mix_f32 v11, v9, s21, v11 op_sel:[0,0,1] op_sel_hi:[0,0,1]
	v_mul_f32_e32 v9, v10, v10
	v_fmac_f32_e32 v9, v12, v12
	v_fmac_f32_e32 v9, v13, v13
	v_fmac_f32_e32 v9, v11, v11
	s_nop 1
	v_add_f32_dpp v9, v9, v9 quad_perm:[1,0,3,2] row_mask:0xf bank_mask:0xf bound_ctrl:1
	s_nop 1
	v_add_f32_dpp v9, v9, v9 quad_perm:[2,3,0,1] row_mask:0xf bank_mask:0xf bound_ctrl:1
	s_nop 1
	v_add_f32_dpp v9, v9, v9 row_half_mirror row_mask:0xf bank_mask:0xf bound_ctrl:1
	s_nop 1
	v_add_f32_dpp v9, v9, v9 row_mirror row_mask:0xf bank_mask:0xf bound_ctrl:1
	v_mov_b32_e32 v14, v9
	s_nop 1
	v_permlane16_swap_b32_e32 v9, v14
	v_add_f32_e32 v9, v9, v14
	v_mov_b32_e32 v14, v9
	s_nop 1
	v_permlane32_swap_b32_e32 v9, v14
	v_add_f32_e32 v9, v9, v14
	v_fmamk_f32 v9, v9, 0x3b800000, v130
	v_cmp_gt_f32_e32 vcc, s26, v9
	v_mul_f32_e32 v14, 0x4b800000, v9
	s_nop 0
	v_cndmask_b32_e32 v9, v9, v14, vcc
	v_rsq_f32_e32 v9, v9
	s_nop 0
	v_mul_f32_e32 v14, 0x45800000, v9
	v_cndmask_b32_e32 v14, v9, v14, vcc
	v_mul_f32_e32 v9, v12, v14
	v_fma_f32 v15, v246, v9, v250
	v_add_u32_e32 v12, s0, v8
	v_cvt_pk_bf16_f32 v9, v15, v129
	ds_write_b16 v12, v9 offset:32
	v_mul_f32_e32 v9, v10, v14
	v_fma_f32 v15, v247, v9, v251
	v_add_u32_e32 v9, s0, v7
	v_cvt_pk_bf16_f32 v10, v15, v129
	ds_write_b16 v9, v10 offset:32
	v_mul_f32_e32 v10, v13, v14
	s_add_i32 s0, s0, 4
	s_cmp_eq_u32 s0, 0
	v_fma_f32 v15, v248, v10, v252
	v_cvt_pk_bf16_f32 v10, v15, v129
	ds_write_b16 v9, v10 offset:304
	v_mul_f32_e32 v10, v11, v14
	v_fma_f32 v13, v249, v10, v253
	v_cvt_pk_bf16_f32 v10, v13, v129
	ds_write_b16 v9, v10 offset:576
	v_cvt_f32_f16_e32 v13, v236
	v_cvt_f32_f16_sdwa v14, v236 dst_sel:DWORD dst_unused:UNUSED_PAD src0_sel:WORD_1
	v_cvt_f32_f16_e32 v15, v237
	v_cvt_f32_f16_sdwa v16, v237 dst_sel:DWORD dst_unused:UNUSED_PAD src0_sel:WORD_1
	v_add_f32_e32 v13, v13, v14
	v_add_f32_e32 v13, v13, v15
	v_add_f32_e32 v13, v13, v16
	s_nop 1
	v_add_f32_dpp v13, v13, v13 quad_perm:[1,0,3,2] row_mask:0xf bank_mask:0xf bound_ctrl:1
	s_nop 1
	v_add_f32_dpp v13, v13, v13 quad_perm:[2,3,0,1] row_mask:0xf bank_mask:0xf bound_ctrl:1
	s_nop 1
	v_add_f32_dpp v13, v13, v13 row_half_mirror row_mask:0xf bank_mask:0xf bound_ctrl:1
	s_nop 1
	v_add_f32_dpp v13, v13, v13 row_mirror row_mask:0xf bank_mask:0xf bound_ctrl:1
	v_mov_b32_e32 v14, v13
	s_nop 1
	v_permlane16_swap_b32_e32 v13, v14
	v_add_f32_e32 v13, v13, v14
	v_mov_b32_e32 v14, v13
	s_nop 1
	v_permlane32_swap_b32_e32 v13, v14
	v_add_f32_e32 v13, v13, v14
	v_fma_mix_f32 v14, v13, s21, v236 op_sel_hi:[0,0,1]
	v_fma_mix_f32 v10, v13, s21, v236 op_sel:[0,0,1] op_sel_hi:[0,0,1]
	v_fma_mix_f32 v15, v13, s21, v237 op_sel_hi:[0,0,1]
	v_fma_mix_f32 v11, v13, s21, v237 op_sel:[0,0,1] op_sel_hi:[0,0,1]
	v_mul_f32_e32 v13, v10, v10
	v_fmac_f32_e32 v13, v14, v14
	v_fmac_f32_e32 v13, v15, v15
	v_fmac_f32_e32 v13, v11, v11
	s_nop 1
	v_add_f32_dpp v13, v13, v13 quad_perm:[1,0,3,2] row_mask:0xf bank_mask:0xf bound_ctrl:1
	s_nop 1
	v_add_f32_dpp v13, v13, v13 quad_perm:[2,3,0,1] row_mask:0xf bank_mask:0xf bound_ctrl:1
	s_nop 1
	v_add_f32_dpp v13, v13, v13 row_half_mirror row_mask:0xf bank_mask:0xf bound_ctrl:1
	s_nop 1
	v_add_f32_dpp v13, v13, v13 row_mirror row_mask:0xf bank_mask:0xf bound_ctrl:1
	v_mov_b32_e32 v16, v13
	s_nop 1
	v_permlane16_swap_b32_e32 v13, v16
	v_add_f32_e32 v13, v13, v16
	v_mov_b32_e32 v16, v13
	s_nop 1
	v_permlane32_swap_b32_e32 v13, v16
	v_add_f32_e32 v13, v13, v16
	v_fmamk_f32 v13, v13, 0x3b800000, v130
	v_cmp_gt_f32_e32 vcc, s26, v13
	v_mul_f32_e32 v16, 0x4b800000, v13
	s_nop 0
	v_cndmask_b32_e32 v13, v13, v16, vcc
	v_rsq_f32_e32 v13, v13
	s_nop 0
	v_mul_f32_e32 v16, 0x45800000, v13
	v_cndmask_b32_e32 v13, v13, v16, vcc
	v_mul_f32_e32 v14, v14, v13
	v_mul_f32_e32 v10, v10, v13
	v_fma_f32 v17, v246, v14, v250
	v_cvt_pk_bf16_f32 v14, v17, v129
	ds_write_b16 v12, v14 offset:34
	v_fma_f32 v14, v247, v10, v251
	v_cvt_pk_bf16_f32 v10, v14, v129
	ds_write_b16 v9, v10 offset:34
	v_mul_f32_e32 v10, v15, v13
	v_fma_f32 v14, v248, v10, v252
	v_cvt_pk_bf16_f32 v10, v14, v129
	ds_write_b16 v9, v10 offset:306
	v_mul_f32_e32 v10, v11, v13
	v_fma_f32 v12, v249, v10, v253
	v_cvt_pk_bf16_f32 v10, v12, v129
	ds_write_b16 v9, v10 offset:578
	s_cbranch_scc0 .LBB0_800
; DEVI void prepSGU_tile(const Params& p, int l, int g, int tile, char* lds) {
;     ...
;   {
;     const int gi = wid >> 1, mh = wid & 1;
;     const u16* Ws = (const u16*)(p.ws + OFF_WS) + ((size_t)l * 4 + gi) * 128 * 128;
;     f32x4 acc[4][4];
; #pragma unroll
;     for (int mb = 0; mb < 4; ++mb)
; #pragma unroll
;       for (int nb = 0; nb < 4; ++nb) acc[mb][nb] = (f32x4){0.f, 0.f, 0.f, 0.f};
; #pragma unroll 1
;     for (int ks = 0; ks < 4; ++ks) {
;       bf16x8 bfr[4];
; #pragma unroll
;       for (int nb = 0; nb < 4; ++nb) bfr[nb] = *(const bf16x8*)(lds + (gi * 64 + nb * 16 + l15) * RS + ks * 64 + l4 * 16);
; #pragma unroll
;       for (int mb = 0; mb < 4; ++mb) {
;         bf16x8 a = *(const bf16x8*)(Ws + (size_t)(mh * 64 + mb * 16 + l15) * 128 + ks * 32 + l4 * 8);
; #pragma unroll
;         for (int nb = 0; nb < 4; ++nb) acc[mb][nb] = __builtin_amdgcn_mfma_f32_16x16x32_bf16(a, bfr[nb], acc[mb][nb], 0, 0, 0);
;       }
;     }
	v_ashrrev_i32_e32 v66, 7, v6
	v_and_b32_e32 v70, 15, v6
	v_ashrrev_i32_e32 v67, 31, v66
	v_bfe_u32 v65, v6, 6, 1
	v_lshlrev_b32_e32 v4, 8, v70
	v_lshlrev_b64 v[0:1], 15, v[66:67]
	v_and_b32_e32 v3, 48, v64
	v_lshl_or_b32 v4, v65, 14, v4
	v_or3_b32 v0, v0, v3, v4
	s_movk_i32 s0, 0x4400
	v_lshl_add_u64 v[68:69], s[18:19], 0, v[0:1]
	v_mul_lo_u32 v0, v66, s0
	v_and_b32_e32 v2, 48, v6
	v_mad_u32_u24 v0, v70, s27, v0
	v_mov_b32_e32 v16, 0
	v_add3_u32 v71, v0, v2, 16
	s_mov_b64 s[0:1], 0
	v_mov_b32_e32 v17, v16
	v_mov_b32_e32 v18, v16
	v_mov_b32_e32 v19, v16
	v_mov_b32_e32 v20, v16
	v_mov_b32_e32 v21, v16
	v_mov_b32_e32 v22, v16
	v_mov_b32_e32 v23, v16
	v_mov_b32_e32 v24, v16
	v_mov_b32_e32 v25, v16
	v_mov_b32_e32 v26, v16
	v_mov_b32_e32 v27, v16
	v_mov_b32_e32 v28, v16
	v_mov_b32_e32 v29, v16
	v_mov_b32_e32 v30, v16
	v_mov_b32_e32 v31, v16
	v_mov_b32_e32 v32, v16
	v_mov_b32_e32 v33, v16
	v_mov_b32_e32 v34, v16
	v_mov_b32_e32 v35, v16
	v_mov_b32_e32 v36, v16
	v_mov_b32_e32 v37, v16
	v_mov_b32_e32 v38, v16
	v_mov_b32_e32 v39, v16
	v_mov_b32_e32 v40, v16
	v_mov_b32_e32 v41, v16
	v_mov_b32_e32 v42, v16
	v_mov_b32_e32 v43, v16
	v_mov_b32_e32 v44, v16
	v_mov_b32_e32 v45, v16
	v_mov_b32_e32 v46, v16
	v_mov_b32_e32 v47, v16
	v_mov_b32_e32 v48, v16
	v_mov_b32_e32 v49, v16
	v_mov_b32_e32 v50, v16
	v_mov_b32_e32 v51, v16
	v_mov_b32_e32 v52, v16
	v_mov_b32_e32 v53, v16
	v_mov_b32_e32 v54, v16
	v_mov_b32_e32 v55, v16
	v_mov_b32_e32 v56, v16
	v_mov_b32_e32 v57, v16
	v_mov_b32_e32 v58, v16
	v_mov_b32_e32 v59, v16
	v_mov_b32_e32 v60, v16
	v_mov_b32_e32 v61, v16
	v_mov_b32_e32 v62, v16
	v_mov_b32_e32 v63, v16
	v_mov_b32_e32 v12, v16
	v_mov_b32_e32 v13, v16
	v_mov_b32_e32 v14, v16
	v_mov_b32_e32 v15, v16
	v_mov_b32_e32 v8, v16
	v_mov_b32_e32 v9, v16
	v_mov_b32_e32 v10, v16
	v_mov_b32_e32 v11, v16
	v_mov_b32_e32 v4, v16
	v_mov_b32_e32 v5, v16
	v_mov_b32_e32 v6, v16
	v_mov_b32_e32 v7, v16
	v_mov_b32_e32 v0, v16
	v_mov_b32_e32 v1, v16
	v_mov_b32_e32 v2, v16
	v_mov_b32_e32 v3, v16
	s_waitcnt lgkmcnt(0)
	s_barrier
	v_add_co_u32_e32 v238, vcc, 0x2459000, v68
	s_nop 1
	v_addc_co_u32_e32 v239, vcc, 0, v69, vcc
	v_add_co_u32_e32 v240, vcc, 0x245b000, v68
	s_nop 1
	v_addc_co_u32_e32 v241, vcc, 0, v69, vcc
	global_load_dwordx4 v[162:165], v[238:239], off offset:-4096
	global_load_dwordx4 v[166:169], v[238:239], off
	global_load_dwordx4 v[170:173], v[240:241], off offset:-4096
	global_load_dwordx4 v[174:177], v[240:241], off
	global_load_dwordx4 v[178:181], v[238:239], off offset:-4032
	global_load_dwordx4 v[182:185], v[238:239], off offset:64
	global_load_dwordx4 v[186:189], v[240:241], off offset:-4032
	global_load_dwordx4 v[190:193], v[240:241], off offset:64
	global_load_dwordx4 v[194:197], v[238:239], off offset:-3968
	global_load_dwordx4 v[198:201], v[238:239], off offset:128
	global_load_dwordx4 v[202:205], v[240:241], off offset:-3968
	global_load_dwordx4 v[206:209], v[240:241], off offset:128
	global_load_dwordx4 v[210:213], v[238:239], off offset:-3904
	global_load_dwordx4 v[214:217], v[238:239], off offset:192
	global_load_dwordx4 v[222:225], v[240:241], off offset:-3904
	global_load_dwordx4 v[226:229], v[240:241], off offset:192
	ds_read_b128 v[72:75], v71
	ds_read_b128 v[76:79], v71 offset:4352
	ds_read_b128 v[80:83], v71 offset:8704
	ds_read_b128 v[84:87], v71 offset:13056
	s_waitcnt vmcnt(15) lgkmcnt(0)
	v_mfma_f32_16x16x32_bf16 v[60:63], v[162:165], v[72:75], v[60:63]
	v_mfma_f32_16x16x32_bf16 v[56:59], v[162:165], v[76:79], v[56:59]
	v_mfma_f32_16x16x32_bf16 v[52:55], v[162:165], v[80:83], v[52:55]
	v_mfma_f32_16x16x32_bf16 v[48:51], v[162:165], v[84:87], v[48:51]
	s_waitcnt vmcnt(14)
	v_mfma_f32_16x16x32_bf16 v[44:47], v[166:169], v[72:75], v[44:47]
	v_mfma_f32_16x16x32_bf16 v[40:43], v[166:169], v[76:79], v[40:43]
	v_mfma_f32_16x16x32_bf16 v[36:39], v[166:169], v[80:83], v[36:39]
	v_mfma_f32_16x16x32_bf16 v[32:35], v[166:169], v[84:87], v[32:35]
	s_waitcnt vmcnt(13)
	v_mfma_f32_16x16x32_bf16 v[28:31], v[170:173], v[72:75], v[28:31]
	v_mfma_f32_16x16x32_bf16 v[24:27], v[170:173], v[76:79], v[24:27]
	v_mfma_f32_16x16x32_bf16 v[20:23], v[170:173], v[80:83], v[20:23]
	v_mfma_f32_16x16x32_bf16 v[16:19], v[170:173], v[84:87], v[16:19]
	s_waitcnt vmcnt(12)
	v_mfma_f32_16x16x32_bf16 v[12:15], v[174:177], v[72:75], v[12:15]
	v_mfma_f32_16x16x32_bf16 v[8:11], v[174:177], v[76:79], v[8:11]
	v_mfma_f32_16x16x32_bf16 v[4:7], v[174:177], v[80:83], v[4:7]
	v_mfma_f32_16x16x32_bf16 v[0:3], v[174:177], v[84:87], v[0:3]
	ds_read_b128 v[72:75], v71 offset:64
	ds_read_b128 v[76:79], v71 offset:4416
	ds_read_b128 v[80:83], v71 offset:8768
	ds_read_b128 v[84:87], v71 offset:13120
	s_waitcnt vmcnt(11) lgkmcnt(0)
	v_mfma_f32_16x16x32_bf16 v[60:63], v[178:181], v[72:75], v[60:63]
	v_mfma_f32_16x16x32_bf16 v[56:59], v[178:181], v[76:79], v[56:59]
	v_mfma_f32_16x16x32_bf16 v[52:55], v[178:181], v[80:83], v[52:55]
	v_mfma_f32_16x16x32_bf16 v[48:51], v[178:181], v[84:87], v[48:51]
	s_waitcnt vmcnt(10)
	v_mfma_f32_16x16x32_bf16 v[44:47], v[182:185], v[72:75], v[44:47]
	v_mfma_f32_16x16x32_bf16 v[40:43], v[182:185], v[76:79], v[40:43]
	v_mfma_f32_16x16x32_bf16 v[36:39], v[182:185], v[80:83], v[36:39]
	v_mfma_f32_16x16x32_bf16 v[32:35], v[182:185], v[84:87], v[32:35]
	s_waitcnt vmcnt(9)
	v_mfma_f32_16x16x32_bf16 v[28:31], v[186:189], v[72:75], v[28:31]
	v_mfma_f32_16x16x32_bf16 v[24:27], v[186:189], v[76:79], v[24:27]
	v_mfma_f32_16x16x32_bf16 v[20:23], v[186:189], v[80:83], v[20:23]
	v_mfma_f32_16x16x32_bf16 v[16:19], v[186:189], v[84:87], v[16:19]
	s_waitcnt vmcnt(8)
; DEVI u16 f2bf(float f) { return (u16)(cvtpk(f, 0.f) & 0xffffu); }
; DEVI float siluf_(float x) { return x / (1.f + __expf(-x)); }
; DEVI void prepSGU_tile(const Params& p, int l, int g, int tile, char* lds) {
;     ...
; #pragma unroll 1
;     for (int ks = 0; ks < 4; ++ks) {
;       bf16x8 bfr[4];
; #pragma unroll
;       for (int nb = 0; nb < 4; ++nb) bfr[nb] = *(const bf16x8*)(lds + (gi * 64 + nb * 16 + l15) * RS + ks * 64 + l4 * 16);
; #pragma unroll
;       for (int mb = 0; mb < 4; ++mb) {
;         bf16x8 a = *(const bf16x8*)(Ws + (size_t)(mh * 64 + mb * 16 + l15) * 128 + ks * 32 + l4 * 8);
; #pragma unroll
;         for (int nb = 0; nb < 4; ++nb) acc[mb][nb] = __builtin_amdgcn_mfma_f32_16x16x32_bf16(a, bfr[nb], acc[mb][nb], 0, 0, 0);
;       }
;     }
;     const float* bs = p.b_s + ((size_t)l * 4 + gi) * 128;
;     u16* Yc = (u16*)(p.ws + OFF_YC);
; #pragma unroll
;     for (int mb = 0; mb < 4; ++mb)
; #pragma unroll
;       for (int j = 0; j < 4; ++j) {
;         int pp = mh * 64 + mb * 16 + l4 * 4 + j; float bv = bs[pp];
;         const h16* zr = Z + (size_t)pp * NBC;
; #pragma unroll
;         for (int nb = 0; nb < 4; ++nb) {
;           int c = gi * 64 + nb * 16 + l15;
;           float u = (float)zr[736 + c], gc = (float)zr[1248 + c];
;           Yc[(size_t)(t0 + pp) * 256 + c] = f2bf(u * (acc[mb][nb][j] + bv) * siluf_(gc));
;         }
;       }
	v_mfma_f32_16x16x32_bf16 v[12:15], v[190:193], v[72:75], v[12:15]
	v_mfma_f32_16x16x32_bf16 v[8:11], v[190:193], v[76:79], v[8:11]
	v_mfma_f32_16x16x32_bf16 v[4:7], v[190:193], v[80:83], v[4:7]
	v_mfma_f32_16x16x32_bf16 v[0:3], v[190:193], v[84:87], v[0:3]
	ds_read_b128 v[72:75], v71 offset:128
	ds_read_b128 v[76:79], v71 offset:4480
	ds_read_b128 v[80:83], v71 offset:8832
	ds_read_b128 v[84:87], v71 offset:13184
	s_waitcnt vmcnt(7) lgkmcnt(0)
	v_mfma_f32_16x16x32_bf16 v[60:63], v[194:197], v[72:75], v[60:63]
	v_mfma_f32_16x16x32_bf16 v[56:59], v[194:197], v[76:79], v[56:59]
	v_mfma_f32_16x16x32_bf16 v[52:55], v[194:197], v[80:83], v[52:55]
	v_mfma_f32_16x16x32_bf16 v[48:51], v[194:197], v[84:87], v[48:51]
	s_waitcnt vmcnt(6)
	v_mfma_f32_16x16x32_bf16 v[44:47], v[198:201], v[72:75], v[44:47]
	v_mfma_f32_16x16x32_bf16 v[40:43], v[198:201], v[76:79], v[40:43]
	v_mfma_f32_16x16x32_bf16 v[36:39], v[198:201], v[80:83], v[36:39]
	v_mfma_f32_16x16x32_bf16 v[32:35], v[198:201], v[84:87], v[32:35]
	s_waitcnt vmcnt(5)
	v_mfma_f32_16x16x32_bf16 v[28:31], v[202:205], v[72:75], v[28:31]
	v_mfma_f32_16x16x32_bf16 v[24:27], v[202:205], v[76:79], v[24:27]
	v_mfma_f32_16x16x32_bf16 v[20:23], v[202:205], v[80:83], v[20:23]
	v_mfma_f32_16x16x32_bf16 v[16:19], v[202:205], v[84:87], v[16:19]
	s_waitcnt vmcnt(4)
	v_mfma_f32_16x16x32_bf16 v[12:15], v[206:209], v[72:75], v[12:15]
	v_mfma_f32_16x16x32_bf16 v[8:11], v[206:209], v[76:79], v[8:11]
	v_mfma_f32_16x16x32_bf16 v[4:7], v[206:209], v[80:83], v[4:7]
	v_mfma_f32_16x16x32_bf16 v[0:3], v[206:209], v[84:87], v[0:3]
	ds_read_b128 v[72:75], v71 offset:192
	ds_read_b128 v[76:79], v71 offset:4544
	ds_read_b128 v[80:83], v71 offset:8896
	ds_read_b128 v[84:87], v71 offset:13248
	s_waitcnt vmcnt(3) lgkmcnt(0)
	v_mfma_f32_16x16x32_bf16 v[60:63], v[210:213], v[72:75], v[60:63]
	v_mfma_f32_16x16x32_bf16 v[56:59], v[210:213], v[76:79], v[56:59]
	v_mfma_f32_16x16x32_bf16 v[52:55], v[210:213], v[80:83], v[52:55]
	v_mfma_f32_16x16x32_bf16 v[48:51], v[210:213], v[84:87], v[48:51]
	s_waitcnt vmcnt(2)
	v_mfma_f32_16x16x32_bf16 v[44:47], v[214:217], v[72:75], v[44:47]
	v_mfma_f32_16x16x32_bf16 v[40:43], v[214:217], v[76:79], v[40:43]
	v_mfma_f32_16x16x32_bf16 v[36:39], v[214:217], v[80:83], v[36:39]
	v_mfma_f32_16x16x32_bf16 v[32:35], v[214:217], v[84:87], v[32:35]
	s_waitcnt vmcnt(1)
	v_mfma_f32_16x16x32_bf16 v[28:31], v[222:225], v[72:75], v[28:31]
	v_mfma_f32_16x16x32_bf16 v[24:27], v[222:225], v[76:79], v[24:27]
	v_mfma_f32_16x16x32_bf16 v[20:23], v[222:225], v[80:83], v[20:23]
	v_mfma_f32_16x16x32_bf16 v[16:19], v[222:225], v[84:87], v[16:19]
	s_waitcnt vmcnt(0)
	v_mfma_f32_16x16x32_bf16 v[12:15], v[226:229], v[72:75], v[12:15]
	v_mfma_f32_16x16x32_bf16 v[8:11], v[226:229], v[76:79], v[8:11]
	v_mfma_f32_16x16x32_bf16 v[4:7], v[226:229], v[80:83], v[4:7]
	v_mfma_f32_16x16x32_bf16 v[0:3], v[226:229], v[84:87], v[0:3]
	v_readlane_b32 s38, v220, 61
	s_add_i32 s17, s12, 0xfffffd00
	v_readlane_b32 s39, v220, 62
	s_mul_i32 s0, s17, 0x2f000
	s_mov_b32 s1, s39
	s_lshl_b64 s[0:1], s[0:1], 1
	s_add_u32 s0, s14, s0
	v_lshrrev_b32_e32 v64, 2, v64
	v_lshl_or_b32 v72, v66, 6, v70
	s_addc_u32 s1, s15, s1
	v_and_b32_e32 v64, 12, v64
	v_lshl_or_b32 v70, v65, 6, v64
	v_ashrrev_i32_e32 v73, 31, v72
	v_mov_b64_e32 v[68:69], s[0:1]
	v_mad_u64_u32 v[74:75], s[0:1], v70, s23, v[68:69]
	v_lshlrev_b64 v[64:65], 1, v[72:73]
	v_lshl_add_u64 v[72:73], v[74:75], 0, v[64:65]
	v_lshlrev_b64 v[66:67], 7, v[66:67]
	v_readlane_b32 s40, v221, 11
	v_lshl_add_u64 v[66:67], v[66:67], 0, s[62:63]
	v_readlane_b32 s46, v221, 17
	v_readlane_b32 s47, v221, 18
	v_lshlrev_b32_e32 v128, 2, v70
	v_readlane_b32 s41, v221, 12
	v_lshl_add_u64 v[66:67], v[66:67], 2, s[46:47]
	v_lshl_add_u64 v[66:67], v[66:67], 0, v[128:129]
	v_readlane_b32 s42, v221, 13
	v_readlane_b32 s43, v221, 14
	v_readlane_b32 s44, v221, 15
	v_readlane_b32 s45, v221, 16
	s_lshl_b32 s0, s17, 7
	s_add_i32 s0, s0, s13
	v_mov_b32_e32 v238, v72
	v_mov_b32_e32 v239, v73
	v_add_co_u32_e32 v240, vcc, 0xbc0, v72
	s_nop 1
	v_addc_co_u32_e32 v241, vcc, 0, v73, vcc
	v_add_co_u32_e32 v242, vcc, 0x1780, v72
	s_nop 1
	v_addc_co_u32_e32 v243, vcc, 0, v73, vcc
	v_add_co_u32_e32 v244, vcc, 0x2340, v72
	s_nop 1
	v_addc_co_u32_e32 v245, vcc, 0, v73, vcc
	global_load_ushort v162, v[238:239], off offset:2496
	global_load_ushort v163, v[238:239], off offset:1472
	global_load_ushort v164, v[238:239], off offset:2528
	global_load_ushort v165, v[238:239], off offset:1504
	global_load_ushort v166, v[238:239], off offset:2560
	global_load_ushort v167, v[238:239], off offset:1536
	global_load_ushort v168, v[238:239], off offset:2592
	global_load_ushort v169, v[238:239], off offset:1568
	global_load_ushort v170, v[240:241], off offset:2496
	global_load_ushort v171, v[240:241], off offset:1472
	global_load_ushort v172, v[240:241], off offset:2528
	global_load_ushort v173, v[240:241], off offset:1504
	global_load_ushort v174, v[240:241], off offset:2560
	global_load_ushort v175, v[240:241], off offset:1536
	global_load_ushort v176, v[240:241], off offset:2592
	global_load_ushort v177, v[240:241], off offset:1568
	global_load_ushort v178, v[242:243], off offset:2496
	global_load_ushort v179, v[242:243], off offset:1472
	global_load_ushort v180, v[242:243], off offset:2528
	global_load_ushort v181, v[242:243], off offset:1504
	global_load_ushort v182, v[242:243], off offset:2560
	global_load_ushort v183, v[242:243], off offset:1536
	global_load_ushort v184, v[242:243], off offset:2592
	global_load_ushort v185, v[242:243], off offset:1568
	global_load_ushort v186, v[244:245], off offset:2496
	global_load_ushort v187, v[244:245], off offset:1472
; DEVI u16 f2bf(float f) { return (u16)(cvtpk(f, 0.f) & 0xffffu); }
; DEVI float siluf_(float x) { return x / (1.f + __expf(-x)); }
; DEVI void prepSGU_tile(const Params& p, int l, int g, int tile, char* lds) {
;     ...
; #pragma unroll
;     for (int mb = 0; mb < 4; ++mb)
; #pragma unroll
;       for (int j = 0; j < 4; ++j) {
;         int pp = mh * 64 + mb * 16 + l4 * 4 + j; float bv = bs[pp];
;         const h16* zr = Z + (size_t)pp * NBC;
; #pragma unroll
;         for (int nb = 0; nb < 4; ++nb) {
;           int c = gi * 64 + nb * 16 + l15;
;           float u = (float)zr[736 + c], gc = (float)zr[1248 + c];
;           Yc[(size_t)(t0 + pp) * 256 + c] = f2bf(u * (acc[mb][nb][j] + bv) * siluf_(gc));
;         }
;       }
	global_load_ushort v188, v[244:245], off offset:2528
	global_load_ushort v189, v[244:245], off offset:1504
	global_load_ushort v190, v[244:245], off offset:2560
	global_load_ushort v191, v[244:245], off offset:1536
	global_load_ushort v192, v[244:245], off offset:2592
	global_load_ushort v193, v[244:245], off offset:1568
	global_load_dword v194, v[66:67], off
	global_load_dword v195, v[66:67], off offset:4
	global_load_dword v196, v[66:67], off offset:8
	global_load_dword v197, v[66:67], off offset:12
	v_add_co_u32_e32 v238, vcc, 0xbc00, v72
	s_nop 1
	v_addc_co_u32_e32 v239, vcc, 0, v73, vcc
	v_add_co_u32_e32 v240, vcc, 0xc7c0, v72
	s_nop 1
	v_addc_co_u32_e32 v241, vcc, 0, v73, vcc
	v_add_co_u32_e32 v242, vcc, 0xd380, v72
	s_nop 1
	v_addc_co_u32_e32 v243, vcc, 0, v73, vcc
	v_add_co_u32_e32 v244, vcc, 0xdf40, v72
	s_nop 1
	v_addc_co_u32_e32 v245, vcc, 0, v73, vcc
	global_load_ushort v198, v[238:239], off offset:2496
	global_load_ushort v199, v[238:239], off offset:1472
	global_load_ushort v200, v[238:239], off offset:2528
	global_load_ushort v201, v[238:239], off offset:1504
	global_load_ushort v202, v[238:239], off offset:2560
	global_load_ushort v203, v[238:239], off offset:1536
	global_load_ushort v204, v[238:239], off offset:2592
	global_load_ushort v205, v[238:239], off offset:1568
	global_load_ushort v206, v[240:241], off offset:2496
	global_load_ushort v207, v[240:241], off offset:1472
	global_load_ushort v208, v[240:241], off offset:2528
	global_load_ushort v209, v[240:241], off offset:1504
	global_load_ushort v210, v[240:241], off offset:2560
	global_load_ushort v211, v[240:241], off offset:1536
	global_load_ushort v212, v[240:241], off offset:2592
	global_load_ushort v213, v[240:241], off offset:1568
	global_load_ushort v214, v[242:243], off offset:2496
	global_load_ushort v215, v[242:243], off offset:1472
	global_load_ushort v216, v[242:243], off offset:2528
	global_load_ushort v217, v[242:243], off offset:1504
	global_load_ushort v222, v[242:243], off offset:2560
	global_load_ushort v223, v[242:243], off offset:1536
	global_load_ushort v224, v[242:243], off offset:2592
	global_load_ushort v225, v[242:243], off offset:1568
	global_load_ushort v226, v[244:245], off offset:2496
	global_load_ushort v227, v[244:245], off offset:1472
	global_load_ushort v228, v[244:245], off offset:2528
	global_load_ushort v229, v[244:245], off offset:1504
	global_load_ushort v230, v[244:245], off offset:2560
	global_load_ushort v231, v[244:245], off offset:1536
	global_load_ushort v232, v[244:245], off offset:2592
	global_load_ushort v233, v[244:245], off offset:1568
	global_load_dword v234, v[66:67], off offset:64
	global_load_dword v235, v[66:67], off offset:68
	global_load_dword v236, v[66:67], off offset:72
	global_load_dword v237, v[66:67], off offset:76
	s_waitcnt vmcnt(36)
	v_or_b32_e32 v128, s0, v70
	v_lshlrev_b64 v[74:75], 9, v[128:129]
	v_lshl_add_u64 v[74:75], s[28:29], 0, v[74:75]
	v_lshl_add_u64 v[74:75], v[74:75], 0, v[64:65]
	v_cvt_f32_f16_e32 v246, v162
	v_cvt_f32_f16_e32 v247, v163
	v_mul_f32_e32 v248, 0xbfb8aa3b, v246
	v_exp_f32_e32 v248, v248
	v_add_f32_e32 v60, v60, v194
	v_add_f32_e32 v248, 1.0, v248
	v_div_scale_f32 v249, s[38:39], v248, v248, v246
	v_rcp_f32_e32 v250, v249
	v_mul_f32_e32 v60, v60, v247
	v_div_scale_f32 v251, vcc, v246, v248, v246
	v_fma_f32 v252, -v249, v250, 1.0
	v_fmac_f32_e32 v250, v252, v250
	v_mul_f32_e32 v252, v251, v250
	v_fma_f32 v253, -v249, v252, v251
	v_fmac_f32_e32 v252, v253, v250
	v_fma_f32 v251, -v249, v252, v251
	v_div_fmas_f32 v251, v251, v250, v252
	v_div_fixup_f32 v251, v251, v248, v246
	v_mul_f32_e32 v60, v60, v251
	v_cvt_pk_bf16_f32 v60, v60, v129
	global_store_short v[74:75], v60, off
	v_cvt_f32_f16_e32 v246, v164
	v_cvt_f32_f16_e32 v247, v165
	v_mul_f32_e32 v248, 0xbfb8aa3b, v246
	v_exp_f32_e32 v248, v248
	v_add_f32_e32 v56, v56, v194
	v_add_f32_e32 v248, 1.0, v248
	v_div_scale_f32 v249, s[38:39], v248, v248, v246
	v_rcp_f32_e32 v250, v249
	v_mul_f32_e32 v56, v56, v247
	v_div_scale_f32 v251, vcc, v246, v248, v246
	v_fma_f32 v252, -v249, v250, 1.0
	v_fmac_f32_e32 v250, v252, v250
	v_mul_f32_e32 v252, v251, v250
	v_fma_f32 v253, -v249, v252, v251
	v_fmac_f32_e32 v252, v253, v250
	v_fma_f32 v251, -v249, v252, v251
	v_div_fmas_f32 v251, v251, v250, v252
	v_div_fixup_f32 v251, v251, v248, v246
	v_mul_f32_e32 v56, v56, v251
	v_cvt_pk_bf16_f32 v56, v56, v129
	global_store_short v[74:75], v56, off offset:32
	v_cvt_f32_f16_e32 v246, v166
	v_cvt_f32_f16_e32 v247, v167
	v_mul_f32_e32 v248, 0xbfb8aa3b, v246
	v_exp_f32_e32 v248, v248
	v_add_f32_e32 v52, v52, v194
	v_add_f32_e32 v248, 1.0, v248
	v_div_scale_f32 v249, s[38:39], v248, v248, v246
	v_rcp_f32_e32 v250, v249
	v_mul_f32_e32 v52, v52, v247
	v_div_scale_f32 v251, vcc, v246, v248, v246
	v_fma_f32 v252, -v249, v250, 1.0
	v_fmac_f32_e32 v250, v252, v250
	v_mul_f32_e32 v252, v251, v250
	v_fma_f32 v253, -v249, v252, v251
	v_fmac_f32_e32 v252, v253, v250
	v_fma_f32 v251, -v249, v252, v251
	v_div_fmas_f32 v251, v251, v250, v252
	v_div_fixup_f32 v251, v251, v248, v246
	v_mul_f32_e32 v52, v52, v251
	v_cvt_pk_bf16_f32 v52, v52, v129
	global_store_short v[74:75], v52, off offset:64
	v_cvt_f32_f16_e32 v246, v168
	v_cvt_f32_f16_e32 v247, v169
	v_mul_f32_e32 v248, 0xbfb8aa3b, v246
	v_exp_f32_e32 v248, v248
	v_add_f32_e32 v48, v48, v194
	v_add_f32_e32 v248, 1.0, v248
	v_div_scale_f32 v249, s[38:39], v248, v248, v246
	v_rcp_f32_e32 v250, v249
	v_mul_f32_e32 v48, v48, v247
	v_div_scale_f32 v251, vcc, v246, v248, v246
	v_fma_f32 v252, -v249, v250, 1.0
	v_fmac_f32_e32 v250, v252, v250
	v_mul_f32_e32 v252, v251, v250
	v_fma_f32 v253, -v249, v252, v251
; DEVI u16 f2bf(float f) { return (u16)(cvtpk(f, 0.f) & 0xffffu); }
; DEVI float siluf_(float x) { return x / (1.f + __expf(-x)); }
; DEVI void prepSGU_tile(const Params& p, int l, int g, int tile, char* lds) {
;     ...
; #pragma unroll
;     for (int mb = 0; mb < 4; ++mb)
; #pragma unroll
;       for (int j = 0; j < 4; ++j) {
;         int pp = mh * 64 + mb * 16 + l4 * 4 + j; float bv = bs[pp];
;         const h16* zr = Z + (size_t)pp * NBC;
; #pragma unroll
;         for (int nb = 0; nb < 4; ++nb) {
;           int c = gi * 64 + nb * 16 + l15;
;           float u = (float)zr[736 + c], gc = (float)zr[1248 + c];
;           Yc[(size_t)(t0 + pp) * 256 + c] = f2bf(u * (acc[mb][nb][j] + bv) * siluf_(gc));
;         }
;       }
	v_fmac_f32_e32 v252, v253, v250
	v_fma_f32 v251, -v249, v252, v251
	v_div_fmas_f32 v251, v251, v250, v252
	v_div_fixup_f32 v251, v251, v248, v246
	v_mul_f32_e32 v48, v48, v251
	v_cvt_pk_bf16_f32 v48, v48, v129
	global_store_short v[74:75], v48, off offset:96
	v_cvt_f32_f16_e32 v246, v170
	v_cvt_f32_f16_e32 v247, v171
	v_mul_f32_e32 v248, 0xbfb8aa3b, v246
	v_exp_f32_e32 v248, v248
	v_add_f32_e32 v61, v61, v195
	v_add_f32_e32 v248, 1.0, v248
	v_div_scale_f32 v249, s[38:39], v248, v248, v246
	v_rcp_f32_e32 v250, v249
	v_mul_f32_e32 v61, v61, v247
	v_div_scale_f32 v251, vcc, v246, v248, v246
	v_fma_f32 v252, -v249, v250, 1.0
	v_fmac_f32_e32 v250, v252, v250
	v_mul_f32_e32 v252, v251, v250
	v_fma_f32 v253, -v249, v252, v251
	v_fmac_f32_e32 v252, v253, v250
	v_fma_f32 v251, -v249, v252, v251
	v_div_fmas_f32 v251, v251, v250, v252
	v_div_fixup_f32 v251, v251, v248, v246
	v_mul_f32_e32 v61, v61, v251
	v_cvt_pk_bf16_f32 v61, v61, v129
	global_store_short v[74:75], v61, off offset:512
	v_cvt_f32_f16_e32 v246, v172
	v_cvt_f32_f16_e32 v247, v173
	v_mul_f32_e32 v248, 0xbfb8aa3b, v246
	v_exp_f32_e32 v248, v248
	v_add_f32_e32 v57, v57, v195
	v_add_f32_e32 v248, 1.0, v248
	v_div_scale_f32 v249, s[38:39], v248, v248, v246
	v_rcp_f32_e32 v250, v249
	v_mul_f32_e32 v57, v57, v247
	v_div_scale_f32 v251, vcc, v246, v248, v246
	v_fma_f32 v252, -v249, v250, 1.0
	v_fmac_f32_e32 v250, v252, v250
	v_mul_f32_e32 v252, v251, v250
	v_fma_f32 v253, -v249, v252, v251
	v_fmac_f32_e32 v252, v253, v250
	v_fma_f32 v251, -v249, v252, v251
	v_div_fmas_f32 v251, v251, v250, v252
	v_div_fixup_f32 v251, v251, v248, v246
	v_mul_f32_e32 v57, v57, v251
	v_cvt_pk_bf16_f32 v57, v57, v129
	global_store_short v[74:75], v57, off offset:544
	v_cvt_f32_f16_e32 v246, v174
	v_cvt_f32_f16_e32 v247, v175
	v_mul_f32_e32 v248, 0xbfb8aa3b, v246
	v_exp_f32_e32 v248, v248
	v_add_f32_e32 v53, v53, v195
	v_add_f32_e32 v248, 1.0, v248
	v_div_scale_f32 v249, s[38:39], v248, v248, v246
	v_rcp_f32_e32 v250, v249
	v_mul_f32_e32 v53, v53, v247
	v_div_scale_f32 v251, vcc, v246, v248, v246
	v_fma_f32 v252, -v249, v250, 1.0
	v_fmac_f32_e32 v250, v252, v250
	v_mul_f32_e32 v252, v251, v250
	v_fma_f32 v253, -v249, v252, v251
	v_fmac_f32_e32 v252, v253, v250
	v_fma_f32 v251, -v249, v252, v251
	v_div_fmas_f32 v251, v251, v250, v252
	v_div_fixup_f32 v251, v251, v248, v246
	v_mul_f32_e32 v53, v53, v251
	v_cvt_pk_bf16_f32 v53, v53, v129
	global_store_short v[74:75], v53, off offset:576
	v_cvt_f32_f16_e32 v246, v176
	v_cvt_f32_f16_e32 v247, v177
	v_mul_f32_e32 v248, 0xbfb8aa3b, v246
	v_exp_f32_e32 v248, v248
	v_add_f32_e32 v49, v49, v195
	v_add_f32_e32 v248, 1.0, v248
	v_div_scale_f32 v249, s[38:39], v248, v248, v246
	v_rcp_f32_e32 v250, v249
	v_mul_f32_e32 v49, v49, v247
	v_div_scale_f32 v251, vcc, v246, v248, v246
	v_fma_f32 v252, -v249, v250, 1.0
	v_fmac_f32_e32 v250, v252, v250
	v_mul_f32_e32 v252, v251, v250
	v_fma_f32 v253, -v249, v252, v251
	v_fmac_f32_e32 v252, v253, v250
	v_fma_f32 v251, -v249, v252, v251
	v_div_fmas_f32 v251, v251, v250, v252
	v_div_fixup_f32 v251, v251, v248, v246
	v_mul_f32_e32 v49, v49, v251
	v_cvt_pk_bf16_f32 v49, v49, v129
	global_store_short v[74:75], v49, off offset:608
	v_cvt_f32_f16_e32 v246, v178
	v_cvt_f32_f16_e32 v247, v179
	v_mul_f32_e32 v248, 0xbfb8aa3b, v246
	v_exp_f32_e32 v248, v248
	v_add_f32_e32 v62, v62, v196
	v_add_f32_e32 v248, 1.0, v248
	v_div_scale_f32 v249, s[38:39], v248, v248, v246
	v_rcp_f32_e32 v250, v249
	v_mul_f32_e32 v62, v62, v247
	v_div_scale_f32 v251, vcc, v246, v248, v246
	v_fma_f32 v252, -v249, v250, 1.0
	v_fmac_f32_e32 v250, v252, v250
	v_mul_f32_e32 v252, v251, v250
	v_fma_f32 v253, -v249, v252, v251
	v_fmac_f32_e32 v252, v253, v250
	v_fma_f32 v251, -v249, v252, v251
	v_div_fmas_f32 v251, v251, v250, v252
	v_div_fixup_f32 v251, v251, v248, v246
	v_mul_f32_e32 v62, v62, v251
	v_cvt_pk_bf16_f32 v62, v62, v129
	global_store_short v[74:75], v62, off offset:1024
	v_cvt_f32_f16_e32 v246, v180
	v_cvt_f32_f16_e32 v247, v181
	v_mul_f32_e32 v248, 0xbfb8aa3b, v246
	v_exp_f32_e32 v248, v248
	v_add_f32_e32 v58, v58, v196
	v_add_f32_e32 v248, 1.0, v248
	v_div_scale_f32 v249, s[38:39], v248, v248, v246
	v_rcp_f32_e32 v250, v249
	v_mul_f32_e32 v58, v58, v247
	v_div_scale_f32 v251, vcc, v246, v248, v246
	v_fma_f32 v252, -v249, v250, 1.0
	v_fmac_f32_e32 v250, v252, v250
	v_mul_f32_e32 v252, v251, v250
	v_fma_f32 v253, -v249, v252, v251
	v_fmac_f32_e32 v252, v253, v250
	v_fma_f32 v251, -v249, v252, v251
	v_div_fmas_f32 v251, v251, v250, v252
	v_div_fixup_f32 v251, v251, v248, v246
	v_mul_f32_e32 v58, v58, v251
	v_cvt_pk_bf16_f32 v58, v58, v129
	global_store_short v[74:75], v58, off offset:1056
	v_cvt_f32_f16_e32 v246, v182
	v_cvt_f32_f16_e32 v247, v183
	v_mul_f32_e32 v248, 0xbfb8aa3b, v246
	v_exp_f32_e32 v248, v248
	v_add_f32_e32 v54, v54, v196
	v_add_f32_e32 v248, 1.0, v248
	v_div_scale_f32 v249, s[38:39], v248, v248, v246
	v_rcp_f32_e32 v250, v249
	v_mul_f32_e32 v54, v54, v247
	v_div_scale_f32 v251, vcc, v246, v248, v246
	v_fma_f32 v252, -v249, v250, 1.0
	v_fmac_f32_e32 v250, v252, v250
	v_mul_f32_e32 v252, v251, v250
	v_fma_f32 v253, -v249, v252, v251
	v_fmac_f32_e32 v252, v253, v250
	v_fma_f32 v251, -v249, v252, v251
	v_div_fmas_f32 v251, v251, v250, v252
	v_div_fixup_f32 v251, v251, v248, v246
	v_mul_f32_e32 v54, v54, v251
	v_cvt_pk_bf16_f32 v54, v54, v129
	global_store_short v[74:75], v54, off offset:1088
	v_cvt_f32_f16_e32 v246, v184
	v_cvt_f32_f16_e32 v247, v185
	v_mul_f32_e32 v248, 0xbfb8aa3b, v246
	v_exp_f32_e32 v248, v248
	v_add_f32_e32 v50, v50, v196
	v_add_f32_e32 v248, 1.0, v248
	v_div_scale_f32 v249, s[38:39], v248, v248, v246
	v_rcp_f32_e32 v250, v249
; DEVI u16 f2bf(float f) { return (u16)(cvtpk(f, 0.f) & 0xffffu); }
; DEVI float siluf_(float x) { return x / (1.f + __expf(-x)); }
; DEVI void prepSGU_tile(const Params& p, int l, int g, int tile, char* lds) {
;     ...
; #pragma unroll
;     for (int mb = 0; mb < 4; ++mb)
; #pragma unroll
;       for (int j = 0; j < 4; ++j) {
;         int pp = mh * 64 + mb * 16 + l4 * 4 + j; float bv = bs[pp];
;         const h16* zr = Z + (size_t)pp * NBC;
; #pragma unroll
;         for (int nb = 0; nb < 4; ++nb) {
;           int c = gi * 64 + nb * 16 + l15;
;           float u = (float)zr[736 + c], gc = (float)zr[1248 + c];
;           Yc[(size_t)(t0 + pp) * 256 + c] = f2bf(u * (acc[mb][nb][j] + bv) * siluf_(gc));
;         }
;       }
	v_mul_f32_e32 v50, v50, v247
	v_div_scale_f32 v251, vcc, v246, v248, v246
	v_fma_f32 v252, -v249, v250, 1.0
	v_fmac_f32_e32 v250, v252, v250
	v_mul_f32_e32 v252, v251, v250
	v_fma_f32 v253, -v249, v252, v251
	v_fmac_f32_e32 v252, v253, v250
	v_fma_f32 v251, -v249, v252, v251
	v_div_fmas_f32 v251, v251, v250, v252
	v_div_fixup_f32 v251, v251, v248, v246
	v_mul_f32_e32 v50, v50, v251
	v_cvt_pk_bf16_f32 v50, v50, v129
	global_store_short v[74:75], v50, off offset:1120
	v_cvt_f32_f16_e32 v246, v186
	v_cvt_f32_f16_e32 v247, v187
	v_mul_f32_e32 v248, 0xbfb8aa3b, v246
	v_exp_f32_e32 v248, v248
	v_add_f32_e32 v63, v63, v197
	v_add_f32_e32 v248, 1.0, v248
	v_div_scale_f32 v249, s[38:39], v248, v248, v246
	v_rcp_f32_e32 v250, v249
	v_mul_f32_e32 v63, v63, v247
	v_div_scale_f32 v251, vcc, v246, v248, v246
	v_fma_f32 v252, -v249, v250, 1.0
	v_fmac_f32_e32 v250, v252, v250
	v_mul_f32_e32 v252, v251, v250
	v_fma_f32 v253, -v249, v252, v251
	v_fmac_f32_e32 v252, v253, v250
	v_fma_f32 v251, -v249, v252, v251
	v_div_fmas_f32 v251, v251, v250, v252
	v_div_fixup_f32 v251, v251, v248, v246
	v_mul_f32_e32 v63, v63, v251
	v_cvt_pk_bf16_f32 v63, v63, v129
	global_store_short v[74:75], v63, off offset:1536
	v_cvt_f32_f16_e32 v246, v188
	v_cvt_f32_f16_e32 v247, v189
	v_mul_f32_e32 v248, 0xbfb8aa3b, v246
	v_exp_f32_e32 v248, v248
	v_add_f32_e32 v59, v59, v197
	v_add_f32_e32 v248, 1.0, v248
	v_div_scale_f32 v249, s[38:39], v248, v248, v246
	v_rcp_f32_e32 v250, v249
	v_mul_f32_e32 v59, v59, v247
	v_div_scale_f32 v251, vcc, v246, v248, v246
	v_fma_f32 v252, -v249, v250, 1.0
	v_fmac_f32_e32 v250, v252, v250
	v_mul_f32_e32 v252, v251, v250
	v_fma_f32 v253, -v249, v252, v251
	v_fmac_f32_e32 v252, v253, v250
	v_fma_f32 v251, -v249, v252, v251
	v_div_fmas_f32 v251, v251, v250, v252
	v_div_fixup_f32 v251, v251, v248, v246
	v_mul_f32_e32 v59, v59, v251
	v_cvt_pk_bf16_f32 v59, v59, v129
	global_store_short v[74:75], v59, off offset:1568
	v_cvt_f32_f16_e32 v246, v190
	v_cvt_f32_f16_e32 v247, v191
	v_mul_f32_e32 v248, 0xbfb8aa3b, v246
	v_exp_f32_e32 v248, v248
	v_add_f32_e32 v55, v55, v197
	v_add_f32_e32 v248, 1.0, v248
	v_div_scale_f32 v249, s[38:39], v248, v248, v246
	v_rcp_f32_e32 v250, v249
	v_mul_f32_e32 v55, v55, v247
	v_div_scale_f32 v251, vcc, v246, v248, v246
	v_fma_f32 v252, -v249, v250, 1.0
	v_fmac_f32_e32 v250, v252, v250
	v_mul_f32_e32 v252, v251, v250
	v_fma_f32 v253, -v249, v252, v251
	v_fmac_f32_e32 v252, v253, v250
	v_fma_f32 v251, -v249, v252, v251
	v_div_fmas_f32 v251, v251, v250, v252
	v_div_fixup_f32 v251, v251, v248, v246
	v_mul_f32_e32 v55, v55, v251
	v_cvt_pk_bf16_f32 v55, v55, v129
	global_store_short v[74:75], v55, off offset:1600
	v_cvt_f32_f16_e32 v246, v192
	v_cvt_f32_f16_e32 v247, v193
	v_mul_f32_e32 v248, 0xbfb8aa3b, v246
	v_exp_f32_e32 v248, v248
	v_add_f32_e32 v51, v51, v197
	v_add_f32_e32 v248, 1.0, v248
	v_div_scale_f32 v249, s[38:39], v248, v248, v246
	v_rcp_f32_e32 v250, v249
	v_mul_f32_e32 v51, v51, v247
	v_div_scale_f32 v251, vcc, v246, v248, v246
	v_fma_f32 v252, -v249, v250, 1.0
	v_fmac_f32_e32 v250, v252, v250
	v_mul_f32_e32 v252, v251, v250
	v_fma_f32 v253, -v249, v252, v251
	v_fmac_f32_e32 v252, v253, v250
	v_fma_f32 v251, -v249, v252, v251
	v_div_fmas_f32 v251, v251, v250, v252
	v_div_fixup_f32 v251, v251, v248, v246
	v_mul_f32_e32 v51, v51, v251
	v_cvt_pk_bf16_f32 v51, v51, v129
	global_store_short v[74:75], v51, off offset:1632
	v_add_co_u32_e32 v238, vcc, 0x17800, v72
	s_nop 1
	v_addc_co_u32_e32 v239, vcc, 0, v73, vcc
	v_add_co_u32_e32 v240, vcc, 0x183c0, v72
	s_nop 1
	v_addc_co_u32_e32 v241, vcc, 0, v73, vcc
	v_add_co_u32_e32 v242, vcc, 0x18f80, v72
	s_nop 1
	v_addc_co_u32_e32 v243, vcc, 0, v73, vcc
	v_add_co_u32_e32 v244, vcc, 0x19b40, v72
	s_nop 1
	v_addc_co_u32_e32 v245, vcc, 0, v73, vcc
	global_load_ushort v162, v[238:239], off offset:2496
	global_load_ushort v163, v[238:239], off offset:1472
	global_load_ushort v164, v[238:239], off offset:2528
	global_load_ushort v165, v[238:239], off offset:1504
	global_load_ushort v166, v[238:239], off offset:2560
	global_load_ushort v167, v[238:239], off offset:1536
	global_load_ushort v168, v[238:239], off offset:2592
	global_load_ushort v169, v[238:239], off offset:1568
	global_load_ushort v170, v[240:241], off offset:2496
	global_load_ushort v171, v[240:241], off offset:1472
	global_load_ushort v172, v[240:241], off offset:2528
	global_load_ushort v173, v[240:241], off offset:1504
	global_load_ushort v174, v[240:241], off offset:2560
	global_load_ushort v175, v[240:241], off offset:1536
	global_load_ushort v176, v[240:241], off offset:2592
	global_load_ushort v177, v[240:241], off offset:1568
	global_load_ushort v178, v[242:243], off offset:2496
	global_load_ushort v179, v[242:243], off offset:1472
	global_load_ushort v180, v[242:243], off offset:2528
	global_load_ushort v181, v[242:243], off offset:1504
	global_load_ushort v182, v[242:243], off offset:2560
	global_load_ushort v183, v[242:243], off offset:1536
	global_load_ushort v184, v[242:243], off offset:2592
	global_load_ushort v185, v[242:243], off offset:1568
	global_load_ushort v186, v[244:245], off offset:2496
	global_load_ushort v187, v[244:245], off offset:1472
	global_load_ushort v188, v[244:245], off offset:2528
	global_load_ushort v189, v[244:245], off offset:1504
	global_load_ushort v190, v[244:245], off offset:2560
	global_load_ushort v191, v[244:245], off offset:1536
	global_load_ushort v192, v[244:245], off offset:2592
	global_load_ushort v193, v[244:245], off offset:1568
	global_load_dword v194, v[66:67], off offset:128
	global_load_dword v195, v[66:67], off offset:132
	global_load_dword v196, v[66:67], off offset:136
	global_load_dword v197, v[66:67], off offset:140
	s_waitcnt vmcnt(52)
; DEVI u16 f2bf(float f) { return (u16)(cvtpk(f, 0.f) & 0xffffu); }
; DEVI float siluf_(float x) { return x / (1.f + __expf(-x)); }
; DEVI void prepSGU_tile(const Params& p, int l, int g, int tile, char* lds) {
;     ...
; #pragma unroll
;     for (int mb = 0; mb < 4; ++mb)
; #pragma unroll
;       for (int j = 0; j < 4; ++j) {
;         int pp = mh * 64 + mb * 16 + l4 * 4 + j; float bv = bs[pp];
;         const h16* zr = Z + (size_t)pp * NBC;
; #pragma unroll
;         for (int nb = 0; nb < 4; ++nb) {
;           int c = gi * 64 + nb * 16 + l15;
;           float u = (float)zr[736 + c], gc = (float)zr[1248 + c];
;           Yc[(size_t)(t0 + pp) * 256 + c] = f2bf(u * (acc[mb][nb][j] + bv) * siluf_(gc));
;         }
;       }
	v_or_b32_e32 v128, s0, v70
	v_or_b32_e32 v128, 16, v128
	v_lshlrev_b64 v[74:75], 9, v[128:129]
	v_lshl_add_u64 v[74:75], s[28:29], 0, v[74:75]
	v_lshl_add_u64 v[74:75], v[74:75], 0, v[64:65]
	v_cvt_f32_f16_e32 v246, v198
	v_cvt_f32_f16_e32 v247, v199
	v_mul_f32_e32 v248, 0xbfb8aa3b, v246
	v_exp_f32_e32 v248, v248
	v_add_f32_e32 v44, v44, v234
	v_add_f32_e32 v248, 1.0, v248
	v_div_scale_f32 v249, s[38:39], v248, v248, v246
	v_rcp_f32_e32 v250, v249
	v_mul_f32_e32 v44, v44, v247
	v_div_scale_f32 v251, vcc, v246, v248, v246
	v_fma_f32 v252, -v249, v250, 1.0
	v_fmac_f32_e32 v250, v252, v250
	v_mul_f32_e32 v252, v251, v250
	v_fma_f32 v253, -v249, v252, v251
	v_fmac_f32_e32 v252, v253, v250
	v_fma_f32 v251, -v249, v252, v251
	v_div_fmas_f32 v251, v251, v250, v252
	v_div_fixup_f32 v251, v251, v248, v246
	v_mul_f32_e32 v44, v44, v251
	v_cvt_pk_bf16_f32 v44, v44, v129
	global_store_short v[74:75], v44, off
	v_cvt_f32_f16_e32 v246, v200
	v_cvt_f32_f16_e32 v247, v201
	v_mul_f32_e32 v248, 0xbfb8aa3b, v246
	v_exp_f32_e32 v248, v248
	v_add_f32_e32 v40, v40, v234
	v_add_f32_e32 v248, 1.0, v248
	v_div_scale_f32 v249, s[38:39], v248, v248, v246
	v_rcp_f32_e32 v250, v249
	v_mul_f32_e32 v40, v40, v247
	v_div_scale_f32 v251, vcc, v246, v248, v246
	v_fma_f32 v252, -v249, v250, 1.0
	v_fmac_f32_e32 v250, v252, v250
	v_mul_f32_e32 v252, v251, v250
	v_fma_f32 v253, -v249, v252, v251
	v_fmac_f32_e32 v252, v253, v250
	v_fma_f32 v251, -v249, v252, v251
	v_div_fmas_f32 v251, v251, v250, v252
	v_div_fixup_f32 v251, v251, v248, v246
	v_mul_f32_e32 v40, v40, v251
	v_cvt_pk_bf16_f32 v40, v40, v129
	global_store_short v[74:75], v40, off offset:32
	v_cvt_f32_f16_e32 v246, v202
	v_cvt_f32_f16_e32 v247, v203
	v_mul_f32_e32 v248, 0xbfb8aa3b, v246
	v_exp_f32_e32 v248, v248
	v_add_f32_e32 v36, v36, v234
	v_add_f32_e32 v248, 1.0, v248
	v_div_scale_f32 v249, s[38:39], v248, v248, v246
	v_rcp_f32_e32 v250, v249
	v_mul_f32_e32 v36, v36, v247
	v_div_scale_f32 v251, vcc, v246, v248, v246
	v_fma_f32 v252, -v249, v250, 1.0
	v_fmac_f32_e32 v250, v252, v250
	v_mul_f32_e32 v252, v251, v250
	v_fma_f32 v253, -v249, v252, v251
	v_fmac_f32_e32 v252, v253, v250
	v_fma_f32 v251, -v249, v252, v251
	v_div_fmas_f32 v251, v251, v250, v252
	v_div_fixup_f32 v251, v251, v248, v246
	v_mul_f32_e32 v36, v36, v251
	v_cvt_pk_bf16_f32 v36, v36, v129
	global_store_short v[74:75], v36, off offset:64
	v_cvt_f32_f16_e32 v246, v204
	v_cvt_f32_f16_e32 v247, v205
	v_mul_f32_e32 v248, 0xbfb8aa3b, v246
	v_exp_f32_e32 v248, v248
	v_add_f32_e32 v32, v32, v234
	v_add_f32_e32 v248, 1.0, v248
	v_div_scale_f32 v249, s[38:39], v248, v248, v246
	v_rcp_f32_e32 v250, v249
	v_mul_f32_e32 v32, v32, v247
	v_div_scale_f32 v251, vcc, v246, v248, v246
	v_fma_f32 v252, -v249, v250, 1.0
	v_fmac_f32_e32 v250, v252, v250
	v_mul_f32_e32 v252, v251, v250
	v_fma_f32 v253, -v249, v252, v251
	v_fmac_f32_e32 v252, v253, v250
	v_fma_f32 v251, -v249, v252, v251
	v_div_fmas_f32 v251, v251, v250, v252
	v_div_fixup_f32 v251, v251, v248, v246
	v_mul_f32_e32 v32, v32, v251
	v_cvt_pk_bf16_f32 v32, v32, v129
	global_store_short v[74:75], v32, off offset:96
	v_cvt_f32_f16_e32 v246, v206
	v_cvt_f32_f16_e32 v247, v207
	v_mul_f32_e32 v248, 0xbfb8aa3b, v246
	v_exp_f32_e32 v248, v248
	v_add_f32_e32 v45, v45, v235
	v_add_f32_e32 v248, 1.0, v248
	v_div_scale_f32 v249, s[38:39], v248, v248, v246
	v_rcp_f32_e32 v250, v249
	v_mul_f32_e32 v45, v45, v247
	v_div_scale_f32 v251, vcc, v246, v248, v246
	v_fma_f32 v252, -v249, v250, 1.0
	v_fmac_f32_e32 v250, v252, v250
	v_mul_f32_e32 v252, v251, v250
	v_fma_f32 v253, -v249, v252, v251
	v_fmac_f32_e32 v252, v253, v250
	v_fma_f32 v251, -v249, v252, v251
	v_div_fmas_f32 v251, v251, v250, v252
	v_div_fixup_f32 v251, v251, v248, v246
	v_mul_f32_e32 v45, v45, v251
	v_cvt_pk_bf16_f32 v45, v45, v129
	global_store_short v[74:75], v45, off offset:512
	v_cvt_f32_f16_e32 v246, v208
	v_cvt_f32_f16_e32 v247, v209
	v_mul_f32_e32 v248, 0xbfb8aa3b, v246
	v_exp_f32_e32 v248, v248
	v_add_f32_e32 v41, v41, v235
	v_add_f32_e32 v248, 1.0, v248
	v_div_scale_f32 v249, s[38:39], v248, v248, v246
	v_rcp_f32_e32 v250, v249
	v_mul_f32_e32 v41, v41, v247
	v_div_scale_f32 v251, vcc, v246, v248, v246
	v_fma_f32 v252, -v249, v250, 1.0
	v_fmac_f32_e32 v250, v252, v250
	v_mul_f32_e32 v252, v251, v250
	v_fma_f32 v253, -v249, v252, v251
	v_fmac_f32_e32 v252, v253, v250
	v_fma_f32 v251, -v249, v252, v251
	v_div_fmas_f32 v251, v251, v250, v252
	v_div_fixup_f32 v251, v251, v248, v246
	v_mul_f32_e32 v41, v41, v251
	v_cvt_pk_bf16_f32 v41, v41, v129
	global_store_short v[74:75], v41, off offset:544
	v_cvt_f32_f16_e32 v246, v210
	v_cvt_f32_f16_e32 v247, v211
	v_mul_f32_e32 v248, 0xbfb8aa3b, v246
	v_exp_f32_e32 v248, v248
	v_add_f32_e32 v37, v37, v235
	v_add_f32_e32 v248, 1.0, v248
	v_div_scale_f32 v249, s[38:39], v248, v248, v246
	v_rcp_f32_e32 v250, v249
	v_mul_f32_e32 v37, v37, v247
	v_div_scale_f32 v251, vcc, v246, v248, v246
	v_fma_f32 v252, -v249, v250, 1.0
	v_fmac_f32_e32 v250, v252, v250
	v_mul_f32_e32 v252, v251, v250
	v_fma_f32 v253, -v249, v252, v251
	v_fmac_f32_e32 v252, v253, v250
	v_fma_f32 v251, -v249, v252, v251
	v_div_fmas_f32 v251, v251, v250, v252
	v_div_fixup_f32 v251, v251, v248, v246
	v_mul_f32_e32 v37, v37, v251
	v_cvt_pk_bf16_f32 v37, v37, v129
	global_store_short v[74:75], v37, off offset:576
	v_cvt_f32_f16_e32 v246, v212
	v_cvt_f32_f16_e32 v247, v213
	v_mul_f32_e32 v248, 0xbfb8aa3b, v246
	v_exp_f32_e32 v248, v248
	v_add_f32_e32 v33, v33, v235
	v_add_f32_e32 v248, 1.0, v248
	v_div_scale_f32 v249, s[38:39], v248, v248, v246
	v_rcp_f32_e32 v250, v249
	v_mul_f32_e32 v33, v33, v247
	v_div_scale_f32 v251, vcc, v246, v248, v246
; DEVI u16 f2bf(float f) { return (u16)(cvtpk(f, 0.f) & 0xffffu); }
; DEVI float siluf_(float x) { return x / (1.f + __expf(-x)); }
; DEVI void prepSGU_tile(const Params& p, int l, int g, int tile, char* lds) {
;     ...
; #pragma unroll
;     for (int mb = 0; mb < 4; ++mb)
; #pragma unroll
;       for (int j = 0; j < 4; ++j) {
;         int pp = mh * 64 + mb * 16 + l4 * 4 + j; float bv = bs[pp];
;         const h16* zr = Z + (size_t)pp * NBC;
; #pragma unroll
;         for (int nb = 0; nb < 4; ++nb) {
;           int c = gi * 64 + nb * 16 + l15;
;           float u = (float)zr[736 + c], gc = (float)zr[1248 + c];
;           Yc[(size_t)(t0 + pp) * 256 + c] = f2bf(u * (acc[mb][nb][j] + bv) * siluf_(gc));
;         }
;       }
	v_fma_f32 v252, -v249, v250, 1.0
	v_fmac_f32_e32 v250, v252, v250
	v_mul_f32_e32 v252, v251, v250
	v_fma_f32 v253, -v249, v252, v251
	v_fmac_f32_e32 v252, v253, v250
	v_fma_f32 v251, -v249, v252, v251
	v_div_fmas_f32 v251, v251, v250, v252
	v_div_fixup_f32 v251, v251, v248, v246
	v_mul_f32_e32 v33, v33, v251
	v_cvt_pk_bf16_f32 v33, v33, v129
	global_store_short v[74:75], v33, off offset:608
	v_cvt_f32_f16_e32 v246, v214
	v_cvt_f32_f16_e32 v247, v215
	v_mul_f32_e32 v248, 0xbfb8aa3b, v246
	v_exp_f32_e32 v248, v248
	v_add_f32_e32 v46, v46, v236
	v_add_f32_e32 v248, 1.0, v248
	v_div_scale_f32 v249, s[38:39], v248, v248, v246
	v_rcp_f32_e32 v250, v249
	v_mul_f32_e32 v46, v46, v247
	v_div_scale_f32 v251, vcc, v246, v248, v246
	v_fma_f32 v252, -v249, v250, 1.0
	v_fmac_f32_e32 v250, v252, v250
	v_mul_f32_e32 v252, v251, v250
	v_fma_f32 v253, -v249, v252, v251
	v_fmac_f32_e32 v252, v253, v250
	v_fma_f32 v251, -v249, v252, v251
	v_div_fmas_f32 v251, v251, v250, v252
	v_div_fixup_f32 v251, v251, v248, v246
	v_mul_f32_e32 v46, v46, v251
	v_cvt_pk_bf16_f32 v46, v46, v129
	global_store_short v[74:75], v46, off offset:1024
	v_cvt_f32_f16_e32 v246, v216
	v_cvt_f32_f16_e32 v247, v217
	v_mul_f32_e32 v248, 0xbfb8aa3b, v246
	v_exp_f32_e32 v248, v248
	v_add_f32_e32 v42, v42, v236
	v_add_f32_e32 v248, 1.0, v248
	v_div_scale_f32 v249, s[38:39], v248, v248, v246
	v_rcp_f32_e32 v250, v249
	v_mul_f32_e32 v42, v42, v247
	v_div_scale_f32 v251, vcc, v246, v248, v246
	v_fma_f32 v252, -v249, v250, 1.0
	v_fmac_f32_e32 v250, v252, v250
	v_mul_f32_e32 v252, v251, v250
	v_fma_f32 v253, -v249, v252, v251
	v_fmac_f32_e32 v252, v253, v250
	v_fma_f32 v251, -v249, v252, v251
	v_div_fmas_f32 v251, v251, v250, v252
	v_div_fixup_f32 v251, v251, v248, v246
	v_mul_f32_e32 v42, v42, v251
	v_cvt_pk_bf16_f32 v42, v42, v129
	global_store_short v[74:75], v42, off offset:1056
	v_cvt_f32_f16_e32 v246, v222
	v_cvt_f32_f16_e32 v247, v223
	v_mul_f32_e32 v248, 0xbfb8aa3b, v246
	v_exp_f32_e32 v248, v248
	v_add_f32_e32 v38, v38, v236
	v_add_f32_e32 v248, 1.0, v248
	v_div_scale_f32 v249, s[38:39], v248, v248, v246
	v_rcp_f32_e32 v250, v249
	v_mul_f32_e32 v38, v38, v247
	v_div_scale_f32 v251, vcc, v246, v248, v246
	v_fma_f32 v252, -v249, v250, 1.0
	v_fmac_f32_e32 v250, v252, v250
	v_mul_f32_e32 v252, v251, v250
	v_fma_f32 v253, -v249, v252, v251
	v_fmac_f32_e32 v252, v253, v250
	v_fma_f32 v251, -v249, v252, v251
	v_div_fmas_f32 v251, v251, v250, v252
	v_div_fixup_f32 v251, v251, v248, v246
	v_mul_f32_e32 v38, v38, v251
	v_cvt_pk_bf16_f32 v38, v38, v129
	global_store_short v[74:75], v38, off offset:1088
	v_cvt_f32_f16_e32 v246, v224
	v_cvt_f32_f16_e32 v247, v225
	v_mul_f32_e32 v248, 0xbfb8aa3b, v246
	v_exp_f32_e32 v248, v248
	v_add_f32_e32 v34, v34, v236
	v_add_f32_e32 v248, 1.0, v248
	v_div_scale_f32 v249, s[38:39], v248, v248, v246
	v_rcp_f32_e32 v250, v249
	v_mul_f32_e32 v34, v34, v247
	v_div_scale_f32 v251, vcc, v246, v248, v246
	v_fma_f32 v252, -v249, v250, 1.0
	v_fmac_f32_e32 v250, v252, v250
	v_mul_f32_e32 v252, v251, v250
	v_fma_f32 v253, -v249, v252, v251
	v_fmac_f32_e32 v252, v253, v250
	v_fma_f32 v251, -v249, v252, v251
	v_div_fmas_f32 v251, v251, v250, v252
	v_div_fixup_f32 v251, v251, v248, v246
	v_mul_f32_e32 v34, v34, v251
	v_cvt_pk_bf16_f32 v34, v34, v129
	global_store_short v[74:75], v34, off offset:1120
	v_cvt_f32_f16_e32 v246, v226
	v_cvt_f32_f16_e32 v247, v227
	v_mul_f32_e32 v248, 0xbfb8aa3b, v246
	v_exp_f32_e32 v248, v248
	v_add_f32_e32 v47, v47, v237
	v_add_f32_e32 v248, 1.0, v248
	v_div_scale_f32 v249, s[38:39], v248, v248, v246
	v_rcp_f32_e32 v250, v249
	v_mul_f32_e32 v47, v47, v247
	v_div_scale_f32 v251, vcc, v246, v248, v246
	v_fma_f32 v252, -v249, v250, 1.0
	v_fmac_f32_e32 v250, v252, v250
	v_mul_f32_e32 v252, v251, v250
	v_fma_f32 v253, -v249, v252, v251
	v_fmac_f32_e32 v252, v253, v250
	v_fma_f32 v251, -v249, v252, v251
	v_div_fmas_f32 v251, v251, v250, v252
	v_div_fixup_f32 v251, v251, v248, v246
	v_mul_f32_e32 v47, v47, v251
	v_cvt_pk_bf16_f32 v47, v47, v129
	global_store_short v[74:75], v47, off offset:1536
	v_cvt_f32_f16_e32 v246, v228
	v_cvt_f32_f16_e32 v247, v229
	v_mul_f32_e32 v248, 0xbfb8aa3b, v246
	v_exp_f32_e32 v248, v248
	v_add_f32_e32 v43, v43, v237
	v_add_f32_e32 v248, 1.0, v248
	v_div_scale_f32 v249, s[38:39], v248, v248, v246
	v_rcp_f32_e32 v250, v249
	v_mul_f32_e32 v43, v43, v247
	v_div_scale_f32 v251, vcc, v246, v248, v246
	v_fma_f32 v252, -v249, v250, 1.0
	v_fmac_f32_e32 v250, v252, v250
	v_mul_f32_e32 v252, v251, v250
	v_fma_f32 v253, -v249, v252, v251
	v_fmac_f32_e32 v252, v253, v250
	v_fma_f32 v251, -v249, v252, v251
	v_div_fmas_f32 v251, v251, v250, v252
	v_div_fixup_f32 v251, v251, v248, v246
	v_mul_f32_e32 v43, v43, v251
	v_cvt_pk_bf16_f32 v43, v43, v129
	global_store_short v[74:75], v43, off offset:1568
	v_cvt_f32_f16_e32 v246, v230
	v_cvt_f32_f16_e32 v247, v231
	v_mul_f32_e32 v248, 0xbfb8aa3b, v246
	v_exp_f32_e32 v248, v248
	v_add_f32_e32 v39, v39, v237
	v_add_f32_e32 v248, 1.0, v248
	v_div_scale_f32 v249, s[38:39], v248, v248, v246
	v_rcp_f32_e32 v250, v249
	v_mul_f32_e32 v39, v39, v247
	v_div_scale_f32 v251, vcc, v246, v248, v246
	v_fma_f32 v252, -v249, v250, 1.0
	v_fmac_f32_e32 v250, v252, v250
	v_mul_f32_e32 v252, v251, v250
	v_fma_f32 v253, -v249, v252, v251
	v_fmac_f32_e32 v252, v253, v250
	v_fma_f32 v251, -v249, v252, v251
	v_div_fmas_f32 v251, v251, v250, v252
	v_div_fixup_f32 v251, v251, v248, v246
	v_mul_f32_e32 v39, v39, v251
	v_cvt_pk_bf16_f32 v39, v39, v129
	global_store_short v[74:75], v39, off offset:1600
	v_cvt_f32_f16_e32 v246, v232
	v_cvt_f32_f16_e32 v247, v233
	v_mul_f32_e32 v248, 0xbfb8aa3b, v246
	v_exp_f32_e32 v248, v248
; DEVI u16 f2bf(float f) { return (u16)(cvtpk(f, 0.f) & 0xffffu); }
; DEVI float siluf_(float x) { return x / (1.f + __expf(-x)); }
; DEVI void prepSGU_tile(const Params& p, int l, int g, int tile, char* lds) {
;     ...
; #pragma unroll
;     for (int mb = 0; mb < 4; ++mb)
; #pragma unroll
;       for (int j = 0; j < 4; ++j) {
;         int pp = mh * 64 + mb * 16 + l4 * 4 + j; float bv = bs[pp];
;         const h16* zr = Z + (size_t)pp * NBC;
; #pragma unroll
;         for (int nb = 0; nb < 4; ++nb) {
;           int c = gi * 64 + nb * 16 + l15;
;           float u = (float)zr[736 + c], gc = (float)zr[1248 + c];
;           Yc[(size_t)(t0 + pp) * 256 + c] = f2bf(u * (acc[mb][nb][j] + bv) * siluf_(gc));
;         }
;       }
	v_add_f32_e32 v35, v35, v237
	v_add_f32_e32 v248, 1.0, v248
	v_div_scale_f32 v249, s[38:39], v248, v248, v246
	v_rcp_f32_e32 v250, v249
	v_mul_f32_e32 v35, v35, v247
	v_div_scale_f32 v251, vcc, v246, v248, v246
	v_fma_f32 v252, -v249, v250, 1.0
	v_fmac_f32_e32 v250, v252, v250
	v_mul_f32_e32 v252, v251, v250
	v_fma_f32 v253, -v249, v252, v251
	v_fmac_f32_e32 v252, v253, v250
	v_fma_f32 v251, -v249, v252, v251
	v_div_fmas_f32 v251, v251, v250, v252
	v_div_fixup_f32 v251, v251, v248, v246
	v_mul_f32_e32 v35, v35, v251
	v_cvt_pk_bf16_f32 v35, v35, v129
	global_store_short v[74:75], v35, off offset:1632
	v_add_co_u32_e32 v238, vcc, 0x23400, v72
	s_nop 1
	v_addc_co_u32_e32 v239, vcc, 0, v73, vcc
	v_add_co_u32_e32 v240, vcc, 0x23fc0, v72
	s_nop 1
	v_addc_co_u32_e32 v241, vcc, 0, v73, vcc
	v_add_co_u32_e32 v242, vcc, 0x24b80, v72
	s_nop 1
	v_addc_co_u32_e32 v243, vcc, 0, v73, vcc
	v_add_co_u32_e32 v244, vcc, 0x25740, v72
	s_nop 1
	v_addc_co_u32_e32 v245, vcc, 0, v73, vcc
	global_load_ushort v198, v[238:239], off offset:2496
	global_load_ushort v199, v[238:239], off offset:1472
	global_load_ushort v200, v[238:239], off offset:2528
	global_load_ushort v201, v[238:239], off offset:1504
	global_load_ushort v202, v[238:239], off offset:2560
	global_load_ushort v203, v[238:239], off offset:1536
	global_load_ushort v204, v[238:239], off offset:2592
	global_load_ushort v205, v[238:239], off offset:1568
	global_load_ushort v206, v[240:241], off offset:2496
	global_load_ushort v207, v[240:241], off offset:1472
	global_load_ushort v208, v[240:241], off offset:2528
	global_load_ushort v209, v[240:241], off offset:1504
	global_load_ushort v210, v[240:241], off offset:2560
	global_load_ushort v211, v[240:241], off offset:1536
	global_load_ushort v212, v[240:241], off offset:2592
	global_load_ushort v213, v[240:241], off offset:1568
	global_load_ushort v214, v[242:243], off offset:2496
	global_load_ushort v215, v[242:243], off offset:1472
	global_load_ushort v216, v[242:243], off offset:2528
	global_load_ushort v217, v[242:243], off offset:1504
	global_load_ushort v222, v[242:243], off offset:2560
	global_load_ushort v223, v[242:243], off offset:1536
	global_load_ushort v224, v[242:243], off offset:2592
	global_load_ushort v225, v[242:243], off offset:1568
	global_load_ushort v226, v[244:245], off offset:2496
	global_load_ushort v227, v[244:245], off offset:1472
	global_load_ushort v228, v[244:245], off offset:2528
	global_load_ushort v229, v[244:245], off offset:1504
	global_load_ushort v230, v[244:245], off offset:2560
	global_load_ushort v231, v[244:245], off offset:1536
	global_load_ushort v232, v[244:245], off offset:2592
	global_load_ushort v233, v[244:245], off offset:1568
	global_load_dword v234, v[66:67], off offset:192
	global_load_dword v235, v[66:67], off offset:196
	global_load_dword v236, v[66:67], off offset:200
	global_load_dword v237, v[66:67], off offset:204
	s_waitcnt vmcnt(52)
	v_or_b32_e32 v128, s0, v70
	v_or_b32_e32 v128, 32, v128
	v_lshlrev_b64 v[74:75], 9, v[128:129]
	v_lshl_add_u64 v[74:75], s[28:29], 0, v[74:75]
	v_lshl_add_u64 v[74:75], v[74:75], 0, v[64:65]
	v_cvt_f32_f16_e32 v246, v162
	v_cvt_f32_f16_e32 v247, v163
	v_mul_f32_e32 v248, 0xbfb8aa3b, v246
	v_exp_f32_e32 v248, v248
	v_add_f32_e32 v28, v28, v194
	v_add_f32_e32 v248, 1.0, v248
	v_div_scale_f32 v249, s[38:39], v248, v248, v246
	v_rcp_f32_e32 v250, v249
	v_mul_f32_e32 v28, v28, v247
	v_div_scale_f32 v251, vcc, v246, v248, v246
	v_fma_f32 v252, -v249, v250, 1.0
	v_fmac_f32_e32 v250, v252, v250
	v_mul_f32_e32 v252, v251, v250
	v_fma_f32 v253, -v249, v252, v251
	v_fmac_f32_e32 v252, v253, v250
	v_fma_f32 v251, -v249, v252, v251
	v_div_fmas_f32 v251, v251, v250, v252
	v_div_fixup_f32 v251, v251, v248, v246
	v_mul_f32_e32 v28, v28, v251
	v_cvt_pk_bf16_f32 v28, v28, v129
	global_store_short v[74:75], v28, off
	v_cvt_f32_f16_e32 v246, v164
	v_cvt_f32_f16_e32 v247, v165
	v_mul_f32_e32 v248, 0xbfb8aa3b, v246
	v_exp_f32_e32 v248, v248
	v_add_f32_e32 v24, v24, v194
	v_add_f32_e32 v248, 1.0, v248
	v_div_scale_f32 v249, s[38:39], v248, v248, v246
	v_rcp_f32_e32 v250, v249
	v_mul_f32_e32 v24, v24, v247
	v_div_scale_f32 v251, vcc, v246, v248, v246
	v_fma_f32 v252, -v249, v250, 1.0
	v_fmac_f32_e32 v250, v252, v250
	v_mul_f32_e32 v252, v251, v250
	v_fma_f32 v253, -v249, v252, v251
	v_fmac_f32_e32 v252, v253, v250
	v_fma_f32 v251, -v249, v252, v251
	v_div_fmas_f32 v251, v251, v250, v252
	v_div_fixup_f32 v251, v251, v248, v246
	v_mul_f32_e32 v24, v24, v251
	v_cvt_pk_bf16_f32 v24, v24, v129
	global_store_short v[74:75], v24, off offset:32
	v_cvt_f32_f16_e32 v246, v166
	v_cvt_f32_f16_e32 v247, v167
	v_mul_f32_e32 v248, 0xbfb8aa3b, v246
	v_exp_f32_e32 v248, v248
	v_add_f32_e32 v20, v20, v194
	v_add_f32_e32 v248, 1.0, v248
	v_div_scale_f32 v249, s[38:39], v248, v248, v246
	v_rcp_f32_e32 v250, v249
	v_mul_f32_e32 v20, v20, v247
	v_div_scale_f32 v251, vcc, v246, v248, v246
	v_fma_f32 v252, -v249, v250, 1.0
	v_fmac_f32_e32 v250, v252, v250
	v_mul_f32_e32 v252, v251, v250
	v_fma_f32 v253, -v249, v252, v251
	v_fmac_f32_e32 v252, v253, v250
	v_fma_f32 v251, -v249, v252, v251
	v_div_fmas_f32 v251, v251, v250, v252
	v_div_fixup_f32 v251, v251, v248, v246
	v_mul_f32_e32 v20, v20, v251
	v_cvt_pk_bf16_f32 v20, v20, v129
	global_store_short v[74:75], v20, off offset:64
	v_cvt_f32_f16_e32 v246, v168
	v_cvt_f32_f16_e32 v247, v169
	v_mul_f32_e32 v248, 0xbfb8aa3b, v246
	v_exp_f32_e32 v248, v248
	v_add_f32_e32 v16, v16, v194
	v_add_f32_e32 v248, 1.0, v248
	v_div_scale_f32 v249, s[38:39], v248, v248, v246
	v_rcp_f32_e32 v250, v249
	v_mul_f32_e32 v16, v16, v247
	v_div_scale_f32 v251, vcc, v246, v248, v246
; DEVI u16 f2bf(float f) { return (u16)(cvtpk(f, 0.f) & 0xffffu); }
; DEVI float siluf_(float x) { return x / (1.f + __expf(-x)); }
; DEVI void prepSGU_tile(const Params& p, int l, int g, int tile, char* lds) {
;     ...
; #pragma unroll
;     for (int mb = 0; mb < 4; ++mb)
; #pragma unroll
;       for (int j = 0; j < 4; ++j) {
;         int pp = mh * 64 + mb * 16 + l4 * 4 + j; float bv = bs[pp];
;         const h16* zr = Z + (size_t)pp * NBC;
; #pragma unroll
;         for (int nb = 0; nb < 4; ++nb) {
;           int c = gi * 64 + nb * 16 + l15;
;           float u = (float)zr[736 + c], gc = (float)zr[1248 + c];
;           Yc[(size_t)(t0 + pp) * 256 + c] = f2bf(u * (acc[mb][nb][j] + bv) * siluf_(gc));
;         }
;       }
	v_fma_f32 v252, -v249, v250, 1.0
	v_fmac_f32_e32 v250, v252, v250
	v_mul_f32_e32 v252, v251, v250
	v_fma_f32 v253, -v249, v252, v251
	v_fmac_f32_e32 v252, v253, v250
	v_fma_f32 v251, -v249, v252, v251
	v_div_fmas_f32 v251, v251, v250, v252
	v_div_fixup_f32 v251, v251, v248, v246
	v_mul_f32_e32 v16, v16, v251
	v_cvt_pk_bf16_f32 v16, v16, v129
	global_store_short v[74:75], v16, off offset:96
	v_cvt_f32_f16_e32 v246, v170
	v_cvt_f32_f16_e32 v247, v171
	v_mul_f32_e32 v248, 0xbfb8aa3b, v246
	v_exp_f32_e32 v248, v248
	v_add_f32_e32 v29, v29, v195
	v_add_f32_e32 v248, 1.0, v248
	v_div_scale_f32 v249, s[38:39], v248, v248, v246
	v_rcp_f32_e32 v250, v249
	v_mul_f32_e32 v29, v29, v247
	v_div_scale_f32 v251, vcc, v246, v248, v246
	v_fma_f32 v252, -v249, v250, 1.0
	v_fmac_f32_e32 v250, v252, v250
	v_mul_f32_e32 v252, v251, v250
	v_fma_f32 v253, -v249, v252, v251
	v_fmac_f32_e32 v252, v253, v250
	v_fma_f32 v251, -v249, v252, v251
	v_div_fmas_f32 v251, v251, v250, v252
	v_div_fixup_f32 v251, v251, v248, v246
	v_mul_f32_e32 v29, v29, v251
	v_cvt_pk_bf16_f32 v29, v29, v129
	global_store_short v[74:75], v29, off offset:512
	v_cvt_f32_f16_e32 v246, v172
	v_cvt_f32_f16_e32 v247, v173
	v_mul_f32_e32 v248, 0xbfb8aa3b, v246
	v_exp_f32_e32 v248, v248
	v_add_f32_e32 v25, v25, v195
	v_add_f32_e32 v248, 1.0, v248
	v_div_scale_f32 v249, s[38:39], v248, v248, v246
	v_rcp_f32_e32 v250, v249
	v_mul_f32_e32 v25, v25, v247
	v_div_scale_f32 v251, vcc, v246, v248, v246
	v_fma_f32 v252, -v249, v250, 1.0
	v_fmac_f32_e32 v250, v252, v250
	v_mul_f32_e32 v252, v251, v250
	v_fma_f32 v253, -v249, v252, v251
	v_fmac_f32_e32 v252, v253, v250
	v_fma_f32 v251, -v249, v252, v251
	v_div_fmas_f32 v251, v251, v250, v252
	v_div_fixup_f32 v251, v251, v248, v246
	v_mul_f32_e32 v25, v25, v251
	v_cvt_pk_bf16_f32 v25, v25, v129
	global_store_short v[74:75], v25, off offset:544
	v_cvt_f32_f16_e32 v246, v174
	v_cvt_f32_f16_e32 v247, v175
	v_mul_f32_e32 v248, 0xbfb8aa3b, v246
	v_exp_f32_e32 v248, v248
	v_add_f32_e32 v21, v21, v195
	v_add_f32_e32 v248, 1.0, v248
	v_div_scale_f32 v249, s[38:39], v248, v248, v246
	v_rcp_f32_e32 v250, v249
	v_mul_f32_e32 v21, v21, v247
	v_div_scale_f32 v251, vcc, v246, v248, v246
	v_fma_f32 v252, -v249, v250, 1.0
	v_fmac_f32_e32 v250, v252, v250
	v_mul_f32_e32 v252, v251, v250
	v_fma_f32 v253, -v249, v252, v251
	v_fmac_f32_e32 v252, v253, v250
	v_fma_f32 v251, -v249, v252, v251
	v_div_fmas_f32 v251, v251, v250, v252
	v_div_fixup_f32 v251, v251, v248, v246
	v_mul_f32_e32 v21, v21, v251
	v_cvt_pk_bf16_f32 v21, v21, v129
	global_store_short v[74:75], v21, off offset:576
	v_cvt_f32_f16_e32 v246, v176
	v_cvt_f32_f16_e32 v247, v177
	v_mul_f32_e32 v248, 0xbfb8aa3b, v246
	v_exp_f32_e32 v248, v248
	v_add_f32_e32 v17, v17, v195
	v_add_f32_e32 v248, 1.0, v248
	v_div_scale_f32 v249, s[38:39], v248, v248, v246
	v_rcp_f32_e32 v250, v249
	v_mul_f32_e32 v17, v17, v247
	v_div_scale_f32 v251, vcc, v246, v248, v246
	v_fma_f32 v252, -v249, v250, 1.0
	v_fmac_f32_e32 v250, v252, v250
	v_mul_f32_e32 v252, v251, v250
	v_fma_f32 v253, -v249, v252, v251
	v_fmac_f32_e32 v252, v253, v250
	v_fma_f32 v251, -v249, v252, v251
	v_div_fmas_f32 v251, v251, v250, v252
	v_div_fixup_f32 v251, v251, v248, v246
	v_mul_f32_e32 v17, v17, v251
	v_cvt_pk_bf16_f32 v17, v17, v129
	global_store_short v[74:75], v17, off offset:608
	v_cvt_f32_f16_e32 v246, v178
	v_cvt_f32_f16_e32 v247, v179
	v_mul_f32_e32 v248, 0xbfb8aa3b, v246
	v_exp_f32_e32 v248, v248
	v_add_f32_e32 v30, v30, v196
	v_add_f32_e32 v248, 1.0, v248
	v_div_scale_f32 v249, s[38:39], v248, v248, v246
	v_rcp_f32_e32 v250, v249
	v_mul_f32_e32 v30, v30, v247
	v_div_scale_f32 v251, vcc, v246, v248, v246
	v_fma_f32 v252, -v249, v250, 1.0
	v_fmac_f32_e32 v250, v252, v250
	v_mul_f32_e32 v252, v251, v250
	v_fma_f32 v253, -v249, v252, v251
	v_fmac_f32_e32 v252, v253, v250
	v_fma_f32 v251, -v249, v252, v251
	v_div_fmas_f32 v251, v251, v250, v252
	v_div_fixup_f32 v251, v251, v248, v246
	v_mul_f32_e32 v30, v30, v251
	v_cvt_pk_bf16_f32 v30, v30, v129
	global_store_short v[74:75], v30, off offset:1024
	v_cvt_f32_f16_e32 v246, v180
	v_cvt_f32_f16_e32 v247, v181
	v_mul_f32_e32 v248, 0xbfb8aa3b, v246
	v_exp_f32_e32 v248, v248
	v_add_f32_e32 v26, v26, v196
	v_add_f32_e32 v248, 1.0, v248
	v_div_scale_f32 v249, s[38:39], v248, v248, v246
	v_rcp_f32_e32 v250, v249
	v_mul_f32_e32 v26, v26, v247
	v_div_scale_f32 v251, vcc, v246, v248, v246
	v_fma_f32 v252, -v249, v250, 1.0
	v_fmac_f32_e32 v250, v252, v250
	v_mul_f32_e32 v252, v251, v250
	v_fma_f32 v253, -v249, v252, v251
	v_fmac_f32_e32 v252, v253, v250
	v_fma_f32 v251, -v249, v252, v251
	v_div_fmas_f32 v251, v251, v250, v252
	v_div_fixup_f32 v251, v251, v248, v246
	v_mul_f32_e32 v26, v26, v251
	v_cvt_pk_bf16_f32 v26, v26, v129
	global_store_short v[74:75], v26, off offset:1056
	v_cvt_f32_f16_e32 v246, v182
	v_cvt_f32_f16_e32 v247, v183
	v_mul_f32_e32 v248, 0xbfb8aa3b, v246
	v_exp_f32_e32 v248, v248
	v_add_f32_e32 v22, v22, v196
	v_add_f32_e32 v248, 1.0, v248
	v_div_scale_f32 v249, s[38:39], v248, v248, v246
	v_rcp_f32_e32 v250, v249
	v_mul_f32_e32 v22, v22, v247
	v_div_scale_f32 v251, vcc, v246, v248, v246
	v_fma_f32 v252, -v249, v250, 1.0
	v_fmac_f32_e32 v250, v252, v250
	v_mul_f32_e32 v252, v251, v250
	v_fma_f32 v253, -v249, v252, v251
	v_fmac_f32_e32 v252, v253, v250
	v_fma_f32 v251, -v249, v252, v251
	v_div_fmas_f32 v251, v251, v250, v252
	v_div_fixup_f32 v251, v251, v248, v246
	v_mul_f32_e32 v22, v22, v251
	v_cvt_pk_bf16_f32 v22, v22, v129
	global_store_short v[74:75], v22, off offset:1088
	v_cvt_f32_f16_e32 v246, v184
	v_cvt_f32_f16_e32 v247, v185
	v_mul_f32_e32 v248, 0xbfb8aa3b, v246
	v_exp_f32_e32 v248, v248
; DEVI u16 f2bf(float f) { return (u16)(cvtpk(f, 0.f) & 0xffffu); }
; DEVI float siluf_(float x) { return x / (1.f + __expf(-x)); }
; DEVI void prepSGU_tile(const Params& p, int l, int g, int tile, char* lds) {
;     ...
; #pragma unroll
;     for (int mb = 0; mb < 4; ++mb)
; #pragma unroll
;       for (int j = 0; j < 4; ++j) {
;         int pp = mh * 64 + mb * 16 + l4 * 4 + j; float bv = bs[pp];
;         const h16* zr = Z + (size_t)pp * NBC;
; #pragma unroll
;         for (int nb = 0; nb < 4; ++nb) {
;           int c = gi * 64 + nb * 16 + l15;
;           float u = (float)zr[736 + c], gc = (float)zr[1248 + c];
;           Yc[(size_t)(t0 + pp) * 256 + c] = f2bf(u * (acc[mb][nb][j] + bv) * siluf_(gc));
;         }
;       }
	v_add_f32_e32 v18, v18, v196
	v_add_f32_e32 v248, 1.0, v248
	v_div_scale_f32 v249, s[38:39], v248, v248, v246
	v_rcp_f32_e32 v250, v249
	v_mul_f32_e32 v18, v18, v247
	v_div_scale_f32 v251, vcc, v246, v248, v246
	v_fma_f32 v252, -v249, v250, 1.0
	v_fmac_f32_e32 v250, v252, v250
	v_mul_f32_e32 v252, v251, v250
	v_fma_f32 v253, -v249, v252, v251
	v_fmac_f32_e32 v252, v253, v250
	v_fma_f32 v251, -v249, v252, v251
	v_div_fmas_f32 v251, v251, v250, v252
	v_div_fixup_f32 v251, v251, v248, v246
	v_mul_f32_e32 v18, v18, v251
	v_cvt_pk_bf16_f32 v18, v18, v129
	global_store_short v[74:75], v18, off offset:1120
	v_cvt_f32_f16_e32 v246, v186
	v_cvt_f32_f16_e32 v247, v187
	v_mul_f32_e32 v248, 0xbfb8aa3b, v246
	v_exp_f32_e32 v248, v248
	v_add_f32_e32 v31, v31, v197
	v_add_f32_e32 v248, 1.0, v248
	v_div_scale_f32 v249, s[38:39], v248, v248, v246
	v_rcp_f32_e32 v250, v249
	v_mul_f32_e32 v31, v31, v247
	v_div_scale_f32 v251, vcc, v246, v248, v246
	v_fma_f32 v252, -v249, v250, 1.0
	v_fmac_f32_e32 v250, v252, v250
	v_mul_f32_e32 v252, v251, v250
	v_fma_f32 v253, -v249, v252, v251
	v_fmac_f32_e32 v252, v253, v250
	v_fma_f32 v251, -v249, v252, v251
	v_div_fmas_f32 v251, v251, v250, v252
	v_div_fixup_f32 v251, v251, v248, v246
	v_mul_f32_e32 v31, v31, v251
	v_cvt_pk_bf16_f32 v31, v31, v129
	global_store_short v[74:75], v31, off offset:1536
	v_cvt_f32_f16_e32 v246, v188
	v_cvt_f32_f16_e32 v247, v189
	v_mul_f32_e32 v248, 0xbfb8aa3b, v246
	v_exp_f32_e32 v248, v248
	v_add_f32_e32 v27, v27, v197
	v_add_f32_e32 v248, 1.0, v248
	v_div_scale_f32 v249, s[38:39], v248, v248, v246
	v_rcp_f32_e32 v250, v249
	v_mul_f32_e32 v27, v27, v247
	v_div_scale_f32 v251, vcc, v246, v248, v246
	v_fma_f32 v252, -v249, v250, 1.0
	v_fmac_f32_e32 v250, v252, v250
	v_mul_f32_e32 v252, v251, v250
	v_fma_f32 v253, -v249, v252, v251
	v_fmac_f32_e32 v252, v253, v250
	v_fma_f32 v251, -v249, v252, v251
	v_div_fmas_f32 v251, v251, v250, v252
	v_div_fixup_f32 v251, v251, v248, v246
	v_mul_f32_e32 v27, v27, v251
	v_cvt_pk_bf16_f32 v27, v27, v129
	global_store_short v[74:75], v27, off offset:1568
	v_cvt_f32_f16_e32 v246, v190
	v_cvt_f32_f16_e32 v247, v191
	v_mul_f32_e32 v248, 0xbfb8aa3b, v246
	v_exp_f32_e32 v248, v248
	v_add_f32_e32 v23, v23, v197
	v_add_f32_e32 v248, 1.0, v248
	v_div_scale_f32 v249, s[38:39], v248, v248, v246
	v_rcp_f32_e32 v250, v249
	v_mul_f32_e32 v23, v23, v247
	v_div_scale_f32 v251, vcc, v246, v248, v246
	v_fma_f32 v252, -v249, v250, 1.0
	v_fmac_f32_e32 v250, v252, v250
	v_mul_f32_e32 v252, v251, v250
	v_fma_f32 v253, -v249, v252, v251
	v_fmac_f32_e32 v252, v253, v250
	v_fma_f32 v251, -v249, v252, v251
	v_div_fmas_f32 v251, v251, v250, v252
	v_div_fixup_f32 v251, v251, v248, v246
	v_mul_f32_e32 v23, v23, v251
	v_cvt_pk_bf16_f32 v23, v23, v129
	global_store_short v[74:75], v23, off offset:1600
	v_cvt_f32_f16_e32 v246, v192
	v_cvt_f32_f16_e32 v247, v193
	v_mul_f32_e32 v248, 0xbfb8aa3b, v246
	v_exp_f32_e32 v248, v248
	v_add_f32_e32 v19, v19, v197
	v_add_f32_e32 v248, 1.0, v248
	v_div_scale_f32 v249, s[38:39], v248, v248, v246
	v_rcp_f32_e32 v250, v249
	v_mul_f32_e32 v19, v19, v247
	v_div_scale_f32 v251, vcc, v246, v248, v246
	v_fma_f32 v252, -v249, v250, 1.0
	v_fmac_f32_e32 v250, v252, v250
	v_mul_f32_e32 v252, v251, v250
	v_fma_f32 v253, -v249, v252, v251
	v_fmac_f32_e32 v252, v253, v250
	v_fma_f32 v251, -v249, v252, v251
	v_div_fmas_f32 v251, v251, v250, v252
	v_div_fixup_f32 v251, v251, v248, v246
	v_mul_f32_e32 v19, v19, v251
	v_cvt_pk_bf16_f32 v19, v19, v129
	global_store_short v[74:75], v19, off offset:1632
	s_waitcnt vmcnt(16)
	v_or_b32_e32 v128, s0, v70
	v_or_b32_e32 v128, 48, v128
	v_lshlrev_b64 v[74:75], 9, v[128:129]
	v_lshl_add_u64 v[74:75], s[28:29], 0, v[74:75]
	v_lshl_add_u64 v[74:75], v[74:75], 0, v[64:65]
	v_cvt_f32_f16_e32 v246, v198
	v_cvt_f32_f16_e32 v247, v199
	v_mul_f32_e32 v248, 0xbfb8aa3b, v246
	v_exp_f32_e32 v248, v248
	v_add_f32_e32 v12, v12, v234
	v_add_f32_e32 v248, 1.0, v248
	v_div_scale_f32 v249, s[38:39], v248, v248, v246
	v_rcp_f32_e32 v250, v249
	v_mul_f32_e32 v12, v12, v247
	v_div_scale_f32 v251, vcc, v246, v248, v246
	v_fma_f32 v252, -v249, v250, 1.0
	v_fmac_f32_e32 v250, v252, v250
	v_mul_f32_e32 v252, v251, v250
	v_fma_f32 v253, -v249, v252, v251
	v_fmac_f32_e32 v252, v253, v250
	v_fma_f32 v251, -v249, v252, v251
	v_div_fmas_f32 v251, v251, v250, v252
	v_div_fixup_f32 v251, v251, v248, v246
	v_mul_f32_e32 v12, v12, v251
	v_cvt_pk_bf16_f32 v12, v12, v129
	global_store_short v[74:75], v12, off
	v_cvt_f32_f16_e32 v246, v200
	v_cvt_f32_f16_e32 v247, v201
	v_mul_f32_e32 v248, 0xbfb8aa3b, v246
	v_exp_f32_e32 v248, v248
	v_add_f32_e32 v8, v8, v234
	v_add_f32_e32 v248, 1.0, v248
	v_div_scale_f32 v249, s[38:39], v248, v248, v246
	v_rcp_f32_e32 v250, v249
	v_mul_f32_e32 v8, v8, v247
	v_div_scale_f32 v251, vcc, v246, v248, v246
	v_fma_f32 v252, -v249, v250, 1.0
	v_fmac_f32_e32 v250, v252, v250
	v_mul_f32_e32 v252, v251, v250
	v_fma_f32 v253, -v249, v252, v251
	v_fmac_f32_e32 v252, v253, v250
	v_fma_f32 v251, -v249, v252, v251
	v_div_fmas_f32 v251, v251, v250, v252
	v_div_fixup_f32 v251, v251, v248, v246
	v_mul_f32_e32 v8, v8, v251
	v_cvt_pk_bf16_f32 v8, v8, v129
	global_store_short v[74:75], v8, off offset:32
	v_cvt_f32_f16_e32 v246, v202
	v_cvt_f32_f16_e32 v247, v203
	v_mul_f32_e32 v248, 0xbfb8aa3b, v246
	v_exp_f32_e32 v248, v248
	v_add_f32_e32 v4, v4, v234
	v_add_f32_e32 v248, 1.0, v248
	v_div_scale_f32 v249, s[38:39], v248, v248, v246
	v_rcp_f32_e32 v250, v249
	v_mul_f32_e32 v4, v4, v247
	v_div_scale_f32 v251, vcc, v246, v248, v246
	v_fma_f32 v252, -v249, v250, 1.0
	v_fmac_f32_e32 v250, v252, v250
	v_mul_f32_e32 v252, v251, v250
	v_fma_f32 v253, -v249, v252, v251
; DEVI u16 f2bf(float f) { return (u16)(cvtpk(f, 0.f) & 0xffffu); }
; DEVI float siluf_(float x) { return x / (1.f + __expf(-x)); }
; DEVI void prepSGU_tile(const Params& p, int l, int g, int tile, char* lds) {
;     ...
; #pragma unroll
;     for (int mb = 0; mb < 4; ++mb)
; #pragma unroll
;       for (int j = 0; j < 4; ++j) {
;         int pp = mh * 64 + mb * 16 + l4 * 4 + j; float bv = bs[pp];
;         const h16* zr = Z + (size_t)pp * NBC;
; #pragma unroll
;         for (int nb = 0; nb < 4; ++nb) {
;           int c = gi * 64 + nb * 16 + l15;
;           float u = (float)zr[736 + c], gc = (float)zr[1248 + c];
;           Yc[(size_t)(t0 + pp) * 256 + c] = f2bf(u * (acc[mb][nb][j] + bv) * siluf_(gc));
;         }
;       }
	v_fmac_f32_e32 v252, v253, v250
	v_fma_f32 v251, -v249, v252, v251
	v_div_fmas_f32 v251, v251, v250, v252
	v_div_fixup_f32 v251, v251, v248, v246
	v_mul_f32_e32 v4, v4, v251
	v_cvt_pk_bf16_f32 v4, v4, v129
	global_store_short v[74:75], v4, off offset:64
	v_cvt_f32_f16_e32 v246, v204
	v_cvt_f32_f16_e32 v247, v205
	v_mul_f32_e32 v248, 0xbfb8aa3b, v246
	v_exp_f32_e32 v248, v248
	v_add_f32_e32 v0, v0, v234
	v_add_f32_e32 v248, 1.0, v248
	v_div_scale_f32 v249, s[38:39], v248, v248, v246
	v_rcp_f32_e32 v250, v249
	v_mul_f32_e32 v0, v0, v247
	v_div_scale_f32 v251, vcc, v246, v248, v246
	v_fma_f32 v252, -v249, v250, 1.0
	v_fmac_f32_e32 v250, v252, v250
	v_mul_f32_e32 v252, v251, v250
	v_fma_f32 v253, -v249, v252, v251
	v_fmac_f32_e32 v252, v253, v250
	v_fma_f32 v251, -v249, v252, v251
	v_div_fmas_f32 v251, v251, v250, v252
	v_div_fixup_f32 v251, v251, v248, v246
	v_mul_f32_e32 v0, v0, v251
	v_cvt_pk_bf16_f32 v0, v0, v129
	global_store_short v[74:75], v0, off offset:96
	v_cvt_f32_f16_e32 v246, v206
	v_cvt_f32_f16_e32 v247, v207
	v_mul_f32_e32 v248, 0xbfb8aa3b, v246
	v_exp_f32_e32 v248, v248
	v_add_f32_e32 v13, v13, v235
	v_add_f32_e32 v248, 1.0, v248
	v_div_scale_f32 v249, s[38:39], v248, v248, v246
	v_rcp_f32_e32 v250, v249
	v_mul_f32_e32 v13, v13, v247
	v_div_scale_f32 v251, vcc, v246, v248, v246
	v_fma_f32 v252, -v249, v250, 1.0
	v_fmac_f32_e32 v250, v252, v250
	v_mul_f32_e32 v252, v251, v250
	v_fma_f32 v253, -v249, v252, v251
	v_fmac_f32_e32 v252, v253, v250
	v_fma_f32 v251, -v249, v252, v251
	v_div_fmas_f32 v251, v251, v250, v252
	v_div_fixup_f32 v251, v251, v248, v246
	v_mul_f32_e32 v13, v13, v251
	v_cvt_pk_bf16_f32 v13, v13, v129
	global_store_short v[74:75], v13, off offset:512
	v_cvt_f32_f16_e32 v246, v208
	v_cvt_f32_f16_e32 v247, v209
	v_mul_f32_e32 v248, 0xbfb8aa3b, v246
	v_exp_f32_e32 v248, v248
	v_add_f32_e32 v9, v9, v235
	v_add_f32_e32 v248, 1.0, v248
	v_div_scale_f32 v249, s[38:39], v248, v248, v246
	v_rcp_f32_e32 v250, v249
	v_mul_f32_e32 v9, v9, v247
	v_div_scale_f32 v251, vcc, v246, v248, v246
	v_fma_f32 v252, -v249, v250, 1.0
	v_fmac_f32_e32 v250, v252, v250
	v_mul_f32_e32 v252, v251, v250
	v_fma_f32 v253, -v249, v252, v251
	v_fmac_f32_e32 v252, v253, v250
	v_fma_f32 v251, -v249, v252, v251
	v_div_fmas_f32 v251, v251, v250, v252
	v_div_fixup_f32 v251, v251, v248, v246
	v_mul_f32_e32 v9, v9, v251
	v_cvt_pk_bf16_f32 v9, v9, v129
	global_store_short v[74:75], v9, off offset:544
	v_cvt_f32_f16_e32 v246, v210
	v_cvt_f32_f16_e32 v247, v211
	v_mul_f32_e32 v248, 0xbfb8aa3b, v246
	v_exp_f32_e32 v248, v248
	v_add_f32_e32 v5, v5, v235
	v_add_f32_e32 v248, 1.0, v248
	v_div_scale_f32 v249, s[38:39], v248, v248, v246
	v_rcp_f32_e32 v250, v249
	v_mul_f32_e32 v5, v5, v247
	v_div_scale_f32 v251, vcc, v246, v248, v246
	v_fma_f32 v252, -v249, v250, 1.0
	v_fmac_f32_e32 v250, v252, v250
	v_mul_f32_e32 v252, v251, v250
	v_fma_f32 v253, -v249, v252, v251
	v_fmac_f32_e32 v252, v253, v250
	v_fma_f32 v251, -v249, v252, v251
	v_div_fmas_f32 v251, v251, v250, v252
	v_div_fixup_f32 v251, v251, v248, v246
	v_mul_f32_e32 v5, v5, v251
	v_cvt_pk_bf16_f32 v5, v5, v129
	global_store_short v[74:75], v5, off offset:576
	v_cvt_f32_f16_e32 v246, v212
	v_cvt_f32_f16_e32 v247, v213
	v_mul_f32_e32 v248, 0xbfb8aa3b, v246
	v_exp_f32_e32 v248, v248
	v_add_f32_e32 v1, v1, v235
	v_add_f32_e32 v248, 1.0, v248
	v_div_scale_f32 v249, s[38:39], v248, v248, v246
	v_rcp_f32_e32 v250, v249
	v_mul_f32_e32 v1, v1, v247
	v_div_scale_f32 v251, vcc, v246, v248, v246
	v_fma_f32 v252, -v249, v250, 1.0
	v_fmac_f32_e32 v250, v252, v250
	v_mul_f32_e32 v252, v251, v250
	v_fma_f32 v253, -v249, v252, v251
	v_fmac_f32_e32 v252, v253, v250
	v_fma_f32 v251, -v249, v252, v251
	v_div_fmas_f32 v251, v251, v250, v252
	v_div_fixup_f32 v251, v251, v248, v246
	v_mul_f32_e32 v1, v1, v251
	v_cvt_pk_bf16_f32 v1, v1, v129
	global_store_short v[74:75], v1, off offset:608
	v_cvt_f32_f16_e32 v246, v214
	v_cvt_f32_f16_e32 v247, v215
	v_mul_f32_e32 v248, 0xbfb8aa3b, v246
	v_exp_f32_e32 v248, v248
	v_add_f32_e32 v14, v14, v236
	v_add_f32_e32 v248, 1.0, v248
	v_div_scale_f32 v249, s[38:39], v248, v248, v246
	v_rcp_f32_e32 v250, v249
	v_mul_f32_e32 v14, v14, v247
	v_div_scale_f32 v251, vcc, v246, v248, v246
	v_fma_f32 v252, -v249, v250, 1.0
	v_fmac_f32_e32 v250, v252, v250
	v_mul_f32_e32 v252, v251, v250
	v_fma_f32 v253, -v249, v252, v251
	v_fmac_f32_e32 v252, v253, v250
	v_fma_f32 v251, -v249, v252, v251
	v_div_fmas_f32 v251, v251, v250, v252
	v_div_fixup_f32 v251, v251, v248, v246
	v_mul_f32_e32 v14, v14, v251
	v_cvt_pk_bf16_f32 v14, v14, v129
	global_store_short v[74:75], v14, off offset:1024
	v_cvt_f32_f16_e32 v246, v216
	v_cvt_f32_f16_e32 v247, v217
	v_mul_f32_e32 v248, 0xbfb8aa3b, v246
	v_exp_f32_e32 v248, v248
	v_add_f32_e32 v10, v10, v236
	v_add_f32_e32 v248, 1.0, v248
	v_div_scale_f32 v249, s[38:39], v248, v248, v246
	v_rcp_f32_e32 v250, v249
; DEVI u16 f2bf(float f) { return (u16)(cvtpk(f, 0.f) & 0xffffu); }
; DEVI float siluf_(float x) { return x / (1.f + __expf(-x)); }
; DEVI void prepSGU_tile(const Params& p, int l, int g, int tile, char* lds) {
;     ...
; #pragma unroll
;     for (int mb = 0; mb < 4; ++mb)
; #pragma unroll
;       for (int j = 0; j < 4; ++j) {
;         int pp = mh * 64 + mb * 16 + l4 * 4 + j; float bv = bs[pp];
;         const h16* zr = Z + (size_t)pp * NBC;
; #pragma unroll
;         for (int nb = 0; nb < 4; ++nb) {
;           int c = gi * 64 + nb * 16 + l15;
;           float u = (float)zr[736 + c], gc = (float)zr[1248 + c];
;           Yc[(size_t)(t0 + pp) * 256 + c] = f2bf(u * (acc[mb][nb][j] + bv) * siluf_(gc));
;         }
;       }
;   }
;   __syncthreads();
	v_mul_f32_e32 v10, v10, v247
	v_div_scale_f32 v251, vcc, v246, v248, v246
	v_fma_f32 v252, -v249, v250, 1.0
	v_fmac_f32_e32 v250, v252, v250
	v_mul_f32_e32 v252, v251, v250
	v_fma_f32 v253, -v249, v252, v251
	v_fmac_f32_e32 v252, v253, v250
	v_fma_f32 v251, -v249, v252, v251
	v_div_fmas_f32 v251, v251, v250, v252
	v_div_fixup_f32 v251, v251, v248, v246
	v_mul_f32_e32 v10, v10, v251
	v_cvt_pk_bf16_f32 v10, v10, v129
	global_store_short v[74:75], v10, off offset:1056
	v_cvt_f32_f16_e32 v246, v222
	v_cvt_f32_f16_e32 v247, v223
	v_mul_f32_e32 v248, 0xbfb8aa3b, v246
	v_exp_f32_e32 v248, v248
	v_add_f32_e32 v6, v6, v236
	v_add_f32_e32 v248, 1.0, v248
	v_div_scale_f32 v249, s[38:39], v248, v248, v246
	v_rcp_f32_e32 v250, v249
	v_mul_f32_e32 v6, v6, v247
	v_div_scale_f32 v251, vcc, v246, v248, v246
	v_fma_f32 v252, -v249, v250, 1.0
	v_fmac_f32_e32 v250, v252, v250
	v_mul_f32_e32 v252, v251, v250
	v_fma_f32 v253, -v249, v252, v251
	v_fmac_f32_e32 v252, v253, v250
	v_fma_f32 v251, -v249, v252, v251
	v_div_fmas_f32 v251, v251, v250, v252
	v_div_fixup_f32 v251, v251, v248, v246
	v_mul_f32_e32 v6, v6, v251
	v_cvt_pk_bf16_f32 v6, v6, v129
	global_store_short v[74:75], v6, off offset:1088
	v_cvt_f32_f16_e32 v246, v224
	v_cvt_f32_f16_e32 v247, v225
	v_mul_f32_e32 v248, 0xbfb8aa3b, v246
	v_exp_f32_e32 v248, v248
	v_add_f32_e32 v2, v2, v236
	v_add_f32_e32 v248, 1.0, v248
	v_div_scale_f32 v249, s[38:39], v248, v248, v246
	v_rcp_f32_e32 v250, v249
	v_mul_f32_e32 v2, v2, v247
	v_div_scale_f32 v251, vcc, v246, v248, v246
	v_fma_f32 v252, -v249, v250, 1.0
	v_fmac_f32_e32 v250, v252, v250
	v_mul_f32_e32 v252, v251, v250
	v_fma_f32 v253, -v249, v252, v251
	v_fmac_f32_e32 v252, v253, v250
	v_fma_f32 v251, -v249, v252, v251
	v_div_fmas_f32 v251, v251, v250, v252
	v_div_fixup_f32 v251, v251, v248, v246
	v_mul_f32_e32 v2, v2, v251
	v_cvt_pk_bf16_f32 v2, v2, v129
	global_store_short v[74:75], v2, off offset:1120
	v_cvt_f32_f16_e32 v246, v226
	v_cvt_f32_f16_e32 v247, v227
	v_mul_f32_e32 v248, 0xbfb8aa3b, v246
	v_exp_f32_e32 v248, v248
	v_add_f32_e32 v15, v15, v237
	v_add_f32_e32 v248, 1.0, v248
	v_div_scale_f32 v249, s[38:39], v248, v248, v246
	v_rcp_f32_e32 v250, v249
	v_mul_f32_e32 v15, v15, v247
	v_div_scale_f32 v251, vcc, v246, v248, v246
	v_fma_f32 v252, -v249, v250, 1.0
	v_fmac_f32_e32 v250, v252, v250
	v_mul_f32_e32 v252, v251, v250
	v_fma_f32 v253, -v249, v252, v251
	v_fmac_f32_e32 v252, v253, v250
	v_fma_f32 v251, -v249, v252, v251
	v_div_fmas_f32 v251, v251, v250, v252
	v_div_fixup_f32 v251, v251, v248, v246
	v_mul_f32_e32 v15, v15, v251
	v_cvt_pk_bf16_f32 v15, v15, v129
	global_store_short v[74:75], v15, off offset:1536
	v_cvt_f32_f16_e32 v246, v228
	v_cvt_f32_f16_e32 v247, v229
	v_mul_f32_e32 v248, 0xbfb8aa3b, v246
	v_exp_f32_e32 v248, v248
	v_add_f32_e32 v11, v11, v237
	v_add_f32_e32 v248, 1.0, v248
	v_div_scale_f32 v249, s[38:39], v248, v248, v246
	v_rcp_f32_e32 v250, v249
	v_mul_f32_e32 v11, v11, v247
	v_div_scale_f32 v251, vcc, v246, v248, v246
	v_fma_f32 v252, -v249, v250, 1.0
	v_fmac_f32_e32 v250, v252, v250
	v_mul_f32_e32 v252, v251, v250
	v_fma_f32 v253, -v249, v252, v251
	v_fmac_f32_e32 v252, v253, v250
	v_fma_f32 v251, -v249, v252, v251
	v_div_fmas_f32 v251, v251, v250, v252
	v_div_fixup_f32 v251, v251, v248, v246
	v_mul_f32_e32 v11, v11, v251
	v_cvt_pk_bf16_f32 v11, v11, v129
	global_store_short v[74:75], v11, off offset:1568
	v_cvt_f32_f16_e32 v246, v230
	v_cvt_f32_f16_e32 v247, v231
	v_mul_f32_e32 v248, 0xbfb8aa3b, v246
	v_exp_f32_e32 v248, v248
	v_add_f32_e32 v7, v7, v237
	v_add_f32_e32 v248, 1.0, v248
	v_div_scale_f32 v249, s[38:39], v248, v248, v246
	v_rcp_f32_e32 v250, v249
	v_mul_f32_e32 v7, v7, v247
	v_div_scale_f32 v251, vcc, v246, v248, v246
	v_fma_f32 v252, -v249, v250, 1.0
	v_fmac_f32_e32 v250, v252, v250
	v_mul_f32_e32 v252, v251, v250
	v_fma_f32 v253, -v249, v252, v251
	v_fmac_f32_e32 v252, v253, v250
	v_fma_f32 v251, -v249, v252, v251
	v_div_fmas_f32 v251, v251, v250, v252
	v_div_fixup_f32 v251, v251, v248, v246
	v_mul_f32_e32 v7, v7, v251
	v_cvt_pk_bf16_f32 v7, v7, v129
	global_store_short v[74:75], v7, off offset:1600
	v_cvt_f32_f16_e32 v246, v232
	v_cvt_f32_f16_e32 v247, v233
	v_mul_f32_e32 v248, 0xbfb8aa3b, v246
	v_exp_f32_e32 v248, v248
	v_add_f32_e32 v3, v3, v237
	v_add_f32_e32 v248, 1.0, v248
	v_div_scale_f32 v249, s[38:39], v248, v248, v246
	v_rcp_f32_e32 v250, v249
	v_mul_f32_e32 v3, v3, v247
	v_div_scale_f32 v251, vcc, v246, v248, v246
	v_fma_f32 v252, -v249, v250, 1.0
	v_fmac_f32_e32 v250, v252, v250
	v_mul_f32_e32 v252, v251, v250
	v_fma_f32 v253, -v249, v252, v251
	v_fmac_f32_e32 v252, v253, v250
	v_fma_f32 v251, -v249, v252, v251
	v_div_fmas_f32 v251, v251, v250, v252
	v_div_fixup_f32 v251, v251, v248, v246
	v_mul_f32_e32 v3, v3, v251
	v_cvt_pk_bf16_f32 v3, v3, v129
	global_store_short v[74:75], v3, off offset:1632
	s_barrier
	s_branch .LBB0_778
